# v28 with every s_setprio removed from the GEMM K-loops (A/B of whether the remaining per-segment priority raise matters)
# speedup vs baseline: 1.0045x; 1.0009x over previous
.LBB0_91:
	ds_read_b128 v[150:153], v158
	ds_read_b128 v[162:165], v158 offset:1024
	ds_read_b128 v[166:169], v158 offset:2048
	ds_read_b128 v[170:173], v158 offset:3072
	ds_read_b128 v[174:177], v159
	ds_read_b128 v[178:181], v159 offset:1024
	ds_read_b128 v[182:185], v159 offset:2048
	ds_read_b128 v[186:189], v159 offset:3072
	s_add_u32 s36, s34, 0xfff00080
	s_addc_u32 s37, s35, -1
	s_cmp_eq_u32 s57, 60
	s_cselect_b32 s39, s2, s37
	s_cselect_b32 s38, s25, s36
	s_cselect_b32 s37, s23, s56
	s_cselect_b32 s36, s54, s55
	v_lshl_add_u64 v[146:147], s[34:35], 0, v[138:139]
	s_add_i32 m0, s43, 0xc000
	ds_read_b128 v[190:193], v160
	ds_read_b128 v[194:197], v160 offset:1024
	ds_read_b128 v[198:201], v160 offset:2048
	ds_read_b128 v[202:205], v160 offset:3072
	ds_read_b128 v[206:209], v160 offset:4096
	ds_read_b128 v[210:213], v160 offset:5120
	ds_read_b128 v[214:217], v160 offset:6144
	ds_read_b128 v[218:221], v160 offset:7168
	global_load_lds_dwordx4 v[146:147], off
	v_lshl_add_u64 v[146:147], s[34:35], 0, v[140:141]
	s_add_i32 m0, s43, 0xe000
	s_nop 0
	global_load_lds_dwordx4 v[146:147], off
	s_waitcnt vmcnt(8)
	s_waitcnt lgkmcnt(0)
	s_barrier
	v_mfma_f32_16x16x32_bf16 v[78:81], v[150:153], v[190:193], v[78:81]
	v_mfma_f32_16x16x32_bf16 v[70:73], v[166:169], v[190:193], v[70:73]
	v_mfma_f32_16x16x32_bf16 v[62:65], v[150:153], v[198:201], v[62:65]
	v_mfma_f32_16x16x32_bf16 v[58:61], v[166:169], v[198:201], v[58:61]
	v_mfma_f32_16x16x32_bf16 v[54:57], v[150:153], v[206:209], v[54:57]
	v_mfma_f32_16x16x32_bf16 v[50:53], v[166:169], v[206:209], v[50:53]
	v_mfma_f32_16x16x32_bf16 v[46:49], v[150:153], v[214:217], v[46:49]
	v_mfma_f32_16x16x32_bf16 v[42:45], v[166:169], v[214:217], v[42:45]
	v_mfma_f32_16x16x32_bf16 v[78:81], v[162:165], v[194:197], v[78:81]
	v_mfma_f32_16x16x32_bf16 v[70:73], v[170:173], v[194:197], v[70:73]
	v_mfma_f32_16x16x32_bf16 v[62:65], v[162:165], v[202:205], v[62:65]
	v_mfma_f32_16x16x32_bf16 v[58:61], v[170:173], v[202:205], v[58:61]
	v_mfma_f32_16x16x32_bf16 v[54:57], v[162:165], v[210:213], v[54:57]
	v_mfma_f32_16x16x32_bf16 v[50:53], v[170:173], v[210:213], v[50:53]
	v_mfma_f32_16x16x32_bf16 v[46:49], v[162:165], v[218:221], v[46:49]
	v_mfma_f32_16x16x32_bf16 v[42:45], v[170:173], v[218:221], v[42:45]
	v_mfma_f32_16x16x32_bf16 v[126:129], v[174:177], v[190:193], v[126:129]
	v_mfma_f32_16x16x32_bf16 v[122:125], v[182:185], v[190:193], v[122:125]
	v_mfma_f32_16x16x32_bf16 v[118:121], v[174:177], v[198:201], v[118:121]
	v_mfma_f32_16x16x32_bf16 v[114:117], v[182:185], v[198:201], v[114:117]
	v_mfma_f32_16x16x32_bf16 v[110:113], v[174:177], v[206:209], v[110:113]
	v_mfma_f32_16x16x32_bf16 v[106:109], v[182:185], v[206:209], v[106:109]
	v_mfma_f32_16x16x32_bf16 v[102:105], v[174:177], v[214:217], v[102:105]
	v_mfma_f32_16x16x32_bf16 v[98:101], v[182:185], v[214:217], v[98:101]
	v_mfma_f32_16x16x32_bf16 v[126:129], v[178:181], v[194:197], v[126:129]
	v_mfma_f32_16x16x32_bf16 v[122:125], v[186:189], v[194:197], v[122:125]
	v_mfma_f32_16x16x32_bf16 v[118:121], v[178:181], v[202:205], v[118:121]
	v_mfma_f32_16x16x32_bf16 v[114:117], v[186:189], v[202:205], v[114:117]
	v_mfma_f32_16x16x32_bf16 v[110:113], v[178:181], v[210:213], v[110:113]
	v_mfma_f32_16x16x32_bf16 v[106:109], v[186:189], v[210:213], v[106:109]
	v_mfma_f32_16x16x32_bf16 v[102:105], v[178:181], v[218:221], v[102:105]
	v_mfma_f32_16x16x32_bf16 v[98:101], v[186:189], v[218:221], v[98:101]
	s_barrier
	s_add_i32 s58, s51, s40
	v_lshl_add_u64 v[146:147], s[36:37], 0, v[134:135]
	s_mov_b32 m0, s58
	ds_read_b128 v[190:193], v160 offset:16384
	ds_read_b128 v[194:197], v160 offset:17408
	ds_read_b128 v[198:201], v160 offset:18432
	ds_read_b128 v[202:205], v160 offset:19456
	ds_read_b128 v[206:209], v160 offset:20480
	ds_read_b128 v[210:213], v160 offset:21504
	ds_read_b128 v[214:217], v160 offset:22528
	ds_read_b128 v[218:221], v160 offset:23552
	global_load_lds_dwordx4 v[146:147], off
	s_add_i32 m0, s58, 0x2000
	s_add_u32 s58, s36, 0x100000
	v_lshl_add_u64 v[222:223], s[36:37], 0, v[130:131]
	s_addc_u32 s59, s37, 0
	s_add_i32 s60, s52, s40
	global_load_lds_dwordx4 v[222:223], off
	v_lshl_add_u64 v[224:225], s[58:59], 0, v[134:135]
	s_mov_b32 m0, s60
	v_lshl_add_u64 v[226:227], s[38:39], 0, v[132:133]
	global_load_lds_dwordx4 v[224:225], off
	v_lshl_add_u64 v[224:225], s[58:59], 0, v[130:131]
	s_add_i32 m0, s60, 0x2000
	s_nop 0
	global_load_lds_dwordx4 v[224:225], off
	v_lshl_add_u64 v[224:225], s[38:39], 0, v[136:137]
	s_mov_b32 m0, s43
	s_nop 0
	global_load_lds_dwordx4 v[224:225], off
	s_mov_b32 m0, s44
	s_nop 0
	global_load_lds_dwordx4 v[226:227], off
	s_waitcnt vmcnt(8)
	s_waitcnt lgkmcnt(0)
	s_barrier
	v_mfma_f32_16x16x32_bf16 v[30:33], v[150:153], v[190:193], v[30:33]
	v_mfma_f32_16x16x32_bf16 v[26:29], v[166:169], v[190:193], v[26:29]
	v_mfma_f32_16x16x32_bf16 v[22:25], v[150:153], v[198:201], v[22:25]
	v_mfma_f32_16x16x32_bf16 v[18:21], v[166:169], v[198:201], v[18:21]
	v_mfma_f32_16x16x32_bf16 v[14:17], v[150:153], v[206:209], v[14:17]
	v_mfma_f32_16x16x32_bf16 v[10:13], v[166:169], v[206:209], v[10:13]
	v_mfma_f32_16x16x32_bf16 v[6:9], v[150:153], v[214:217], v[6:9]
	v_mfma_f32_16x16x32_bf16 v[2:5], v[166:169], v[214:217], v[2:5]
	v_mfma_f32_16x16x32_bf16 v[30:33], v[162:165], v[194:197], v[30:33]
	v_mfma_f32_16x16x32_bf16 v[26:29], v[170:173], v[194:197], v[26:29]
	v_mfma_f32_16x16x32_bf16 v[22:25], v[162:165], v[202:205], v[22:25]
	v_mfma_f32_16x16x32_bf16 v[18:21], v[170:173], v[202:205], v[18:21]
	v_mfma_f32_16x16x32_bf16 v[14:17], v[162:165], v[210:213], v[14:17]
	v_mfma_f32_16x16x32_bf16 v[10:13], v[170:173], v[210:213], v[10:13]
	v_mfma_f32_16x16x32_bf16 v[6:9], v[162:165], v[218:221], v[6:9]
	v_mfma_f32_16x16x32_bf16 v[2:5], v[170:173], v[218:221], v[2:5]
	v_mfma_f32_16x16x32_bf16 v[94:97], v[174:177], v[190:193], v[94:97]
	v_mfma_f32_16x16x32_bf16 v[90:93], v[182:185], v[190:193], v[90:93]
	v_mfma_f32_16x16x32_bf16 v[86:89], v[174:177], v[198:201], v[86:89]
	v_mfma_f32_16x16x32_bf16 v[82:85], v[182:185], v[198:201], v[82:85]
	v_mfma_f32_16x16x32_bf16 v[74:77], v[174:177], v[206:209], v[74:77]
	v_mfma_f32_16x16x32_bf16 v[66:69], v[182:185], v[206:209], v[66:69]
	v_mfma_f32_16x16x32_bf16 v[38:41], v[174:177], v[214:217], v[38:41]
	v_mfma_f32_16x16x32_bf16 v[34:37], v[182:185], v[214:217], v[34:37]
	v_mfma_f32_16x16x32_bf16 v[94:97], v[178:181], v[194:197], v[94:97]
	v_mfma_f32_16x16x32_bf16 v[90:93], v[186:189], v[194:197], v[90:93]
	v_mfma_f32_16x16x32_bf16 v[86:89], v[178:181], v[202:205], v[86:89]
	v_mfma_f32_16x16x32_bf16 v[82:85], v[186:189], v[202:205], v[82:85]
	v_mfma_f32_16x16x32_bf16 v[74:77], v[178:181], v[210:213], v[74:77]
	v_mfma_f32_16x16x32_bf16 v[66:69], v[186:189], v[210:213], v[66:69]
	v_mfma_f32_16x16x32_bf16 v[38:41], v[178:181], v[218:221], v[38:41]
	v_mfma_f32_16x16x32_bf16 v[34:37], v[186:189], v[218:221], v[34:37]
	s_barrier
	s_add_i32 s58, 0, 0x18000
	v_add_u32_e32 v148, s58, v156
	s_add_i32 s59, 0, 0x1c000
	ds_read_b128 v[150:153], v148
	ds_read_b128 v[162:165], v148 offset:1024
	ds_read_b128 v[166:169], v148 offset:2048
	ds_read_b128 v[170:173], v148 offset:3072
	v_add_u32_e32 v148, s59, v156
	ds_read_b128 v[174:177], v148
	ds_read_b128 v[178:181], v148 offset:1024
	ds_read_b128 v[182:185], v148 offset:2048
	ds_read_b128 v[186:189], v148 offset:3072
	s_add_u32 s38, s38, 0x100000
	s_addc_u32 s39, s39, 0
	s_mov_b32 m0, s45
	v_lshl_add_u64 v[228:229], s[38:39], 0, v[136:137]
	ds_read_b128 v[190:193], v160 offset:32768
	ds_read_b128 v[194:197], v160 offset:33792
	ds_read_b128 v[198:201], v160 offset:34816
	ds_read_b128 v[202:205], v160 offset:35840
	ds_read_b128 v[206:209], v160 offset:36864
	ds_read_b128 v[210:213], v160 offset:37888
	ds_read_b128 v[214:217], v160 offset:38912
	ds_read_b128 v[218:221], v160 offset:39936
	global_load_lds_dwordx4 v[228:229], off
	v_lshl_add_u64 v[228:229], s[38:39], 0, v[132:133]
	s_mov_b32 m0, s46
	s_nop 0
	global_load_lds_dwordx4 v[228:229], off
	s_waitcnt vmcnt(8)
	s_waitcnt lgkmcnt(0)
	s_barrier
	v_mfma_f32_16x16x32_bf16 v[78:81], v[150:153], v[190:193], v[78:81]
	v_mfma_f32_16x16x32_bf16 v[70:73], v[166:169], v[190:193], v[70:73]
	v_mfma_f32_16x16x32_bf16 v[62:65], v[150:153], v[198:201], v[62:65]
	v_mfma_f32_16x16x32_bf16 v[58:61], v[166:169], v[198:201], v[58:61]
	v_mfma_f32_16x16x32_bf16 v[54:57], v[150:153], v[206:209], v[54:57]
	v_mfma_f32_16x16x32_bf16 v[50:53], v[166:169], v[206:209], v[50:53]
	v_mfma_f32_16x16x32_bf16 v[46:49], v[150:153], v[214:217], v[46:49]
	v_mfma_f32_16x16x32_bf16 v[42:45], v[166:169], v[214:217], v[42:45]
	v_mfma_f32_16x16x32_bf16 v[78:81], v[162:165], v[194:197], v[78:81]
	v_mfma_f32_16x16x32_bf16 v[70:73], v[170:173], v[194:197], v[70:73]
	v_mfma_f32_16x16x32_bf16 v[62:65], v[162:165], v[202:205], v[62:65]
	v_mfma_f32_16x16x32_bf16 v[58:61], v[170:173], v[202:205], v[58:61]
	v_mfma_f32_16x16x32_bf16 v[54:57], v[162:165], v[210:213], v[54:57]
	v_mfma_f32_16x16x32_bf16 v[50:53], v[170:173], v[210:213], v[50:53]
	v_mfma_f32_16x16x32_bf16 v[46:49], v[162:165], v[218:221], v[46:49]
	v_mfma_f32_16x16x32_bf16 v[42:45], v[170:173], v[218:221], v[42:45]
	v_mfma_f32_16x16x32_bf16 v[126:129], v[174:177], v[190:193], v[126:129]
	v_mfma_f32_16x16x32_bf16 v[122:125], v[182:185], v[190:193], v[122:125]
	v_mfma_f32_16x16x32_bf16 v[118:121], v[174:177], v[198:201], v[118:121]
	v_mfma_f32_16x16x32_bf16 v[114:117], v[182:185], v[198:201], v[114:117]
	v_mfma_f32_16x16x32_bf16 v[110:113], v[174:177], v[206:209], v[110:113]
	v_mfma_f32_16x16x32_bf16 v[106:109], v[182:185], v[206:209], v[106:109]
	v_mfma_f32_16x16x32_bf16 v[102:105], v[174:177], v[214:217], v[102:105]
	v_mfma_f32_16x16x32_bf16 v[98:101], v[182:185], v[214:217], v[98:101]
	v_mfma_f32_16x16x32_bf16 v[126:129], v[178:181], v[194:197], v[126:129]
	v_mfma_f32_16x16x32_bf16 v[122:125], v[186:189], v[194:197], v[122:125]
	v_mfma_f32_16x16x32_bf16 v[118:121], v[178:181], v[202:205], v[118:121]
	v_mfma_f32_16x16x32_bf16 v[114:117], v[186:189], v[202:205], v[114:117]
	v_mfma_f32_16x16x32_bf16 v[110:113], v[178:181], v[210:213], v[110:113]
	v_mfma_f32_16x16x32_bf16 v[106:109], v[186:189], v[210:213], v[106:109]
	v_mfma_f32_16x16x32_bf16 v[102:105], v[178:181], v[218:221], v[102:105]
	v_mfma_f32_16x16x32_bf16 v[98:101], v[186:189], v[218:221], v[98:101]
	s_barrier
	s_add_i32 s38, s58, s40
	v_lshl_add_u64 v[146:147], v[146:147], 0, s[18:19]
	s_mov_b32 m0, s38
	ds_read_b128 v[190:193], v160 offset:49152
	ds_read_b128 v[194:197], v160 offset:50176
	ds_read_b128 v[198:201], v160 offset:51200
	ds_read_b128 v[202:205], v160 offset:52224
	ds_read_b128 v[206:209], v160 offset:53248
	ds_read_b128 v[210:213], v160 offset:54272
	ds_read_b128 v[214:217], v160 offset:55296
	ds_read_b128 v[218:221], v160 offset:56320
	global_load_lds_dwordx4 v[146:147], off
	s_add_i32 m0, s38, 0x2000
	s_add_u32 s36, s36, 0x100080
	v_lshl_add_u64 v[146:147], v[222:223], 0, s[18:19]
	s_addc_u32 s37, s37, 0
	s_add_i32 s38, s59, s40
	global_load_lds_dwordx4 v[146:147], off
	v_lshl_add_u64 v[146:147], s[36:37], 0, v[134:135]
	s_mov_b32 m0, s38
	s_nop 0
	global_load_lds_dwordx4 v[146:147], off
	v_lshl_add_u64 v[146:147], s[36:37], 0, v[130:131]
	s_add_i32 m0, s38, 0x2000
	s_nop 0
	global_load_lds_dwordx4 v[146:147], off
	v_lshl_add_u64 v[146:147], v[224:225], 0, s[18:19]
	s_mov_b32 m0, s48
	s_nop 0
	global_load_lds_dwordx4 v[146:147], off
	v_lshl_add_u64 v[146:147], v[226:227], 0, s[18:19]
	s_mov_b32 m0, s49
	s_nop 0
	global_load_lds_dwordx4 v[146:147], off
	s_waitcnt vmcnt(8)
	s_waitcnt lgkmcnt(0)
	s_barrier
	v_mfma_f32_16x16x32_bf16 v[30:33], v[150:153], v[190:193], v[30:33]
	v_mfma_f32_16x16x32_bf16 v[26:29], v[166:169], v[190:193], v[26:29]
	v_mfma_f32_16x16x32_bf16 v[22:25], v[150:153], v[198:201], v[22:25]
	v_mfma_f32_16x16x32_bf16 v[18:21], v[166:169], v[198:201], v[18:21]
	v_mfma_f32_16x16x32_bf16 v[14:17], v[150:153], v[206:209], v[14:17]
	v_mfma_f32_16x16x32_bf16 v[10:13], v[166:169], v[206:209], v[10:13]
	v_mfma_f32_16x16x32_bf16 v[6:9], v[150:153], v[214:217], v[6:9]
	v_mfma_f32_16x16x32_bf16 v[2:5], v[166:169], v[214:217], v[2:5]
	v_mfma_f32_16x16x32_bf16 v[30:33], v[162:165], v[194:197], v[30:33]
	v_mfma_f32_16x16x32_bf16 v[26:29], v[170:173], v[194:197], v[26:29]
	v_mfma_f32_16x16x32_bf16 v[22:25], v[162:165], v[202:205], v[22:25]
	v_mfma_f32_16x16x32_bf16 v[18:21], v[170:173], v[202:205], v[18:21]
	v_mfma_f32_16x16x32_bf16 v[14:17], v[162:165], v[210:213], v[14:17]
	v_mfma_f32_16x16x32_bf16 v[10:13], v[170:173], v[210:213], v[10:13]
	v_mfma_f32_16x16x32_bf16 v[6:9], v[162:165], v[218:221], v[6:9]
	v_mfma_f32_16x16x32_bf16 v[2:5], v[170:173], v[218:221], v[2:5]
	v_mfma_f32_16x16x32_bf16 v[94:97], v[174:177], v[190:193], v[94:97]
	v_mfma_f32_16x16x32_bf16 v[90:93], v[182:185], v[190:193], v[90:93]
	v_mfma_f32_16x16x32_bf16 v[86:89], v[174:177], v[198:201], v[86:89]
	v_mfma_f32_16x16x32_bf16 v[82:85], v[182:185], v[198:201], v[82:85]
	v_mfma_f32_16x16x32_bf16 v[74:77], v[174:177], v[206:209], v[74:77]
	v_mfma_f32_16x16x32_bf16 v[66:69], v[182:185], v[206:209], v[66:69]
	v_mfma_f32_16x16x32_bf16 v[38:41], v[174:177], v[214:217], v[38:41]
	v_mfma_f32_16x16x32_bf16 v[34:37], v[182:185], v[214:217], v[34:37]
	v_mfma_f32_16x16x32_bf16 v[94:97], v[178:181], v[194:197], v[94:97]
	v_mfma_f32_16x16x32_bf16 v[90:93], v[186:189], v[194:197], v[90:93]
	v_mfma_f32_16x16x32_bf16 v[86:89], v[178:181], v[202:205], v[86:89]
	v_mfma_f32_16x16x32_bf16 v[82:85], v[186:189], v[202:205], v[82:85]
	v_mfma_f32_16x16x32_bf16 v[74:77], v[178:181], v[210:213], v[74:77]
	v_mfma_f32_16x16x32_bf16 v[66:69], v[186:189], v[210:213], v[66:69]
	v_mfma_f32_16x16x32_bf16 v[38:41], v[178:181], v[218:221], v[38:41]
	v_mfma_f32_16x16x32_bf16 v[34:37], v[186:189], v[218:221], v[34:37]
	s_barrier
	s_add_i32 s57, s57, 2
	s_add_u32 s34, s34, 0x100
	s_addc_u32 s35, s35, 0
	s_add_u32 s55, s55, 0x100
	s_addc_u32 s56, s56, 0
	s_cmp_gt_u32 s57, 61
	s_cbranch_scc0 .LBB0_91
	s_and_b64 vcc, exec, s[20:21]
	s_cbranch_vccz .LBB0_94
	s_barrier

.LBB0_317:
	ds_read_b128 v[148:151], v166
	ds_read_b128 v[170:173], v166 offset:1024
	ds_read_b128 v[174:177], v166 offset:2048
	ds_read_b128 v[178:181], v166 offset:3072
	ds_read_b128 v[182:185], v167
	ds_read_b128 v[186:189], v167 offset:1024
	ds_read_b128 v[190:193], v167 offset:2048
	ds_read_b128 v[194:197], v167 offset:3072
	s_add_u32 s28, s26, 0xfffc0080
	s_addc_u32 s29, s27, -1
	s_cmp_eq_u32 s53, 12
	s_cselect_b32 s31, s19, s29
	s_cselect_b32 s30, s49, s28
	s_cselect_b32 s29, s17, s52
	s_cselect_b32 s28, s50, s51
	v_lshl_add_u64 v[230:231], s[26:27], 0, v[138:139]
	s_add_i32 m0, s25, 0xc000
	ds_read_b128 v[198:201], v168
	ds_read_b128 v[202:205], v168 offset:1024
	ds_read_b128 v[206:209], v168 offset:2048
	ds_read_b128 v[210:213], v168 offset:3072
	ds_read_b128 v[214:217], v168 offset:4096
	ds_read_b128 v[218:221], v168 offset:5120
	ds_read_b128 v[222:225], v168 offset:6144
	ds_read_b128 v[226:229], v168 offset:7168
	global_load_lds_dwordx4 v[230:231], off
	v_lshl_add_u64 v[230:231], s[26:27], 0, v[140:141]
	s_add_i32 m0, s25, 0xe000
	s_nop 0
	global_load_lds_dwordx4 v[230:231], off
	s_waitcnt vmcnt(8)
	s_waitcnt lgkmcnt(0)
	s_barrier
	v_mfma_f32_16x16x32_bf16 v[126:129], v[148:151], v[198:201], v[126:129]
	v_mfma_f32_16x16x32_bf16 v[122:125], v[174:177], v[198:201], v[122:125]
	v_mfma_f32_16x16x32_bf16 v[114:117], v[148:151], v[206:209], v[114:117]
	v_mfma_f32_16x16x32_bf16 v[106:109], v[174:177], v[206:209], v[106:109]
	v_mfma_f32_16x16x32_bf16 v[98:101], v[148:151], v[214:217], v[98:101]
	v_mfma_f32_16x16x32_bf16 v[90:93], v[174:177], v[214:217], v[90:93]
	v_mfma_f32_16x16x32_bf16 v[82:85], v[148:151], v[222:225], v[82:85]
	v_mfma_f32_16x16x32_bf16 v[74:77], v[174:177], v[222:225], v[74:77]
	v_mfma_f32_16x16x32_bf16 v[126:129], v[170:173], v[202:205], v[126:129]
	v_mfma_f32_16x16x32_bf16 v[122:125], v[178:181], v[202:205], v[122:125]
	v_mfma_f32_16x16x32_bf16 v[114:117], v[170:173], v[210:213], v[114:117]
	v_mfma_f32_16x16x32_bf16 v[106:109], v[178:181], v[210:213], v[106:109]
	v_mfma_f32_16x16x32_bf16 v[98:101], v[170:173], v[218:221], v[98:101]
	v_mfma_f32_16x16x32_bf16 v[90:93], v[178:181], v[218:221], v[90:93]
	v_mfma_f32_16x16x32_bf16 v[82:85], v[170:173], v[226:229], v[82:85]
	v_mfma_f32_16x16x32_bf16 v[74:77], v[178:181], v[226:229], v[74:77]
	v_mfma_f32_16x16x32_bf16 v[118:121], v[182:185], v[198:201], v[118:121]
	v_mfma_f32_16x16x32_bf16 v[110:113], v[190:193], v[198:201], v[110:113]
	v_mfma_f32_16x16x32_bf16 v[102:105], v[182:185], v[206:209], v[102:105]
	v_mfma_f32_16x16x32_bf16 v[94:97], v[190:193], v[206:209], v[94:97]
	v_mfma_f32_16x16x32_bf16 v[86:89], v[182:185], v[214:217], v[86:89]
	v_mfma_f32_16x16x32_bf16 v[78:81], v[190:193], v[214:217], v[78:81]
	v_mfma_f32_16x16x32_bf16 v[70:73], v[182:185], v[222:225], v[70:73]
	v_mfma_f32_16x16x32_bf16 v[66:69], v[190:193], v[222:225], v[66:69]
	v_mfma_f32_16x16x32_bf16 v[118:121], v[186:189], v[202:205], v[118:121]
	v_mfma_f32_16x16x32_bf16 v[110:113], v[194:197], v[202:205], v[110:113]
	v_mfma_f32_16x16x32_bf16 v[102:105], v[186:189], v[210:213], v[102:105]
	v_mfma_f32_16x16x32_bf16 v[94:97], v[194:197], v[210:213], v[94:97]
	v_mfma_f32_16x16x32_bf16 v[86:89], v[186:189], v[218:221], v[86:89]
	v_mfma_f32_16x16x32_bf16 v[78:81], v[194:197], v[218:221], v[78:81]
	v_mfma_f32_16x16x32_bf16 v[70:73], v[186:189], v[226:229], v[70:73]
	v_mfma_f32_16x16x32_bf16 v[66:69], v[194:197], v[226:229], v[66:69]
	s_barrier
	s_add_i32 s54, s46, s36
	v_lshl_add_u64 v[230:231], s[28:29], 0, v[134:135]
	s_mov_b32 m0, s54
	ds_read_b128 v[198:201], v168 offset:16384
	ds_read_b128 v[202:205], v168 offset:17408
	ds_read_b128 v[206:209], v168 offset:18432
	ds_read_b128 v[210:213], v168 offset:19456
	ds_read_b128 v[214:217], v168 offset:20480
	ds_read_b128 v[218:221], v168 offset:21504
	ds_read_b128 v[222:225], v168 offset:22528
	ds_read_b128 v[226:229], v168 offset:23552
	global_load_lds_dwordx4 v[230:231], off
	s_add_i32 m0, s54, 0x2000
	s_add_u32 s54, s28, 0x40000
	v_lshl_add_u64 v[232:233], s[28:29], 0, v[130:131]
	s_addc_u32 s55, s29, 0
	s_add_i32 s56, s47, s36
	global_load_lds_dwordx4 v[232:233], off
	v_lshl_add_u64 v[234:235], s[54:55], 0, v[134:135]
	s_mov_b32 m0, s56
	v_lshl_add_u64 v[236:237], s[30:31], 0, v[132:133]
	global_load_lds_dwordx4 v[234:235], off
	v_lshl_add_u64 v[234:235], s[54:55], 0, v[130:131]
	s_add_i32 m0, s56, 0x2000
	s_nop 0
	global_load_lds_dwordx4 v[234:235], off
	v_lshl_add_u64 v[234:235], s[30:31], 0, v[136:137]
	s_mov_b32 m0, s25
	s_nop 0
	global_load_lds_dwordx4 v[234:235], off
	s_mov_b32 m0, s38
	s_nop 0
	global_load_lds_dwordx4 v[236:237], off
	s_waitcnt vmcnt(8)
	s_waitcnt lgkmcnt(0)
	s_barrier
	v_mfma_f32_16x16x32_bf16 v[62:65], v[148:151], v[198:201], v[62:65]
	v_mfma_f32_16x16x32_bf16 v[58:61], v[174:177], v[198:201], v[58:61]
	v_mfma_f32_16x16x32_bf16 v[50:53], v[148:151], v[206:209], v[50:53]
	v_mfma_f32_16x16x32_bf16 v[42:45], v[174:177], v[206:209], v[42:45]
	v_mfma_f32_16x16x32_bf16 v[34:37], v[148:151], v[214:217], v[34:37]
	v_mfma_f32_16x16x32_bf16 v[26:29], v[174:177], v[214:217], v[26:29]
	v_mfma_f32_16x16x32_bf16 v[18:21], v[148:151], v[222:225], v[18:21]
	v_mfma_f32_16x16x32_bf16 v[10:13], v[174:177], v[222:225], v[10:13]
	v_mfma_f32_16x16x32_bf16 v[62:65], v[170:173], v[202:205], v[62:65]
	v_mfma_f32_16x16x32_bf16 v[58:61], v[178:181], v[202:205], v[58:61]
	v_mfma_f32_16x16x32_bf16 v[50:53], v[170:173], v[210:213], v[50:53]
	v_mfma_f32_16x16x32_bf16 v[42:45], v[178:181], v[210:213], v[42:45]
	v_mfma_f32_16x16x32_bf16 v[34:37], v[170:173], v[218:221], v[34:37]
	v_mfma_f32_16x16x32_bf16 v[26:29], v[178:181], v[218:221], v[26:29]
	v_mfma_f32_16x16x32_bf16 v[18:21], v[170:173], v[226:229], v[18:21]
	v_mfma_f32_16x16x32_bf16 v[10:13], v[178:181], v[226:229], v[10:13]
	v_mfma_f32_16x16x32_bf16 v[54:57], v[182:185], v[198:201], v[54:57]
	v_mfma_f32_16x16x32_bf16 v[46:49], v[190:193], v[198:201], v[46:49]
	v_mfma_f32_16x16x32_bf16 v[38:41], v[182:185], v[206:209], v[38:41]
	v_mfma_f32_16x16x32_bf16 v[30:33], v[190:193], v[206:209], v[30:33]
	v_mfma_f32_16x16x32_bf16 v[22:25], v[182:185], v[214:217], v[22:25]
	v_mfma_f32_16x16x32_bf16 v[14:17], v[190:193], v[214:217], v[14:17]
	v_mfma_f32_16x16x32_bf16 v[6:9], v[182:185], v[222:225], v[6:9]
	v_mfma_f32_16x16x32_bf16 v[2:5], v[190:193], v[222:225], v[2:5]
	v_mfma_f32_16x16x32_bf16 v[54:57], v[186:189], v[202:205], v[54:57]
	v_mfma_f32_16x16x32_bf16 v[46:49], v[194:197], v[202:205], v[46:49]
	v_mfma_f32_16x16x32_bf16 v[38:41], v[186:189], v[210:213], v[38:41]
	v_mfma_f32_16x16x32_bf16 v[30:33], v[194:197], v[210:213], v[30:33]
	v_mfma_f32_16x16x32_bf16 v[22:25], v[186:189], v[218:221], v[22:25]
	v_mfma_f32_16x16x32_bf16 v[14:17], v[194:197], v[218:221], v[14:17]
	v_mfma_f32_16x16x32_bf16 v[6:9], v[186:189], v[226:229], v[6:9]
	v_mfma_f32_16x16x32_bf16 v[2:5], v[194:197], v[226:229], v[2:5]
	s_barrier
	s_add_i32 s54, 0, 0x18000
	v_add_u32_e32 v146, s54, v164
	s_add_i32 s55, 0, 0x1c000
	ds_read_b128 v[148:151], v146
	ds_read_b128 v[170:173], v146 offset:1024
	ds_read_b128 v[174:177], v146 offset:2048
	ds_read_b128 v[178:181], v146 offset:3072
	v_add_u32_e32 v146, s55, v164
	ds_read_b128 v[182:185], v146
	ds_read_b128 v[186:189], v146 offset:1024
	ds_read_b128 v[190:193], v146 offset:2048
	ds_read_b128 v[194:197], v146 offset:3072
	s_add_u32 s30, s30, 0x40000
	s_addc_u32 s31, s31, 0
	s_mov_b32 m0, s39
	v_lshl_add_u64 v[238:239], s[30:31], 0, v[136:137]
	ds_read_b128 v[198:201], v168 offset:32768
	ds_read_b128 v[202:205], v168 offset:33792
	ds_read_b128 v[206:209], v168 offset:34816
	ds_read_b128 v[210:213], v168 offset:35840
	ds_read_b128 v[214:217], v168 offset:36864
	ds_read_b128 v[218:221], v168 offset:37888
	ds_read_b128 v[222:225], v168 offset:38912
	ds_read_b128 v[226:229], v168 offset:39936
	global_load_lds_dwordx4 v[238:239], off
	v_lshl_add_u64 v[238:239], s[30:31], 0, v[132:133]
	s_mov_b32 m0, s40
	s_nop 0
	global_load_lds_dwordx4 v[238:239], off
	s_waitcnt vmcnt(8)
	s_waitcnt lgkmcnt(0)
	s_barrier
	v_mfma_f32_16x16x32_bf16 v[126:129], v[148:151], v[198:201], v[126:129]
	v_mfma_f32_16x16x32_bf16 v[122:125], v[174:177], v[198:201], v[122:125]
	v_mfma_f32_16x16x32_bf16 v[114:117], v[148:151], v[206:209], v[114:117]
	v_mfma_f32_16x16x32_bf16 v[106:109], v[174:177], v[206:209], v[106:109]
	v_mfma_f32_16x16x32_bf16 v[98:101], v[148:151], v[214:217], v[98:101]
	v_mfma_f32_16x16x32_bf16 v[90:93], v[174:177], v[214:217], v[90:93]
	v_mfma_f32_16x16x32_bf16 v[82:85], v[148:151], v[222:225], v[82:85]
	v_mfma_f32_16x16x32_bf16 v[74:77], v[174:177], v[222:225], v[74:77]
	v_mfma_f32_16x16x32_bf16 v[126:129], v[170:173], v[202:205], v[126:129]
	v_mfma_f32_16x16x32_bf16 v[122:125], v[178:181], v[202:205], v[122:125]
	v_mfma_f32_16x16x32_bf16 v[114:117], v[170:173], v[210:213], v[114:117]
	v_mfma_f32_16x16x32_bf16 v[106:109], v[178:181], v[210:213], v[106:109]
	v_mfma_f32_16x16x32_bf16 v[98:101], v[170:173], v[218:221], v[98:101]
	v_mfma_f32_16x16x32_bf16 v[90:93], v[178:181], v[218:221], v[90:93]
	v_mfma_f32_16x16x32_bf16 v[82:85], v[170:173], v[226:229], v[82:85]
	v_mfma_f32_16x16x32_bf16 v[74:77], v[178:181], v[226:229], v[74:77]
	v_mfma_f32_16x16x32_bf16 v[118:121], v[182:185], v[198:201], v[118:121]
	v_mfma_f32_16x16x32_bf16 v[110:113], v[190:193], v[198:201], v[110:113]
	v_mfma_f32_16x16x32_bf16 v[102:105], v[182:185], v[206:209], v[102:105]
	v_mfma_f32_16x16x32_bf16 v[94:97], v[190:193], v[206:209], v[94:97]
	v_mfma_f32_16x16x32_bf16 v[86:89], v[182:185], v[214:217], v[86:89]
	v_mfma_f32_16x16x32_bf16 v[78:81], v[190:193], v[214:217], v[78:81]
	v_mfma_f32_16x16x32_bf16 v[70:73], v[182:185], v[222:225], v[70:73]
	v_mfma_f32_16x16x32_bf16 v[66:69], v[190:193], v[222:225], v[66:69]
	v_mfma_f32_16x16x32_bf16 v[118:121], v[186:189], v[202:205], v[118:121]
	v_mfma_f32_16x16x32_bf16 v[110:113], v[194:197], v[202:205], v[110:113]
	v_mfma_f32_16x16x32_bf16 v[102:105], v[186:189], v[210:213], v[102:105]
	v_mfma_f32_16x16x32_bf16 v[94:97], v[194:197], v[210:213], v[94:97]
	v_mfma_f32_16x16x32_bf16 v[86:89], v[186:189], v[218:221], v[86:89]
	v_mfma_f32_16x16x32_bf16 v[78:81], v[194:197], v[218:221], v[78:81]
	v_mfma_f32_16x16x32_bf16 v[70:73], v[186:189], v[226:229], v[70:73]
	v_mfma_f32_16x16x32_bf16 v[66:69], v[194:197], v[226:229], v[66:69]
	s_barrier
	s_add_i32 s30, s54, s36
	v_lshl_add_u64 v[230:231], v[230:231], 0, s[12:13]
	s_mov_b32 m0, s30
	ds_read_b128 v[198:201], v168 offset:49152
	ds_read_b128 v[202:205], v168 offset:50176
	ds_read_b128 v[206:209], v168 offset:51200
	ds_read_b128 v[210:213], v168 offset:52224
	ds_read_b128 v[214:217], v168 offset:53248
	ds_read_b128 v[218:221], v168 offset:54272
	ds_read_b128 v[222:225], v168 offset:55296
	ds_read_b128 v[226:229], v168 offset:56320
	global_load_lds_dwordx4 v[230:231], off
	s_add_i32 m0, s30, 0x2000
	s_add_u32 s28, s28, 0x40080
	v_lshl_add_u64 v[230:231], v[232:233], 0, s[12:13]
	s_addc_u32 s29, s29, 0
	s_add_i32 s30, s55, s36
	global_load_lds_dwordx4 v[230:231], off
	v_lshl_add_u64 v[230:231], s[28:29], 0, v[134:135]
	s_mov_b32 m0, s30
	s_nop 0
	global_load_lds_dwordx4 v[230:231], off
	v_lshl_add_u64 v[230:231], s[28:29], 0, v[130:131]
	s_add_i32 m0, s30, 0x2000
	s_nop 0
	global_load_lds_dwordx4 v[230:231], off
	v_lshl_add_u64 v[230:231], v[234:235], 0, s[12:13]
	s_mov_b32 m0, s42
	s_nop 0
	global_load_lds_dwordx4 v[230:231], off
	v_lshl_add_u64 v[230:231], v[236:237], 0, s[12:13]
	s_mov_b32 m0, s43
	s_nop 0
	global_load_lds_dwordx4 v[230:231], off
	s_waitcnt vmcnt(8)
	s_waitcnt lgkmcnt(0)
	s_barrier
	v_mfma_f32_16x16x32_bf16 v[62:65], v[148:151], v[198:201], v[62:65]
	v_mfma_f32_16x16x32_bf16 v[58:61], v[174:177], v[198:201], v[58:61]
	v_mfma_f32_16x16x32_bf16 v[50:53], v[148:151], v[206:209], v[50:53]
	v_mfma_f32_16x16x32_bf16 v[42:45], v[174:177], v[206:209], v[42:45]
	v_mfma_f32_16x16x32_bf16 v[34:37], v[148:151], v[214:217], v[34:37]
	v_mfma_f32_16x16x32_bf16 v[26:29], v[174:177], v[214:217], v[26:29]
	v_mfma_f32_16x16x32_bf16 v[18:21], v[148:151], v[222:225], v[18:21]
	v_mfma_f32_16x16x32_bf16 v[10:13], v[174:177], v[222:225], v[10:13]
	v_mfma_f32_16x16x32_bf16 v[62:65], v[170:173], v[202:205], v[62:65]
	v_mfma_f32_16x16x32_bf16 v[58:61], v[178:181], v[202:205], v[58:61]
	v_mfma_f32_16x16x32_bf16 v[50:53], v[170:173], v[210:213], v[50:53]
	v_mfma_f32_16x16x32_bf16 v[42:45], v[178:181], v[210:213], v[42:45]
	v_mfma_f32_16x16x32_bf16 v[34:37], v[170:173], v[218:221], v[34:37]
	v_mfma_f32_16x16x32_bf16 v[26:29], v[178:181], v[218:221], v[26:29]
	v_mfma_f32_16x16x32_bf16 v[18:21], v[170:173], v[226:229], v[18:21]
	v_mfma_f32_16x16x32_bf16 v[10:13], v[178:181], v[226:229], v[10:13]
	v_mfma_f32_16x16x32_bf16 v[54:57], v[182:185], v[198:201], v[54:57]
	v_mfma_f32_16x16x32_bf16 v[46:49], v[190:193], v[198:201], v[46:49]
	v_mfma_f32_16x16x32_bf16 v[38:41], v[182:185], v[206:209], v[38:41]
	v_mfma_f32_16x16x32_bf16 v[30:33], v[190:193], v[206:209], v[30:33]
	v_mfma_f32_16x16x32_bf16 v[22:25], v[182:185], v[214:217], v[22:25]
	v_mfma_f32_16x16x32_bf16 v[14:17], v[190:193], v[214:217], v[14:17]
	v_mfma_f32_16x16x32_bf16 v[6:9], v[182:185], v[222:225], v[6:9]
	v_mfma_f32_16x16x32_bf16 v[2:5], v[190:193], v[222:225], v[2:5]
	v_mfma_f32_16x16x32_bf16 v[54:57], v[186:189], v[202:205], v[54:57]
	v_mfma_f32_16x16x32_bf16 v[46:49], v[194:197], v[202:205], v[46:49]
	v_mfma_f32_16x16x32_bf16 v[38:41], v[186:189], v[210:213], v[38:41]
	v_mfma_f32_16x16x32_bf16 v[30:33], v[194:197], v[210:213], v[30:33]
	v_mfma_f32_16x16x32_bf16 v[22:25], v[186:189], v[218:221], v[22:25]
	v_mfma_f32_16x16x32_bf16 v[14:17], v[194:197], v[218:221], v[14:17]
	v_mfma_f32_16x16x32_bf16 v[6:9], v[186:189], v[226:229], v[6:9]
	v_mfma_f32_16x16x32_bf16 v[2:5], v[194:197], v[226:229], v[2:5]
	s_barrier
	s_add_i32 s53, s53, 2
	s_add_u32 s26, s26, 0x100
	s_addc_u32 s27, s27, 0
	s_add_u32 s51, s51, 0x100
	s_addc_u32 s52, s52, 0
	s_cmp_gt_u32 s53, 13
	s_cbranch_scc0 .LBB0_317
	s_and_b64 vcc, exec, s[14:15]
	s_cbranch_vccz .LBB0_320
	s_barrier

.LBB0_341:
	ds_read_b128 v[156:159], v1
	ds_read_b128 v[160:163], v1 offset:1024
	ds_read_b128 v[164:167], v1 offset:2048
	ds_read_b128 v[168:171], v1 offset:3072
	ds_read_b128 v[172:175], v147
	ds_read_b128 v[176:179], v147 offset:1024
	ds_read_b128 v[180:183], v147 offset:2048
	ds_read_b128 v[184:187], v147 offset:3072
	s_add_u32 s38, s36, 0xfffe0080
	s_addc_u32 s39, s37, -1
	s_cmp_eq_u32 s63, 4
	s_cselect_b32 s41, s27, s39
	s_cselect_b32 s40, s59, s38
	s_cselect_b32 s39, s25, s62
	s_cselect_b32 s38, s60, s61
	v_lshl_add_u64 v[148:149], s[36:37], 0, v[138:139]
	s_add_i32 m0, s35, 0xc000
	ds_read_b128 v[188:191], v152
	ds_read_b128 v[192:195], v152 offset:1024
	ds_read_b128 v[196:199], v152 offset:2048
	ds_read_b128 v[200:203], v152 offset:3072
	ds_read_b128 v[204:207], v152 offset:4096
	ds_read_b128 v[208:211], v152 offset:5120
	ds_read_b128 v[212:215], v152 offset:6144
	ds_read_b128 v[216:219], v152 offset:7168
	global_load_lds_dwordx4 v[148:149], off
	v_lshl_add_u64 v[148:149], s[36:37], 0, v[140:141]
	s_add_i32 m0, s35, 0xe000
	s_nop 0
	global_load_lds_dwordx4 v[148:149], off
	s_waitcnt vmcnt(8)
	s_waitcnt lgkmcnt(0)
	s_barrier
	v_mfma_f32_16x16x32_bf16 v[126:129], v[156:159], v[188:191], v[126:129]
	v_mfma_f32_16x16x32_bf16 v[122:125], v[164:167], v[188:191], v[122:125]
	v_mfma_f32_16x16x32_bf16 v[114:117], v[156:159], v[196:199], v[114:117]
	v_mfma_f32_16x16x32_bf16 v[106:109], v[164:167], v[196:199], v[106:109]
	v_mfma_f32_16x16x32_bf16 v[98:101], v[156:159], v[204:207], v[98:101]
	v_mfma_f32_16x16x32_bf16 v[90:93], v[164:167], v[204:207], v[90:93]
	v_mfma_f32_16x16x32_bf16 v[82:85], v[156:159], v[212:215], v[82:85]
	v_mfma_f32_16x16x32_bf16 v[74:77], v[164:167], v[212:215], v[74:77]
	v_mfma_f32_16x16x32_bf16 v[126:129], v[160:163], v[192:195], v[126:129]
	v_mfma_f32_16x16x32_bf16 v[122:125], v[168:171], v[192:195], v[122:125]
	v_mfma_f32_16x16x32_bf16 v[114:117], v[160:163], v[200:203], v[114:117]
	v_mfma_f32_16x16x32_bf16 v[106:109], v[168:171], v[200:203], v[106:109]
	v_mfma_f32_16x16x32_bf16 v[98:101], v[160:163], v[208:211], v[98:101]
	v_mfma_f32_16x16x32_bf16 v[90:93], v[168:171], v[208:211], v[90:93]
	v_mfma_f32_16x16x32_bf16 v[82:85], v[160:163], v[216:219], v[82:85]
	v_mfma_f32_16x16x32_bf16 v[74:77], v[168:171], v[216:219], v[74:77]
	v_mfma_f32_16x16x32_bf16 v[118:121], v[172:175], v[188:191], v[118:121]
	v_mfma_f32_16x16x32_bf16 v[110:113], v[180:183], v[188:191], v[110:113]
	v_mfma_f32_16x16x32_bf16 v[102:105], v[172:175], v[196:199], v[102:105]
	v_mfma_f32_16x16x32_bf16 v[94:97], v[180:183], v[196:199], v[94:97]
	v_mfma_f32_16x16x32_bf16 v[86:89], v[172:175], v[204:207], v[86:89]
	v_mfma_f32_16x16x32_bf16 v[78:81], v[180:183], v[204:207], v[78:81]
	v_mfma_f32_16x16x32_bf16 v[70:73], v[172:175], v[212:215], v[70:73]
	v_mfma_f32_16x16x32_bf16 v[66:69], v[180:183], v[212:215], v[66:69]
	v_mfma_f32_16x16x32_bf16 v[118:121], v[176:179], v[192:195], v[118:121]
	v_mfma_f32_16x16x32_bf16 v[110:113], v[184:187], v[192:195], v[110:113]
	v_mfma_f32_16x16x32_bf16 v[102:105], v[176:179], v[200:203], v[102:105]
	v_mfma_f32_16x16x32_bf16 v[94:97], v[184:187], v[200:203], v[94:97]
	v_mfma_f32_16x16x32_bf16 v[86:89], v[176:179], v[208:211], v[86:89]
	v_mfma_f32_16x16x32_bf16 v[78:81], v[184:187], v[208:211], v[78:81]
	v_mfma_f32_16x16x32_bf16 v[70:73], v[176:179], v[216:219], v[70:73]
	v_mfma_f32_16x16x32_bf16 v[66:69], v[184:187], v[216:219], v[66:69]
	s_barrier
	s_add_i32 s64, s53, s45
	v_lshl_add_u64 v[148:149], s[38:39], 0, v[132:133]
	s_mov_b32 m0, s64
	ds_read_b128 v[188:191], v152 offset:16384
	ds_read_b128 v[192:195], v152 offset:17408
	ds_read_b128 v[196:199], v152 offset:18432
	ds_read_b128 v[200:203], v152 offset:19456
	ds_read_b128 v[204:207], v152 offset:20480
	ds_read_b128 v[208:211], v152 offset:21504
	ds_read_b128 v[212:215], v152 offset:22528
	ds_read_b128 v[216:219], v152 offset:23552
	global_load_lds_dwordx4 v[148:149], off
	s_add_i32 m0, s64, 0x2000
	s_add_u32 s64, s38, 0x20000
	v_lshl_add_u64 v[220:221], s[38:39], 0, v[136:137]
	s_addc_u32 s65, s39, 0
	s_add_i32 s66, s54, s45
	global_load_lds_dwordx4 v[220:221], off
	v_lshl_add_u64 v[222:223], s[64:65], 0, v[132:133]
	s_mov_b32 m0, s66
	v_lshl_add_u64 v[224:225], s[40:41], 0, v[134:135]
	global_load_lds_dwordx4 v[222:223], off
	v_lshl_add_u64 v[222:223], s[64:65], 0, v[136:137]
	s_add_i32 m0, s66, 0x2000
	s_nop 0
	global_load_lds_dwordx4 v[222:223], off
	v_lshl_add_u64 v[222:223], s[40:41], 0, v[130:131]
	s_mov_b32 m0, s35
	s_nop 0
	global_load_lds_dwordx4 v[222:223], off
	s_mov_b32 m0, s46
	s_nop 0
	global_load_lds_dwordx4 v[224:225], off
	s_waitcnt vmcnt(8)
	s_waitcnt lgkmcnt(0)
	s_barrier
	v_mfma_f32_16x16x32_bf16 v[62:65], v[156:159], v[188:191], v[62:65]
	v_mfma_f32_16x16x32_bf16 v[58:61], v[164:167], v[188:191], v[58:61]
	v_mfma_f32_16x16x32_bf16 v[50:53], v[156:159], v[196:199], v[50:53]
	v_mfma_f32_16x16x32_bf16 v[42:45], v[164:167], v[196:199], v[42:45]
	v_mfma_f32_16x16x32_bf16 v[34:37], v[156:159], v[204:207], v[34:37]
	v_mfma_f32_16x16x32_bf16 v[26:29], v[164:167], v[204:207], v[26:29]
	v_mfma_f32_16x16x32_bf16 v[18:21], v[156:159], v[212:215], v[18:21]
	v_mfma_f32_16x16x32_bf16 v[10:13], v[164:167], v[212:215], v[10:13]
	v_mfma_f32_16x16x32_bf16 v[62:65], v[160:163], v[192:195], v[62:65]
	v_mfma_f32_16x16x32_bf16 v[58:61], v[168:171], v[192:195], v[58:61]
	v_mfma_f32_16x16x32_bf16 v[50:53], v[160:163], v[200:203], v[50:53]
	v_mfma_f32_16x16x32_bf16 v[42:45], v[168:171], v[200:203], v[42:45]
	v_mfma_f32_16x16x32_bf16 v[34:37], v[160:163], v[208:211], v[34:37]
	v_mfma_f32_16x16x32_bf16 v[26:29], v[168:171], v[208:211], v[26:29]
	v_mfma_f32_16x16x32_bf16 v[18:21], v[160:163], v[216:219], v[18:21]
	v_mfma_f32_16x16x32_bf16 v[10:13], v[168:171], v[216:219], v[10:13]
	v_mfma_f32_16x16x32_bf16 v[54:57], v[172:175], v[188:191], v[54:57]
	v_mfma_f32_16x16x32_bf16 v[46:49], v[180:183], v[188:191], v[46:49]
	v_mfma_f32_16x16x32_bf16 v[38:41], v[172:175], v[196:199], v[38:41]
	v_mfma_f32_16x16x32_bf16 v[30:33], v[180:183], v[196:199], v[30:33]
	v_mfma_f32_16x16x32_bf16 v[22:25], v[172:175], v[204:207], v[22:25]
	v_mfma_f32_16x16x32_bf16 v[14:17], v[180:183], v[204:207], v[14:17]
	v_mfma_f32_16x16x32_bf16 v[6:9], v[172:175], v[212:215], v[6:9]
	v_mfma_f32_16x16x32_bf16 v[2:5], v[180:183], v[212:215], v[2:5]
	v_mfma_f32_16x16x32_bf16 v[54:57], v[176:179], v[192:195], v[54:57]
	v_mfma_f32_16x16x32_bf16 v[46:49], v[184:187], v[192:195], v[46:49]
	v_mfma_f32_16x16x32_bf16 v[38:41], v[176:179], v[200:203], v[38:41]
	v_mfma_f32_16x16x32_bf16 v[30:33], v[184:187], v[200:203], v[30:33]
	v_mfma_f32_16x16x32_bf16 v[22:25], v[176:179], v[208:211], v[22:25]
	v_mfma_f32_16x16x32_bf16 v[14:17], v[184:187], v[208:211], v[14:17]
	v_mfma_f32_16x16x32_bf16 v[6:9], v[176:179], v[216:219], v[6:9]
	v_mfma_f32_16x16x32_bf16 v[2:5], v[184:187], v[216:219], v[2:5]
	s_barrier
	s_add_i32 s64, 0, 0x18000
	v_add_u32_e32 v146, s64, v151
	s_add_i32 s65, 0, 0x1c000
	ds_read_b128 v[156:159], v146
	ds_read_b128 v[160:163], v146 offset:1024
	ds_read_b128 v[164:167], v146 offset:2048
	ds_read_b128 v[168:171], v146 offset:3072
	v_add_u32_e32 v146, s65, v151
	ds_read_b128 v[172:175], v146
	ds_read_b128 v[176:179], v146 offset:1024
	ds_read_b128 v[180:183], v146 offset:2048
	ds_read_b128 v[184:187], v146 offset:3072
	s_add_u32 s40, s40, 0x20000
	s_addc_u32 s41, s41, 0
	s_mov_b32 m0, s47
	v_lshl_add_u64 v[226:227], s[40:41], 0, v[130:131]
	ds_read_b128 v[188:191], v152 offset:32768
	ds_read_b128 v[192:195], v152 offset:33792
	ds_read_b128 v[196:199], v152 offset:34816
	ds_read_b128 v[200:203], v152 offset:35840
	ds_read_b128 v[204:207], v152 offset:36864
	ds_read_b128 v[208:211], v152 offset:37888
	ds_read_b128 v[212:215], v152 offset:38912
	ds_read_b128 v[216:219], v152 offset:39936
	global_load_lds_dwordx4 v[226:227], off
	v_lshl_add_u64 v[226:227], s[40:41], 0, v[134:135]
	s_mov_b32 m0, s48
	s_nop 0
	global_load_lds_dwordx4 v[226:227], off
	s_waitcnt vmcnt(8)
	s_waitcnt lgkmcnt(0)
	s_barrier
	v_mfma_f32_16x16x32_bf16 v[126:129], v[156:159], v[188:191], v[126:129]
	v_mfma_f32_16x16x32_bf16 v[122:125], v[164:167], v[188:191], v[122:125]
	v_mfma_f32_16x16x32_bf16 v[114:117], v[156:159], v[196:199], v[114:117]
	v_mfma_f32_16x16x32_bf16 v[106:109], v[164:167], v[196:199], v[106:109]
	v_mfma_f32_16x16x32_bf16 v[98:101], v[156:159], v[204:207], v[98:101]
	v_mfma_f32_16x16x32_bf16 v[90:93], v[164:167], v[204:207], v[90:93]
	v_mfma_f32_16x16x32_bf16 v[82:85], v[156:159], v[212:215], v[82:85]
	v_mfma_f32_16x16x32_bf16 v[74:77], v[164:167], v[212:215], v[74:77]
	v_mfma_f32_16x16x32_bf16 v[126:129], v[160:163], v[192:195], v[126:129]
	v_mfma_f32_16x16x32_bf16 v[122:125], v[168:171], v[192:195], v[122:125]
	v_mfma_f32_16x16x32_bf16 v[114:117], v[160:163], v[200:203], v[114:117]
	v_mfma_f32_16x16x32_bf16 v[106:109], v[168:171], v[200:203], v[106:109]
	v_mfma_f32_16x16x32_bf16 v[98:101], v[160:163], v[208:211], v[98:101]
	v_mfma_f32_16x16x32_bf16 v[90:93], v[168:171], v[208:211], v[90:93]
	v_mfma_f32_16x16x32_bf16 v[82:85], v[160:163], v[216:219], v[82:85]
	v_mfma_f32_16x16x32_bf16 v[74:77], v[168:171], v[216:219], v[74:77]
	v_mfma_f32_16x16x32_bf16 v[118:121], v[172:175], v[188:191], v[118:121]
	v_mfma_f32_16x16x32_bf16 v[110:113], v[180:183], v[188:191], v[110:113]
	v_mfma_f32_16x16x32_bf16 v[102:105], v[172:175], v[196:199], v[102:105]
	v_mfma_f32_16x16x32_bf16 v[94:97], v[180:183], v[196:199], v[94:97]
	v_mfma_f32_16x16x32_bf16 v[86:89], v[172:175], v[204:207], v[86:89]
	v_mfma_f32_16x16x32_bf16 v[78:81], v[180:183], v[204:207], v[78:81]
	v_mfma_f32_16x16x32_bf16 v[70:73], v[172:175], v[212:215], v[70:73]
	v_mfma_f32_16x16x32_bf16 v[66:69], v[180:183], v[212:215], v[66:69]
	v_mfma_f32_16x16x32_bf16 v[118:121], v[176:179], v[192:195], v[118:121]
	v_mfma_f32_16x16x32_bf16 v[110:113], v[184:187], v[192:195], v[110:113]
	v_mfma_f32_16x16x32_bf16 v[102:105], v[176:179], v[200:203], v[102:105]
	v_mfma_f32_16x16x32_bf16 v[94:97], v[184:187], v[200:203], v[94:97]
	v_mfma_f32_16x16x32_bf16 v[86:89], v[176:179], v[208:211], v[86:89]
	v_mfma_f32_16x16x32_bf16 v[78:81], v[184:187], v[208:211], v[78:81]
	v_mfma_f32_16x16x32_bf16 v[70:73], v[176:179], v[216:219], v[70:73]
	v_mfma_f32_16x16x32_bf16 v[66:69], v[184:187], v[216:219], v[66:69]
	s_barrier
	s_add_i32 s40, s64, s45
	v_lshl_add_u64 v[148:149], v[148:149], 0, s[12:13]
	s_mov_b32 m0, s40
	ds_read_b128 v[188:191], v152 offset:49152
	ds_read_b128 v[192:195], v152 offset:50176
	ds_read_b128 v[196:199], v152 offset:51200
	ds_read_b128 v[200:203], v152 offset:52224
	ds_read_b128 v[204:207], v152 offset:53248
	ds_read_b128 v[208:211], v152 offset:54272
	ds_read_b128 v[212:215], v152 offset:55296
	ds_read_b128 v[216:219], v152 offset:56320
	global_load_lds_dwordx4 v[148:149], off
	s_add_i32 m0, s40, 0x2000
	s_add_u32 s38, s38, 0x20080
	v_lshl_add_u64 v[148:149], v[220:221], 0, s[12:13]
	s_addc_u32 s39, s39, 0
	s_add_i32 s40, s65, s45
	global_load_lds_dwordx4 v[148:149], off
	v_lshl_add_u64 v[148:149], s[38:39], 0, v[132:133]
	s_mov_b32 m0, s40
	s_nop 0
	global_load_lds_dwordx4 v[148:149], off
	v_lshl_add_u64 v[148:149], s[38:39], 0, v[136:137]
	s_add_i32 m0, s40, 0x2000
	s_nop 0
	global_load_lds_dwordx4 v[148:149], off
	v_lshl_add_u64 v[148:149], v[222:223], 0, s[12:13]
	s_mov_b32 m0, s50
	s_nop 0
	global_load_lds_dwordx4 v[148:149], off
	v_lshl_add_u64 v[148:149], v[224:225], 0, s[12:13]
	s_mov_b32 m0, s51
	s_nop 0
	global_load_lds_dwordx4 v[148:149], off
	s_waitcnt vmcnt(8)
	s_waitcnt lgkmcnt(0)
	s_barrier
	v_mfma_f32_16x16x32_bf16 v[62:65], v[156:159], v[188:191], v[62:65]
	v_mfma_f32_16x16x32_bf16 v[58:61], v[164:167], v[188:191], v[58:61]
	v_mfma_f32_16x16x32_bf16 v[50:53], v[156:159], v[196:199], v[50:53]
	v_mfma_f32_16x16x32_bf16 v[42:45], v[164:167], v[196:199], v[42:45]
	v_mfma_f32_16x16x32_bf16 v[34:37], v[156:159], v[204:207], v[34:37]
	v_mfma_f32_16x16x32_bf16 v[26:29], v[164:167], v[204:207], v[26:29]
	v_mfma_f32_16x16x32_bf16 v[18:21], v[156:159], v[212:215], v[18:21]
	v_mfma_f32_16x16x32_bf16 v[10:13], v[164:167], v[212:215], v[10:13]
	v_mfma_f32_16x16x32_bf16 v[62:65], v[160:163], v[192:195], v[62:65]
	v_mfma_f32_16x16x32_bf16 v[58:61], v[168:171], v[192:195], v[58:61]
	v_mfma_f32_16x16x32_bf16 v[50:53], v[160:163], v[200:203], v[50:53]
	v_mfma_f32_16x16x32_bf16 v[42:45], v[168:171], v[200:203], v[42:45]
	v_mfma_f32_16x16x32_bf16 v[34:37], v[160:163], v[208:211], v[34:37]
	v_mfma_f32_16x16x32_bf16 v[26:29], v[168:171], v[208:211], v[26:29]
	v_mfma_f32_16x16x32_bf16 v[18:21], v[160:163], v[216:219], v[18:21]
	v_mfma_f32_16x16x32_bf16 v[10:13], v[168:171], v[216:219], v[10:13]
	v_mfma_f32_16x16x32_bf16 v[54:57], v[172:175], v[188:191], v[54:57]
	v_mfma_f32_16x16x32_bf16 v[46:49], v[180:183], v[188:191], v[46:49]
	v_mfma_f32_16x16x32_bf16 v[38:41], v[172:175], v[196:199], v[38:41]
	v_mfma_f32_16x16x32_bf16 v[30:33], v[180:183], v[196:199], v[30:33]
	v_mfma_f32_16x16x32_bf16 v[22:25], v[172:175], v[204:207], v[22:25]
	v_mfma_f32_16x16x32_bf16 v[14:17], v[180:183], v[204:207], v[14:17]
	v_mfma_f32_16x16x32_bf16 v[6:9], v[172:175], v[212:215], v[6:9]
	v_mfma_f32_16x16x32_bf16 v[2:5], v[180:183], v[212:215], v[2:5]
	v_mfma_f32_16x16x32_bf16 v[54:57], v[176:179], v[192:195], v[54:57]
	v_mfma_f32_16x16x32_bf16 v[46:49], v[184:187], v[192:195], v[46:49]
	v_mfma_f32_16x16x32_bf16 v[38:41], v[176:179], v[200:203], v[38:41]
	v_mfma_f32_16x16x32_bf16 v[30:33], v[184:187], v[200:203], v[30:33]
	v_mfma_f32_16x16x32_bf16 v[22:25], v[176:179], v[208:211], v[22:25]
	v_mfma_f32_16x16x32_bf16 v[14:17], v[184:187], v[208:211], v[14:17]
	v_mfma_f32_16x16x32_bf16 v[6:9], v[176:179], v[216:219], v[6:9]
	v_mfma_f32_16x16x32_bf16 v[2:5], v[184:187], v[216:219], v[2:5]
	s_barrier
	s_add_i32 s63, s63, 2
	s_add_u32 s36, s36, 0x100
	s_addc_u32 s37, s37, 0
	s_add_u32 s61, s61, 0x100
	s_addc_u32 s62, s62, 0
	s_cmp_gt_u32 s63, 5
	s_cbranch_scc0 .LBB0_341
	s_and_b64 vcc, exec, s[14:15]
	s_cbranch_vccz .LBB0_344
	s_barrier

.LBB0_728:
	ds_read_b128 v[130:133], v156
	ds_read_b128 v[134:137], v156 offset:1024
	ds_read_b128 v[160:163], v156 offset:2048
	ds_read_b128 v[164:167], v156 offset:3072
	ds_read_b128 v[168:171], v157
	ds_read_b128 v[172:175], v157 offset:1024
	ds_read_b128 v[176:179], v157 offset:2048
	ds_read_b128 v[180:183], v157 offset:3072
	s_add_u32 s28, s26, 0xfff00080
	s_addc_u32 s29, s27, -1
	s_cmp_eq_u32 s48, 60
	s_cselect_b32 s31, s19, s29
	s_cselect_b32 s30, s44, s28
	s_cselect_b32 s29, s17, s47
	s_cselect_b32 s28, s45, s46
	v_lshl_add_u64 v[216:217], s[26:27], 0, v[146:147]
	s_add_i32 m0, s25, 0xc000
	ds_read_b128 v[184:187], v158
	ds_read_b128 v[188:191], v158 offset:1024
	ds_read_b128 v[192:195], v158 offset:2048
	ds_read_b128 v[196:199], v158 offset:3072
	ds_read_b128 v[200:203], v158 offset:4096
	ds_read_b128 v[204:207], v158 offset:5120
	ds_read_b128 v[208:211], v158 offset:6144
	ds_read_b128 v[212:215], v158 offset:7168
	global_load_lds_dwordx4 v[216:217], off
	v_lshl_add_u64 v[216:217], s[26:27], 0, v[148:149]
	s_add_i32 m0, s25, 0xe000
	s_nop 0
	global_load_lds_dwordx4 v[216:217], off
	s_waitcnt vmcnt(8)
	s_waitcnt lgkmcnt(0)
	s_barrier
	v_mfma_f32_16x16x32_bf16 v[126:129], v[130:133], v[184:187], v[126:129]
	v_mfma_f32_16x16x32_bf16 v[122:125], v[160:163], v[184:187], v[122:125]
	v_mfma_f32_16x16x32_bf16 v[118:121], v[130:133], v[192:195], v[118:121]
	v_mfma_f32_16x16x32_bf16 v[114:117], v[160:163], v[192:195], v[114:117]
	v_mfma_f32_16x16x32_bf16 v[94:97], v[130:133], v[200:203], v[94:97]
	v_mfma_f32_16x16x32_bf16 v[90:93], v[160:163], v[200:203], v[90:93]
	v_mfma_f32_16x16x32_bf16 v[82:85], v[130:133], v[208:211], v[82:85]
	v_mfma_f32_16x16x32_bf16 v[74:77], v[160:163], v[208:211], v[74:77]
	v_mfma_f32_16x16x32_bf16 v[126:129], v[134:137], v[188:191], v[126:129]
	v_mfma_f32_16x16x32_bf16 v[122:125], v[164:167], v[188:191], v[122:125]
	v_mfma_f32_16x16x32_bf16 v[118:121], v[134:137], v[196:199], v[118:121]
	v_mfma_f32_16x16x32_bf16 v[114:117], v[164:167], v[196:199], v[114:117]
	v_mfma_f32_16x16x32_bf16 v[94:97], v[134:137], v[204:207], v[94:97]
	v_mfma_f32_16x16x32_bf16 v[90:93], v[164:167], v[204:207], v[90:93]
	v_mfma_f32_16x16x32_bf16 v[82:85], v[134:137], v[212:215], v[82:85]
	v_mfma_f32_16x16x32_bf16 v[74:77], v[164:167], v[212:215], v[74:77]
	v_mfma_f32_16x16x32_bf16 v[110:113], v[168:171], v[184:187], v[110:113]
	v_mfma_f32_16x16x32_bf16 v[106:109], v[176:179], v[184:187], v[106:109]
	v_mfma_f32_16x16x32_bf16 v[102:105], v[168:171], v[192:195], v[102:105]
	v_mfma_f32_16x16x32_bf16 v[98:101], v[176:179], v[192:195], v[98:101]
	v_mfma_f32_16x16x32_bf16 v[86:89], v[168:171], v[200:203], v[86:89]
	v_mfma_f32_16x16x32_bf16 v[78:81], v[176:179], v[200:203], v[78:81]
	v_mfma_f32_16x16x32_bf16 v[70:73], v[168:171], v[208:211], v[70:73]
	v_mfma_f32_16x16x32_bf16 v[66:69], v[176:179], v[208:211], v[66:69]
	v_mfma_f32_16x16x32_bf16 v[110:113], v[172:175], v[188:191], v[110:113]
	v_mfma_f32_16x16x32_bf16 v[106:109], v[180:183], v[188:191], v[106:109]
	v_mfma_f32_16x16x32_bf16 v[102:105], v[172:175], v[196:199], v[102:105]
	v_mfma_f32_16x16x32_bf16 v[98:101], v[180:183], v[196:199], v[98:101]
	v_mfma_f32_16x16x32_bf16 v[86:89], v[172:175], v[204:207], v[86:89]
	v_mfma_f32_16x16x32_bf16 v[78:81], v[180:183], v[204:207], v[78:81]
	v_mfma_f32_16x16x32_bf16 v[70:73], v[172:175], v[212:215], v[70:73]
	v_mfma_f32_16x16x32_bf16 v[66:69], v[180:183], v[212:215], v[66:69]
	s_barrier
	s_add_i32 s49, s42, s34
	v_lshl_add_u64 v[216:217], s[28:29], 0, v[140:141]
	s_mov_b32 m0, s49
	ds_read_b128 v[184:187], v158 offset:16384
	ds_read_b128 v[188:191], v158 offset:17408
	ds_read_b128 v[192:195], v158 offset:18432
	ds_read_b128 v[196:199], v158 offset:19456
	ds_read_b128 v[200:203], v158 offset:20480
	ds_read_b128 v[204:207], v158 offset:21504
	ds_read_b128 v[208:211], v158 offset:22528
	ds_read_b128 v[212:215], v158 offset:23552
	global_load_lds_dwordx4 v[216:217], off
	s_add_i32 m0, s49, 0x2000
	s_add_u32 s50, s28, 0x100000
	v_lshl_add_u64 v[218:219], s[28:29], 0, v[144:145]
	s_addc_u32 s51, s29, 0
	s_add_i32 s49, s43, s34
	global_load_lds_dwordx4 v[218:219], off
	v_lshl_add_u64 v[220:221], s[50:51], 0, v[140:141]
	s_mov_b32 m0, s49
	v_lshl_add_u64 v[222:223], s[30:31], 0, v[142:143]
	global_load_lds_dwordx4 v[220:221], off
	v_lshl_add_u64 v[220:221], s[50:51], 0, v[144:145]
	s_add_i32 m0, s49, 0x2000
	s_nop 0
	global_load_lds_dwordx4 v[220:221], off
	v_lshl_add_u64 v[220:221], s[30:31], 0, v[138:139]
	s_mov_b32 m0, s25
	s_nop 0
	global_load_lds_dwordx4 v[220:221], off
	s_mov_b32 m0, s35
	s_nop 0
	global_load_lds_dwordx4 v[222:223], off
	s_waitcnt vmcnt(8)
	s_waitcnt lgkmcnt(0)
	s_barrier
	v_mfma_f32_16x16x32_bf16 v[62:65], v[130:133], v[184:187], v[62:65]
	v_mfma_f32_16x16x32_bf16 v[58:61], v[160:163], v[184:187], v[58:61]
	v_mfma_f32_16x16x32_bf16 v[50:53], v[130:133], v[192:195], v[50:53]
	v_mfma_f32_16x16x32_bf16 v[42:45], v[160:163], v[192:195], v[42:45]
	v_mfma_f32_16x16x32_bf16 v[34:37], v[130:133], v[200:203], v[34:37]
	v_mfma_f32_16x16x32_bf16 v[26:29], v[160:163], v[200:203], v[26:29]
	v_mfma_f32_16x16x32_bf16 v[18:21], v[130:133], v[208:211], v[18:21]
	v_mfma_f32_16x16x32_bf16 v[10:13], v[160:163], v[208:211], v[10:13]
	v_mfma_f32_16x16x32_bf16 v[62:65], v[134:137], v[188:191], v[62:65]
	v_mfma_f32_16x16x32_bf16 v[58:61], v[164:167], v[188:191], v[58:61]
	v_mfma_f32_16x16x32_bf16 v[50:53], v[134:137], v[196:199], v[50:53]
	v_mfma_f32_16x16x32_bf16 v[42:45], v[164:167], v[196:199], v[42:45]
	v_mfma_f32_16x16x32_bf16 v[34:37], v[134:137], v[204:207], v[34:37]
	v_mfma_f32_16x16x32_bf16 v[26:29], v[164:167], v[204:207], v[26:29]
	v_mfma_f32_16x16x32_bf16 v[18:21], v[134:137], v[212:215], v[18:21]
	v_mfma_f32_16x16x32_bf16 v[10:13], v[164:167], v[212:215], v[10:13]
	v_mfma_f32_16x16x32_bf16 v[54:57], v[168:171], v[184:187], v[54:57]
	v_mfma_f32_16x16x32_bf16 v[46:49], v[176:179], v[184:187], v[46:49]
	v_mfma_f32_16x16x32_bf16 v[38:41], v[168:171], v[192:195], v[38:41]
	v_mfma_f32_16x16x32_bf16 v[30:33], v[176:179], v[192:195], v[30:33]
	v_mfma_f32_16x16x32_bf16 v[22:25], v[168:171], v[200:203], v[22:25]
	v_mfma_f32_16x16x32_bf16 v[14:17], v[176:179], v[200:203], v[14:17]
	v_mfma_f32_16x16x32_bf16 v[6:9], v[168:171], v[208:211], v[6:9]
	v_mfma_f32_16x16x32_bf16 v[2:5], v[176:179], v[208:211], v[2:5]
	v_mfma_f32_16x16x32_bf16 v[54:57], v[172:175], v[188:191], v[54:57]
	v_mfma_f32_16x16x32_bf16 v[46:49], v[180:183], v[188:191], v[46:49]
	v_mfma_f32_16x16x32_bf16 v[38:41], v[172:175], v[196:199], v[38:41]
	v_mfma_f32_16x16x32_bf16 v[30:33], v[180:183], v[196:199], v[30:33]
	v_mfma_f32_16x16x32_bf16 v[22:25], v[172:175], v[204:207], v[22:25]
	v_mfma_f32_16x16x32_bf16 v[14:17], v[180:183], v[204:207], v[14:17]
	v_mfma_f32_16x16x32_bf16 v[6:9], v[172:175], v[212:215], v[6:9]
	v_mfma_f32_16x16x32_bf16 v[2:5], v[180:183], v[212:215], v[2:5]
	s_barrier
	s_add_i32 s49, 0, 0x18000
	v_add_u32_e32 v159, s49, v154
	s_add_i32 s50, 0, 0x1c000
	ds_read_b128 v[130:133], v159
	ds_read_b128 v[134:137], v159 offset:1024
	ds_read_b128 v[160:163], v159 offset:2048
	ds_read_b128 v[164:167], v159 offset:3072
	v_add_u32_e32 v159, s50, v154
	ds_read_b128 v[168:171], v159
	ds_read_b128 v[172:175], v159 offset:1024
	ds_read_b128 v[176:179], v159 offset:2048
	ds_read_b128 v[180:183], v159 offset:3072
	s_add_u32 s30, s30, 0x100000
	s_addc_u32 s31, s31, 0
	s_mov_b32 m0, s36
	v_lshl_add_u64 v[224:225], s[30:31], 0, v[138:139]
	ds_read_b128 v[184:187], v158 offset:32768
	ds_read_b128 v[188:191], v158 offset:33792
	ds_read_b128 v[192:195], v158 offset:34816
	ds_read_b128 v[196:199], v158 offset:35840
	ds_read_b128 v[200:203], v158 offset:36864
	ds_read_b128 v[204:207], v158 offset:37888
	ds_read_b128 v[208:211], v158 offset:38912
	ds_read_b128 v[212:215], v158 offset:39936
	global_load_lds_dwordx4 v[224:225], off
	v_lshl_add_u64 v[224:225], s[30:31], 0, v[142:143]
	s_mov_b32 m0, s37
	s_nop 0
	global_load_lds_dwordx4 v[224:225], off
	s_waitcnt vmcnt(8)
	s_waitcnt lgkmcnt(0)
	s_barrier
	v_mfma_f32_16x16x32_bf16 v[126:129], v[130:133], v[184:187], v[126:129]
	v_mfma_f32_16x16x32_bf16 v[122:125], v[160:163], v[184:187], v[122:125]
	v_mfma_f32_16x16x32_bf16 v[118:121], v[130:133], v[192:195], v[118:121]
	v_mfma_f32_16x16x32_bf16 v[114:117], v[160:163], v[192:195], v[114:117]
	v_mfma_f32_16x16x32_bf16 v[94:97], v[130:133], v[200:203], v[94:97]
	v_mfma_f32_16x16x32_bf16 v[90:93], v[160:163], v[200:203], v[90:93]
	v_mfma_f32_16x16x32_bf16 v[82:85], v[130:133], v[208:211], v[82:85]
	v_mfma_f32_16x16x32_bf16 v[74:77], v[160:163], v[208:211], v[74:77]
	v_mfma_f32_16x16x32_bf16 v[126:129], v[134:137], v[188:191], v[126:129]
	v_mfma_f32_16x16x32_bf16 v[122:125], v[164:167], v[188:191], v[122:125]
	v_mfma_f32_16x16x32_bf16 v[118:121], v[134:137], v[196:199], v[118:121]
	v_mfma_f32_16x16x32_bf16 v[114:117], v[164:167], v[196:199], v[114:117]
	v_mfma_f32_16x16x32_bf16 v[94:97], v[134:137], v[204:207], v[94:97]
	v_mfma_f32_16x16x32_bf16 v[90:93], v[164:167], v[204:207], v[90:93]
	v_mfma_f32_16x16x32_bf16 v[82:85], v[134:137], v[212:215], v[82:85]
	v_mfma_f32_16x16x32_bf16 v[74:77], v[164:167], v[212:215], v[74:77]
	v_mfma_f32_16x16x32_bf16 v[110:113], v[168:171], v[184:187], v[110:113]
	v_mfma_f32_16x16x32_bf16 v[106:109], v[176:179], v[184:187], v[106:109]
	v_mfma_f32_16x16x32_bf16 v[102:105], v[168:171], v[192:195], v[102:105]
	v_mfma_f32_16x16x32_bf16 v[98:101], v[176:179], v[192:195], v[98:101]
	v_mfma_f32_16x16x32_bf16 v[86:89], v[168:171], v[200:203], v[86:89]
	v_mfma_f32_16x16x32_bf16 v[78:81], v[176:179], v[200:203], v[78:81]
	v_mfma_f32_16x16x32_bf16 v[70:73], v[168:171], v[208:211], v[70:73]
	v_mfma_f32_16x16x32_bf16 v[66:69], v[176:179], v[208:211], v[66:69]
	v_mfma_f32_16x16x32_bf16 v[110:113], v[172:175], v[188:191], v[110:113]
	v_mfma_f32_16x16x32_bf16 v[106:109], v[180:183], v[188:191], v[106:109]
	v_mfma_f32_16x16x32_bf16 v[102:105], v[172:175], v[196:199], v[102:105]
	v_mfma_f32_16x16x32_bf16 v[98:101], v[180:183], v[196:199], v[98:101]
	v_mfma_f32_16x16x32_bf16 v[86:89], v[172:175], v[204:207], v[86:89]
	v_mfma_f32_16x16x32_bf16 v[78:81], v[180:183], v[204:207], v[78:81]
	v_mfma_f32_16x16x32_bf16 v[70:73], v[172:175], v[212:215], v[70:73]
	v_mfma_f32_16x16x32_bf16 v[66:69], v[180:183], v[212:215], v[66:69]
	s_barrier
	s_add_i32 s30, s49, s34
	v_lshl_add_u64 v[216:217], v[216:217], 0, s[10:11]
	s_mov_b32 m0, s30
	ds_read_b128 v[184:187], v158 offset:49152
	ds_read_b128 v[188:191], v158 offset:50176
	ds_read_b128 v[192:195], v158 offset:51200
	ds_read_b128 v[196:199], v158 offset:52224
	ds_read_b128 v[200:203], v158 offset:53248
	ds_read_b128 v[204:207], v158 offset:54272
	ds_read_b128 v[208:211], v158 offset:55296
	ds_read_b128 v[212:215], v158 offset:56320
	global_load_lds_dwordx4 v[216:217], off
	s_add_i32 m0, s30, 0x2000
	s_add_u32 s28, s28, 0x100080
	v_lshl_add_u64 v[216:217], v[218:219], 0, s[10:11]
	s_addc_u32 s29, s29, 0
	s_add_i32 s30, s50, s34
	global_load_lds_dwordx4 v[216:217], off
	v_lshl_add_u64 v[216:217], s[28:29], 0, v[140:141]
	s_mov_b32 m0, s30
	s_nop 0
	global_load_lds_dwordx4 v[216:217], off
	v_lshl_add_u64 v[216:217], s[28:29], 0, v[144:145]
	s_add_i32 m0, s30, 0x2000
	s_nop 0
	global_load_lds_dwordx4 v[216:217], off
	v_lshl_add_u64 v[216:217], v[220:221], 0, s[10:11]
	s_mov_b32 m0, s39
	s_nop 0
	global_load_lds_dwordx4 v[216:217], off
	v_lshl_add_u64 v[216:217], v[222:223], 0, s[10:11]
	s_mov_b32 m0, s40
	s_nop 0
	global_load_lds_dwordx4 v[216:217], off
	s_waitcnt vmcnt(8)
	s_waitcnt lgkmcnt(0)
	s_barrier
	v_mfma_f32_16x16x32_bf16 v[62:65], v[130:133], v[184:187], v[62:65]
	v_mfma_f32_16x16x32_bf16 v[58:61], v[160:163], v[184:187], v[58:61]
	v_mfma_f32_16x16x32_bf16 v[50:53], v[130:133], v[192:195], v[50:53]
	v_mfma_f32_16x16x32_bf16 v[42:45], v[160:163], v[192:195], v[42:45]
	v_mfma_f32_16x16x32_bf16 v[34:37], v[130:133], v[200:203], v[34:37]
	v_mfma_f32_16x16x32_bf16 v[26:29], v[160:163], v[200:203], v[26:29]
	v_mfma_f32_16x16x32_bf16 v[18:21], v[130:133], v[208:211], v[18:21]
	v_mfma_f32_16x16x32_bf16 v[10:13], v[160:163], v[208:211], v[10:13]
	v_mfma_f32_16x16x32_bf16 v[62:65], v[134:137], v[188:191], v[62:65]
	v_mfma_f32_16x16x32_bf16 v[58:61], v[164:167], v[188:191], v[58:61]
	v_mfma_f32_16x16x32_bf16 v[50:53], v[134:137], v[196:199], v[50:53]
	v_mfma_f32_16x16x32_bf16 v[42:45], v[164:167], v[196:199], v[42:45]
	v_mfma_f32_16x16x32_bf16 v[34:37], v[134:137], v[204:207], v[34:37]
	v_mfma_f32_16x16x32_bf16 v[26:29], v[164:167], v[204:207], v[26:29]
	v_mfma_f32_16x16x32_bf16 v[18:21], v[134:137], v[212:215], v[18:21]
	v_mfma_f32_16x16x32_bf16 v[10:13], v[164:167], v[212:215], v[10:13]
	v_mfma_f32_16x16x32_bf16 v[54:57], v[168:171], v[184:187], v[54:57]
	v_mfma_f32_16x16x32_bf16 v[46:49], v[176:179], v[184:187], v[46:49]
	v_mfma_f32_16x16x32_bf16 v[38:41], v[168:171], v[192:195], v[38:41]
	v_mfma_f32_16x16x32_bf16 v[30:33], v[176:179], v[192:195], v[30:33]
	v_mfma_f32_16x16x32_bf16 v[22:25], v[168:171], v[200:203], v[22:25]
	v_mfma_f32_16x16x32_bf16 v[14:17], v[176:179], v[200:203], v[14:17]
	v_mfma_f32_16x16x32_bf16 v[6:9], v[168:171], v[208:211], v[6:9]
	v_mfma_f32_16x16x32_bf16 v[2:5], v[176:179], v[208:211], v[2:5]
	v_mfma_f32_16x16x32_bf16 v[54:57], v[172:175], v[188:191], v[54:57]
	v_mfma_f32_16x16x32_bf16 v[46:49], v[180:183], v[188:191], v[46:49]
	v_mfma_f32_16x16x32_bf16 v[38:41], v[172:175], v[196:199], v[38:41]
	v_mfma_f32_16x16x32_bf16 v[30:33], v[180:183], v[196:199], v[30:33]
	v_mfma_f32_16x16x32_bf16 v[22:25], v[172:175], v[204:207], v[22:25]
	v_mfma_f32_16x16x32_bf16 v[14:17], v[180:183], v[204:207], v[14:17]
	v_mfma_f32_16x16x32_bf16 v[6:9], v[172:175], v[212:215], v[6:9]
	v_mfma_f32_16x16x32_bf16 v[2:5], v[180:183], v[212:215], v[2:5]
	s_barrier
	s_add_i32 s48, s48, 2
	s_add_u32 s26, s26, 0x100
	s_addc_u32 s27, s27, 0
	s_add_u32 s46, s46, 0x100
	s_addc_u32 s47, s47, 0
	s_cmp_gt_u32 s48, 61
	s_cbranch_scc0 .LBB0_728
	s_and_b64 vcc, exec, s[12:13]
	s_cbranch_vccz .LBB0_731
	s_barrier

.LBB0_860:
	ds_read_b128 v[156:159], v153
	ds_read_b128 v[160:163], v153 offset:1024
	ds_read_b128 v[164:167], v153 offset:2048
	ds_read_b128 v[168:171], v153 offset:3072
	ds_read_b128 v[172:175], v154
	ds_read_b128 v[176:179], v154 offset:1024
	ds_read_b128 v[180:183], v154 offset:2048
	ds_read_b128 v[184:187], v154 offset:3072
	s_add_u32 s28, s26, 0xfff00080
	s_addc_u32 s29, s27, -1
	s_cmp_eq_u32 s51, 60
	s_cselect_b32 s31, s19, s29
	s_cselect_b32 s30, s47, s28
	s_cselect_b32 s29, s17, s50
	s_cselect_b32 s28, s48, s49
	v_lshl_add_u64 v[146:147], s[26:27], 0, v[138:139]
	s_add_i32 m0, s25, 0xc000
	ds_read_b128 v[188:191], v155
	ds_read_b128 v[192:195], v155 offset:1024
	ds_read_b128 v[196:199], v155 offset:2048
	ds_read_b128 v[200:203], v155 offset:3072
	ds_read_b128 v[204:207], v155 offset:4096
	ds_read_b128 v[208:211], v155 offset:5120
	ds_read_b128 v[212:215], v155 offset:6144
	ds_read_b128 v[216:219], v155 offset:7168
	global_load_lds_dwordx4 v[146:147], off
	v_lshl_add_u64 v[146:147], s[26:27], 0, v[140:141]
	s_add_i32 m0, s25, 0xe000
	s_nop 0
	global_load_lds_dwordx4 v[146:147], off
	s_waitcnt vmcnt(8)
	s_waitcnt lgkmcnt(0)
	s_barrier
	v_mfma_f32_16x16x32_bf16 v[126:129], v[156:159], v[188:191], v[126:129]
	v_mfma_f32_16x16x32_bf16 v[122:125], v[164:167], v[188:191], v[122:125]
	v_mfma_f32_16x16x32_bf16 v[110:113], v[156:159], v[196:199], v[110:113]
	v_mfma_f32_16x16x32_bf16 v[106:109], v[164:167], v[196:199], v[106:109]
	v_mfma_f32_16x16x32_bf16 v[94:97], v[156:159], v[204:207], v[94:97]
	v_mfma_f32_16x16x32_bf16 v[90:93], v[164:167], v[204:207], v[90:93]
	v_mfma_f32_16x16x32_bf16 v[78:81], v[156:159], v[212:215], v[78:81]
	v_mfma_f32_16x16x32_bf16 v[74:77], v[164:167], v[212:215], v[74:77]
	v_mfma_f32_16x16x32_bf16 v[126:129], v[160:163], v[192:195], v[126:129]
	v_mfma_f32_16x16x32_bf16 v[122:125], v[168:171], v[192:195], v[122:125]
	v_mfma_f32_16x16x32_bf16 v[110:113], v[160:163], v[200:203], v[110:113]
	v_mfma_f32_16x16x32_bf16 v[106:109], v[168:171], v[200:203], v[106:109]
	v_mfma_f32_16x16x32_bf16 v[94:97], v[160:163], v[208:211], v[94:97]
	v_mfma_f32_16x16x32_bf16 v[90:93], v[168:171], v[208:211], v[90:93]
	v_mfma_f32_16x16x32_bf16 v[78:81], v[160:163], v[216:219], v[78:81]
	v_mfma_f32_16x16x32_bf16 v[74:77], v[168:171], v[216:219], v[74:77]
	v_mfma_f32_16x16x32_bf16 v[118:121], v[172:175], v[188:191], v[118:121]
	v_mfma_f32_16x16x32_bf16 v[114:117], v[180:183], v[188:191], v[114:117]
	v_mfma_f32_16x16x32_bf16 v[102:105], v[172:175], v[196:199], v[102:105]
	v_mfma_f32_16x16x32_bf16 v[98:101], v[180:183], v[196:199], v[98:101]
	v_mfma_f32_16x16x32_bf16 v[86:89], v[172:175], v[204:207], v[86:89]
	v_mfma_f32_16x16x32_bf16 v[82:85], v[180:183], v[204:207], v[82:85]
	v_mfma_f32_16x16x32_bf16 v[70:73], v[172:175], v[212:215], v[70:73]
	v_mfma_f32_16x16x32_bf16 v[66:69], v[180:183], v[212:215], v[66:69]
	v_mfma_f32_16x16x32_bf16 v[118:121], v[176:179], v[192:195], v[118:121]
	v_mfma_f32_16x16x32_bf16 v[114:117], v[184:187], v[192:195], v[114:117]
	v_mfma_f32_16x16x32_bf16 v[102:105], v[176:179], v[200:203], v[102:105]
	v_mfma_f32_16x16x32_bf16 v[98:101], v[184:187], v[200:203], v[98:101]
	v_mfma_f32_16x16x32_bf16 v[86:89], v[176:179], v[208:211], v[86:89]
	v_mfma_f32_16x16x32_bf16 v[82:85], v[184:187], v[208:211], v[82:85]
	v_mfma_f32_16x16x32_bf16 v[70:73], v[176:179], v[216:219], v[70:73]
	v_mfma_f32_16x16x32_bf16 v[66:69], v[184:187], v[216:219], v[66:69]
	s_barrier
	s_add_i32 s52, s44, s34
	v_lshl_add_u64 v[146:147], s[28:29], 0, v[134:135]
	s_mov_b32 m0, s52
	ds_read_b128 v[188:191], v155 offset:16384
	ds_read_b128 v[192:195], v155 offset:17408
	ds_read_b128 v[196:199], v155 offset:18432
	ds_read_b128 v[200:203], v155 offset:19456
	ds_read_b128 v[204:207], v155 offset:20480
	ds_read_b128 v[208:211], v155 offset:21504
	ds_read_b128 v[212:215], v155 offset:22528
	ds_read_b128 v[216:219], v155 offset:23552
	global_load_lds_dwordx4 v[146:147], off
	s_add_i32 m0, s52, 0x2000
	s_add_u32 s52, s28, 0x100000
	v_lshl_add_u64 v[220:221], s[28:29], 0, v[130:131]
	s_addc_u32 s53, s29, 0
	s_add_i32 s54, s45, s34
	global_load_lds_dwordx4 v[220:221], off
	v_lshl_add_u64 v[222:223], s[52:53], 0, v[134:135]
	s_mov_b32 m0, s54
	v_lshl_add_u64 v[224:225], s[30:31], 0, v[132:133]
	global_load_lds_dwordx4 v[222:223], off
	v_lshl_add_u64 v[222:223], s[52:53], 0, v[130:131]
	s_add_i32 m0, s54, 0x2000
	s_nop 0
	global_load_lds_dwordx4 v[222:223], off
	v_lshl_add_u64 v[222:223], s[30:31], 0, v[136:137]
	s_mov_b32 m0, s25
	s_nop 0
	global_load_lds_dwordx4 v[222:223], off
	s_mov_b32 m0, s37
	s_nop 0
	global_load_lds_dwordx4 v[224:225], off
	s_waitcnt vmcnt(8)
	s_waitcnt lgkmcnt(0)
	s_barrier
	v_mfma_f32_16x16x32_bf16 v[62:65], v[156:159], v[188:191], v[62:65]
	v_mfma_f32_16x16x32_bf16 v[58:61], v[164:167], v[188:191], v[58:61]
	v_mfma_f32_16x16x32_bf16 v[46:49], v[156:159], v[196:199], v[46:49]
	v_mfma_f32_16x16x32_bf16 v[42:45], v[164:167], v[196:199], v[42:45]
	v_mfma_f32_16x16x32_bf16 v[30:33], v[156:159], v[204:207], v[30:33]
	v_mfma_f32_16x16x32_bf16 v[26:29], v[164:167], v[204:207], v[26:29]
	v_mfma_f32_16x16x32_bf16 v[14:17], v[156:159], v[212:215], v[14:17]
	v_mfma_f32_16x16x32_bf16 v[10:13], v[164:167], v[212:215], v[10:13]
	v_mfma_f32_16x16x32_bf16 v[62:65], v[160:163], v[192:195], v[62:65]
	v_mfma_f32_16x16x32_bf16 v[58:61], v[168:171], v[192:195], v[58:61]
	v_mfma_f32_16x16x32_bf16 v[46:49], v[160:163], v[200:203], v[46:49]
	v_mfma_f32_16x16x32_bf16 v[42:45], v[168:171], v[200:203], v[42:45]
	v_mfma_f32_16x16x32_bf16 v[30:33], v[160:163], v[208:211], v[30:33]
	v_mfma_f32_16x16x32_bf16 v[26:29], v[168:171], v[208:211], v[26:29]
	v_mfma_f32_16x16x32_bf16 v[14:17], v[160:163], v[216:219], v[14:17]
	v_mfma_f32_16x16x32_bf16 v[10:13], v[168:171], v[216:219], v[10:13]
	v_mfma_f32_16x16x32_bf16 v[54:57], v[172:175], v[188:191], v[54:57]
	v_mfma_f32_16x16x32_bf16 v[50:53], v[180:183], v[188:191], v[50:53]
	v_mfma_f32_16x16x32_bf16 v[38:41], v[172:175], v[196:199], v[38:41]
	v_mfma_f32_16x16x32_bf16 v[34:37], v[180:183], v[196:199], v[34:37]
	v_mfma_f32_16x16x32_bf16 v[22:25], v[172:175], v[204:207], v[22:25]
	v_mfma_f32_16x16x32_bf16 v[18:21], v[180:183], v[204:207], v[18:21]
	v_mfma_f32_16x16x32_bf16 v[6:9], v[172:175], v[212:215], v[6:9]
	v_mfma_f32_16x16x32_bf16 v[2:5], v[180:183], v[212:215], v[2:5]
	v_mfma_f32_16x16x32_bf16 v[54:57], v[176:179], v[192:195], v[54:57]
	v_mfma_f32_16x16x32_bf16 v[50:53], v[184:187], v[192:195], v[50:53]
	v_mfma_f32_16x16x32_bf16 v[38:41], v[176:179], v[200:203], v[38:41]
	v_mfma_f32_16x16x32_bf16 v[34:37], v[184:187], v[200:203], v[34:37]
	v_mfma_f32_16x16x32_bf16 v[22:25], v[176:179], v[208:211], v[22:25]
	v_mfma_f32_16x16x32_bf16 v[18:21], v[184:187], v[208:211], v[18:21]
	v_mfma_f32_16x16x32_bf16 v[6:9], v[176:179], v[216:219], v[6:9]
	v_mfma_f32_16x16x32_bf16 v[2:5], v[184:187], v[216:219], v[2:5]
	s_barrier
	s_add_i32 s52, 0, 0x18000
	s_add_i32 s53, 0, 0x1c000
	v_add_u32_e32 v168, s52, v151
	v_add_u32_e32 v184, s53, v151
	ds_read_b128 v[156:159], v168
	ds_read_b128 v[160:163], v168 offset:1024
	ds_read_b128 v[164:167], v168 offset:2048
	ds_read_b128 v[168:171], v168 offset:3072
	ds_read_b128 v[172:175], v184
	ds_read_b128 v[176:179], v184 offset:1024
	ds_read_b128 v[180:183], v184 offset:2048
	ds_read_b128 v[184:187], v184 offset:3072
	s_add_u32 s30, s30, 0x100000
	s_addc_u32 s31, s31, 0
	s_mov_b32 m0, s38
	v_lshl_add_u64 v[226:227], s[30:31], 0, v[136:137]
	ds_read_b128 v[188:191], v155 offset:32768
	ds_read_b128 v[192:195], v155 offset:33792
	ds_read_b128 v[196:199], v155 offset:34816
	ds_read_b128 v[200:203], v155 offset:35840
	ds_read_b128 v[204:207], v155 offset:36864
	ds_read_b128 v[208:211], v155 offset:37888
	ds_read_b128 v[212:215], v155 offset:38912
	ds_read_b128 v[216:219], v155 offset:39936
	global_load_lds_dwordx4 v[226:227], off
	v_lshl_add_u64 v[226:227], s[30:31], 0, v[132:133]
	s_mov_b32 m0, s39
	s_nop 0
	global_load_lds_dwordx4 v[226:227], off
	s_waitcnt vmcnt(8)
	s_waitcnt lgkmcnt(0)
	s_barrier
	v_mfma_f32_16x16x32_bf16 v[126:129], v[156:159], v[188:191], v[126:129]
	v_mfma_f32_16x16x32_bf16 v[122:125], v[164:167], v[188:191], v[122:125]
	v_mfma_f32_16x16x32_bf16 v[110:113], v[156:159], v[196:199], v[110:113]
	v_mfma_f32_16x16x32_bf16 v[106:109], v[164:167], v[196:199], v[106:109]
	v_mfma_f32_16x16x32_bf16 v[94:97], v[156:159], v[204:207], v[94:97]
	v_mfma_f32_16x16x32_bf16 v[90:93], v[164:167], v[204:207], v[90:93]
	v_mfma_f32_16x16x32_bf16 v[78:81], v[156:159], v[212:215], v[78:81]
	v_mfma_f32_16x16x32_bf16 v[74:77], v[164:167], v[212:215], v[74:77]
	v_mfma_f32_16x16x32_bf16 v[126:129], v[160:163], v[192:195], v[126:129]
	v_mfma_f32_16x16x32_bf16 v[122:125], v[168:171], v[192:195], v[122:125]
	v_mfma_f32_16x16x32_bf16 v[110:113], v[160:163], v[200:203], v[110:113]
	v_mfma_f32_16x16x32_bf16 v[106:109], v[168:171], v[200:203], v[106:109]
	v_mfma_f32_16x16x32_bf16 v[94:97], v[160:163], v[208:211], v[94:97]
	v_mfma_f32_16x16x32_bf16 v[90:93], v[168:171], v[208:211], v[90:93]
	v_mfma_f32_16x16x32_bf16 v[78:81], v[160:163], v[216:219], v[78:81]
	v_mfma_f32_16x16x32_bf16 v[74:77], v[168:171], v[216:219], v[74:77]
	v_mfma_f32_16x16x32_bf16 v[118:121], v[172:175], v[188:191], v[118:121]
	v_mfma_f32_16x16x32_bf16 v[114:117], v[180:183], v[188:191], v[114:117]
	v_mfma_f32_16x16x32_bf16 v[102:105], v[172:175], v[196:199], v[102:105]
	v_mfma_f32_16x16x32_bf16 v[98:101], v[180:183], v[196:199], v[98:101]
	v_mfma_f32_16x16x32_bf16 v[86:89], v[172:175], v[204:207], v[86:89]
	v_mfma_f32_16x16x32_bf16 v[82:85], v[180:183], v[204:207], v[82:85]
	v_mfma_f32_16x16x32_bf16 v[70:73], v[172:175], v[212:215], v[70:73]
	v_mfma_f32_16x16x32_bf16 v[66:69], v[180:183], v[212:215], v[66:69]
	v_mfma_f32_16x16x32_bf16 v[118:121], v[176:179], v[192:195], v[118:121]
	v_mfma_f32_16x16x32_bf16 v[114:117], v[184:187], v[192:195], v[114:117]
	v_mfma_f32_16x16x32_bf16 v[102:105], v[176:179], v[200:203], v[102:105]
	v_mfma_f32_16x16x32_bf16 v[98:101], v[184:187], v[200:203], v[98:101]
	v_mfma_f32_16x16x32_bf16 v[86:89], v[176:179], v[208:211], v[86:89]
	v_mfma_f32_16x16x32_bf16 v[82:85], v[184:187], v[208:211], v[82:85]
	v_mfma_f32_16x16x32_bf16 v[70:73], v[176:179], v[216:219], v[70:73]
	v_mfma_f32_16x16x32_bf16 v[66:69], v[184:187], v[216:219], v[66:69]
	s_barrier
	s_add_i32 s30, s52, s34
	v_lshl_add_u64 v[146:147], v[146:147], 0, s[12:13]
	s_mov_b32 m0, s30
	ds_read_b128 v[188:191], v155 offset:49152
	ds_read_b128 v[192:195], v155 offset:50176
	ds_read_b128 v[196:199], v155 offset:51200
	ds_read_b128 v[200:203], v155 offset:52224
	ds_read_b128 v[204:207], v155 offset:53248
	ds_read_b128 v[208:211], v155 offset:54272
	ds_read_b128 v[212:215], v155 offset:55296
	ds_read_b128 v[216:219], v155 offset:56320
	global_load_lds_dwordx4 v[146:147], off
	s_add_i32 m0, s30, 0x2000
	s_add_u32 s28, s28, 0x100080
	v_lshl_add_u64 v[146:147], v[220:221], 0, s[12:13]
	s_addc_u32 s29, s29, 0
	s_add_i32 s30, s53, s34
	global_load_lds_dwordx4 v[146:147], off
	v_lshl_add_u64 v[146:147], s[28:29], 0, v[134:135]
	s_mov_b32 m0, s30
	s_nop 0
	global_load_lds_dwordx4 v[146:147], off
	v_lshl_add_u64 v[146:147], s[28:29], 0, v[130:131]
	s_add_i32 m0, s30, 0x2000
	s_nop 0
	global_load_lds_dwordx4 v[146:147], off
	v_lshl_add_u64 v[146:147], v[222:223], 0, s[12:13]
	s_mov_b32 m0, s41
	s_nop 0
	global_load_lds_dwordx4 v[146:147], off
	v_lshl_add_u64 v[146:147], v[224:225], 0, s[12:13]
	s_mov_b32 m0, s42
	s_nop 0
	global_load_lds_dwordx4 v[146:147], off
	s_waitcnt vmcnt(8)
	s_waitcnt lgkmcnt(0)
	s_barrier
	v_mfma_f32_16x16x32_bf16 v[62:65], v[156:159], v[188:191], v[62:65]
	v_mfma_f32_16x16x32_bf16 v[58:61], v[164:167], v[188:191], v[58:61]
	v_mfma_f32_16x16x32_bf16 v[46:49], v[156:159], v[196:199], v[46:49]
	v_mfma_f32_16x16x32_bf16 v[42:45], v[164:167], v[196:199], v[42:45]
	v_mfma_f32_16x16x32_bf16 v[30:33], v[156:159], v[204:207], v[30:33]
	v_mfma_f32_16x16x32_bf16 v[26:29], v[164:167], v[204:207], v[26:29]
	v_mfma_f32_16x16x32_bf16 v[14:17], v[156:159], v[212:215], v[14:17]
	v_mfma_f32_16x16x32_bf16 v[10:13], v[164:167], v[212:215], v[10:13]
	v_mfma_f32_16x16x32_bf16 v[62:65], v[160:163], v[192:195], v[62:65]
	v_mfma_f32_16x16x32_bf16 v[58:61], v[168:171], v[192:195], v[58:61]
	v_mfma_f32_16x16x32_bf16 v[46:49], v[160:163], v[200:203], v[46:49]
	v_mfma_f32_16x16x32_bf16 v[42:45], v[168:171], v[200:203], v[42:45]
	v_mfma_f32_16x16x32_bf16 v[30:33], v[160:163], v[208:211], v[30:33]
	v_mfma_f32_16x16x32_bf16 v[26:29], v[168:171], v[208:211], v[26:29]
	v_mfma_f32_16x16x32_bf16 v[14:17], v[160:163], v[216:219], v[14:17]
	v_mfma_f32_16x16x32_bf16 v[10:13], v[168:171], v[216:219], v[10:13]
	v_mfma_f32_16x16x32_bf16 v[54:57], v[172:175], v[188:191], v[54:57]
	v_mfma_f32_16x16x32_bf16 v[50:53], v[180:183], v[188:191], v[50:53]
	v_mfma_f32_16x16x32_bf16 v[38:41], v[172:175], v[196:199], v[38:41]
	v_mfma_f32_16x16x32_bf16 v[34:37], v[180:183], v[196:199], v[34:37]
	v_mfma_f32_16x16x32_bf16 v[22:25], v[172:175], v[204:207], v[22:25]
	v_mfma_f32_16x16x32_bf16 v[18:21], v[180:183], v[204:207], v[18:21]
	v_mfma_f32_16x16x32_bf16 v[6:9], v[172:175], v[212:215], v[6:9]
	v_mfma_f32_16x16x32_bf16 v[2:5], v[180:183], v[212:215], v[2:5]
	v_mfma_f32_16x16x32_bf16 v[54:57], v[176:179], v[192:195], v[54:57]
	v_mfma_f32_16x16x32_bf16 v[50:53], v[184:187], v[192:195], v[50:53]
	v_mfma_f32_16x16x32_bf16 v[38:41], v[176:179], v[200:203], v[38:41]
	v_mfma_f32_16x16x32_bf16 v[34:37], v[184:187], v[200:203], v[34:37]
	v_mfma_f32_16x16x32_bf16 v[22:25], v[176:179], v[208:211], v[22:25]
	v_mfma_f32_16x16x32_bf16 v[18:21], v[184:187], v[208:211], v[18:21]
	v_mfma_f32_16x16x32_bf16 v[6:9], v[176:179], v[216:219], v[6:9]
	v_mfma_f32_16x16x32_bf16 v[2:5], v[184:187], v[216:219], v[2:5]
	s_barrier
	s_add_i32 s51, s51, 2
	s_add_u32 s26, s26, 0x100
	s_addc_u32 s27, s27, 0
	s_add_u32 s49, s49, 0x100
	s_addc_u32 s50, s50, 0
	s_cmp_gt_u32 s51, 61
	s_cbranch_scc0 .LBB0_860
	s_and_b64 vcc, exec, s[14:15]
	s_cbranch_vccz .LBB0_863
	s_barrier

.LBB0_955:
	ds_read_b128 v[130:133], v199
	ds_read_b128 v[134:137], v199 offset:1024
	ds_read_b128 v[138:141], v199 offset:2048
	ds_read_b128 v[142:145], v199 offset:3072
	ds_read_b128 v[146:149], v200
	ds_read_b128 v[166:169], v200 offset:1024
	ds_read_b128 v[170:173], v200 offset:2048
	ds_read_b128 v[174:177], v200 offset:3072
	s_add_u32 s26, s24, 0xffd50080
	s_addc_u32 s27, s25, -1
	s_cmpk_eq_i32 s50, 0xa8
	s_cselect_b32 s29, s9, s27
	s_cselect_b32 s28, s8, s26
	s_cselect_b32 s27, s23, s49
	s_cselect_b32 s26, s22, s48
	v_lshl_add_u64 v[194:195], s[24:25], 0, v[158:159]
	s_add_i32 m0, s35, 0xc000
	ds_read_b128 v[178:181], v201
	ds_read_b128 v[182:185], v201 offset:1024
	ds_read_b128 v[186:189], v201 offset:2048
	ds_read_b128 v[190:193], v201 offset:3072
	ds_read_b128 v[202:205], v201 offset:4096
	ds_read_b128 v[206:209], v201 offset:5120
	ds_read_b128 v[210:213], v201 offset:6144
	ds_read_b128 v[214:217], v201 offset:7168
	global_load_lds_dwordx4 v[194:195], off
	v_lshl_add_u64 v[194:195], s[24:25], 0, v[160:161]
	s_add_i32 m0, s35, 0xe000
	s_nop 0
	global_load_lds_dwordx4 v[194:195], off
	s_waitcnt vmcnt(8)
	s_waitcnt lgkmcnt(0)
	s_barrier
	v_mfma_f32_16x16x32_bf16 v[126:129], v[130:133], v[178:181], v[126:129]
	v_mfma_f32_16x16x32_bf16 v[122:125], v[138:141], v[178:181], v[122:125]
	v_mfma_f32_16x16x32_bf16 v[118:121], v[130:133], v[186:189], v[118:121]
	v_mfma_f32_16x16x32_bf16 v[114:117], v[138:141], v[186:189], v[114:117]
	v_mfma_f32_16x16x32_bf16 v[110:113], v[130:133], v[202:205], v[110:113]
	v_mfma_f32_16x16x32_bf16 v[106:109], v[138:141], v[202:205], v[106:109]
	v_mfma_f32_16x16x32_bf16 v[102:105], v[130:133], v[210:213], v[102:105]
	v_mfma_f32_16x16x32_bf16 v[98:101], v[138:141], v[210:213], v[98:101]
	v_mfma_f32_16x16x32_bf16 v[126:129], v[134:137], v[182:185], v[126:129]
	v_mfma_f32_16x16x32_bf16 v[122:125], v[142:145], v[182:185], v[122:125]
	v_mfma_f32_16x16x32_bf16 v[118:121], v[134:137], v[190:193], v[118:121]
	v_mfma_f32_16x16x32_bf16 v[114:117], v[142:145], v[190:193], v[114:117]
	v_mfma_f32_16x16x32_bf16 v[110:113], v[134:137], v[206:209], v[110:113]
	v_mfma_f32_16x16x32_bf16 v[106:109], v[142:145], v[206:209], v[106:109]
	v_mfma_f32_16x16x32_bf16 v[102:105], v[134:137], v[214:217], v[102:105]
	v_mfma_f32_16x16x32_bf16 v[98:101], v[142:145], v[214:217], v[98:101]
	v_mfma_f32_16x16x32_bf16 v[62:65], v[146:149], v[178:181], v[62:65]
	v_mfma_f32_16x16x32_bf16 v[58:61], v[170:173], v[178:181], v[58:61]
	v_mfma_f32_16x16x32_bf16 v[54:57], v[146:149], v[186:189], v[54:57]
	v_mfma_f32_16x16x32_bf16 v[50:53], v[170:173], v[186:189], v[50:53]
	v_mfma_f32_16x16x32_bf16 v[46:49], v[146:149], v[202:205], v[46:49]
	v_mfma_f32_16x16x32_bf16 v[42:45], v[170:173], v[202:205], v[42:45]
	v_mfma_f32_16x16x32_bf16 v[38:41], v[146:149], v[210:213], v[38:41]
	v_mfma_f32_16x16x32_bf16 v[34:37], v[170:173], v[210:213], v[34:37]
	v_mfma_f32_16x16x32_bf16 v[62:65], v[166:169], v[182:185], v[62:65]
	v_mfma_f32_16x16x32_bf16 v[58:61], v[174:177], v[182:185], v[58:61]
	v_mfma_f32_16x16x32_bf16 v[54:57], v[166:169], v[190:193], v[54:57]
	v_mfma_f32_16x16x32_bf16 v[50:53], v[174:177], v[190:193], v[50:53]
	v_mfma_f32_16x16x32_bf16 v[46:49], v[166:169], v[206:209], v[46:49]
	v_mfma_f32_16x16x32_bf16 v[42:45], v[174:177], v[206:209], v[42:45]
	v_mfma_f32_16x16x32_bf16 v[38:41], v[166:169], v[214:217], v[38:41]
	v_mfma_f32_16x16x32_bf16 v[34:37], v[174:177], v[214:217], v[34:37]
	s_barrier
	s_add_i32 s51, s43, s34
	v_lshl_add_u64 v[194:195], s[26:27], 0, v[152:153]
	s_mov_b32 m0, s51
	ds_read_b128 v[178:181], v201 offset:16384
	ds_read_b128 v[182:185], v201 offset:17408
	ds_read_b128 v[186:189], v201 offset:18432
	ds_read_b128 v[190:193], v201 offset:19456
	ds_read_b128 v[202:205], v201 offset:20480
	ds_read_b128 v[206:209], v201 offset:21504
	ds_read_b128 v[210:213], v201 offset:22528
	ds_read_b128 v[214:217], v201 offset:23552
	global_load_lds_dwordx4 v[194:195], off
	s_add_i32 m0, s51, 0x2000
	s_add_u32 s52, s26, 0x2b0000
	v_lshl_add_u64 v[218:219], s[26:27], 0, v[156:157]
	s_addc_u32 s53, s27, 0
	s_add_i32 s51, s44, s34
	global_load_lds_dwordx4 v[218:219], off
	v_lshl_add_u64 v[220:221], s[52:53], 0, v[152:153]
	s_mov_b32 m0, s51
	v_lshl_add_u64 v[222:223], s[28:29], 0, v[154:155]
	global_load_lds_dwordx4 v[220:221], off
	v_lshl_add_u64 v[220:221], s[52:53], 0, v[156:157]
	s_add_i32 m0, s51, 0x2000
	s_nop 0
	global_load_lds_dwordx4 v[220:221], off
	v_lshl_add_u64 v[220:221], s[28:29], 0, v[150:151]
	s_mov_b32 m0, s35
	s_nop 0
	global_load_lds_dwordx4 v[220:221], off
	s_mov_b32 m0, s36
	s_nop 0
	global_load_lds_dwordx4 v[222:223], off
	s_waitcnt vmcnt(8)
	s_waitcnt lgkmcnt(0)
	s_barrier
	v_mfma_f32_16x16x32_bf16 v[94:97], v[130:133], v[178:181], v[94:97]
	v_mfma_f32_16x16x32_bf16 v[90:93], v[138:141], v[178:181], v[90:93]
	v_mfma_f32_16x16x32_bf16 v[86:89], v[130:133], v[186:189], v[86:89]
	v_mfma_f32_16x16x32_bf16 v[82:85], v[138:141], v[186:189], v[82:85]
	v_mfma_f32_16x16x32_bf16 v[78:81], v[130:133], v[202:205], v[78:81]
	v_mfma_f32_16x16x32_bf16 v[74:77], v[138:141], v[202:205], v[74:77]
	v_mfma_f32_16x16x32_bf16 v[70:73], v[130:133], v[210:213], v[70:73]
	v_mfma_f32_16x16x32_bf16 v[66:69], v[138:141], v[210:213], v[66:69]
	v_mfma_f32_16x16x32_bf16 v[94:97], v[134:137], v[182:185], v[94:97]
	v_mfma_f32_16x16x32_bf16 v[90:93], v[142:145], v[182:185], v[90:93]
	v_mfma_f32_16x16x32_bf16 v[86:89], v[134:137], v[190:193], v[86:89]
	v_mfma_f32_16x16x32_bf16 v[82:85], v[142:145], v[190:193], v[82:85]
	v_mfma_f32_16x16x32_bf16 v[78:81], v[134:137], v[206:209], v[78:81]
	v_mfma_f32_16x16x32_bf16 v[74:77], v[142:145], v[206:209], v[74:77]
	v_mfma_f32_16x16x32_bf16 v[70:73], v[134:137], v[214:217], v[70:73]
	v_mfma_f32_16x16x32_bf16 v[66:69], v[142:145], v[214:217], v[66:69]
	v_mfma_f32_16x16x32_bf16 v[30:33], v[146:149], v[178:181], v[30:33]
	v_mfma_f32_16x16x32_bf16 v[26:29], v[170:173], v[178:181], v[26:29]
	v_mfma_f32_16x16x32_bf16 v[22:25], v[146:149], v[186:189], v[22:25]
	v_mfma_f32_16x16x32_bf16 v[18:21], v[170:173], v[186:189], v[18:21]
	v_mfma_f32_16x16x32_bf16 v[14:17], v[146:149], v[202:205], v[14:17]
	v_mfma_f32_16x16x32_bf16 v[10:13], v[170:173], v[202:205], v[10:13]
	v_mfma_f32_16x16x32_bf16 v[6:9], v[146:149], v[210:213], v[6:9]
	v_mfma_f32_16x16x32_bf16 v[2:5], v[170:173], v[210:213], v[2:5]
	v_mfma_f32_16x16x32_bf16 v[30:33], v[166:169], v[182:185], v[30:33]
	v_mfma_f32_16x16x32_bf16 v[26:29], v[174:177], v[182:185], v[26:29]
	v_mfma_f32_16x16x32_bf16 v[22:25], v[166:169], v[190:193], v[22:25]
	v_mfma_f32_16x16x32_bf16 v[18:21], v[174:177], v[190:193], v[18:21]
	v_mfma_f32_16x16x32_bf16 v[14:17], v[166:169], v[206:209], v[14:17]
	v_mfma_f32_16x16x32_bf16 v[10:13], v[174:177], v[206:209], v[10:13]
	v_mfma_f32_16x16x32_bf16 v[6:9], v[166:169], v[214:217], v[6:9]
	v_mfma_f32_16x16x32_bf16 v[2:5], v[174:177], v[214:217], v[2:5]
	s_barrier
	s_add_i32 s51, 0, 0x18000
	s_add_i32 s52, 0, 0x1c000
	v_add_u32_e32 v142, s51, v197
	v_add_u32_e32 v174, s52, v197
	ds_read_b128 v[130:133], v142
	ds_read_b128 v[134:137], v142 offset:1024
	ds_read_b128 v[138:141], v142 offset:2048
	ds_read_b128 v[142:145], v142 offset:3072
	ds_read_b128 v[146:149], v174
	ds_read_b128 v[166:169], v174 offset:1024
	ds_read_b128 v[170:173], v174 offset:2048
	ds_read_b128 v[174:177], v174 offset:3072
	s_add_u32 s28, s28, 0x2b0000
	s_addc_u32 s29, s29, 0
	s_mov_b32 m0, s37
	v_lshl_add_u64 v[224:225], s[28:29], 0, v[150:151]
	ds_read_b128 v[178:181], v201 offset:32768
	ds_read_b128 v[182:185], v201 offset:33792
	ds_read_b128 v[186:189], v201 offset:34816
	ds_read_b128 v[190:193], v201 offset:35840
	ds_read_b128 v[202:205], v201 offset:36864
	ds_read_b128 v[206:209], v201 offset:37888
	ds_read_b128 v[210:213], v201 offset:38912
	ds_read_b128 v[214:217], v201 offset:39936
	global_load_lds_dwordx4 v[224:225], off
	v_lshl_add_u64 v[224:225], s[28:29], 0, v[154:155]
	s_mov_b32 m0, s38
	s_nop 0
	global_load_lds_dwordx4 v[224:225], off
	s_waitcnt vmcnt(8)
	s_waitcnt lgkmcnt(0)
	s_barrier
	v_mfma_f32_16x16x32_bf16 v[126:129], v[130:133], v[178:181], v[126:129]
	v_mfma_f32_16x16x32_bf16 v[122:125], v[138:141], v[178:181], v[122:125]
	v_mfma_f32_16x16x32_bf16 v[118:121], v[130:133], v[186:189], v[118:121]
	v_mfma_f32_16x16x32_bf16 v[114:117], v[138:141], v[186:189], v[114:117]
	v_mfma_f32_16x16x32_bf16 v[110:113], v[130:133], v[202:205], v[110:113]
	v_mfma_f32_16x16x32_bf16 v[106:109], v[138:141], v[202:205], v[106:109]
	v_mfma_f32_16x16x32_bf16 v[102:105], v[130:133], v[210:213], v[102:105]
	v_mfma_f32_16x16x32_bf16 v[98:101], v[138:141], v[210:213], v[98:101]
	v_mfma_f32_16x16x32_bf16 v[126:129], v[134:137], v[182:185], v[126:129]
	v_mfma_f32_16x16x32_bf16 v[122:125], v[142:145], v[182:185], v[122:125]
	v_mfma_f32_16x16x32_bf16 v[118:121], v[134:137], v[190:193], v[118:121]
	v_mfma_f32_16x16x32_bf16 v[114:117], v[142:145], v[190:193], v[114:117]
	v_mfma_f32_16x16x32_bf16 v[110:113], v[134:137], v[206:209], v[110:113]
	v_mfma_f32_16x16x32_bf16 v[106:109], v[142:145], v[206:209], v[106:109]
	v_mfma_f32_16x16x32_bf16 v[102:105], v[134:137], v[214:217], v[102:105]
	v_mfma_f32_16x16x32_bf16 v[98:101], v[142:145], v[214:217], v[98:101]
	v_mfma_f32_16x16x32_bf16 v[62:65], v[146:149], v[178:181], v[62:65]
	v_mfma_f32_16x16x32_bf16 v[58:61], v[170:173], v[178:181], v[58:61]
	v_mfma_f32_16x16x32_bf16 v[54:57], v[146:149], v[186:189], v[54:57]
	v_mfma_f32_16x16x32_bf16 v[50:53], v[170:173], v[186:189], v[50:53]
	v_mfma_f32_16x16x32_bf16 v[46:49], v[146:149], v[202:205], v[46:49]
	v_mfma_f32_16x16x32_bf16 v[42:45], v[170:173], v[202:205], v[42:45]
	v_mfma_f32_16x16x32_bf16 v[38:41], v[146:149], v[210:213], v[38:41]
	v_mfma_f32_16x16x32_bf16 v[34:37], v[170:173], v[210:213], v[34:37]
	v_mfma_f32_16x16x32_bf16 v[62:65], v[166:169], v[182:185], v[62:65]
	v_mfma_f32_16x16x32_bf16 v[58:61], v[174:177], v[182:185], v[58:61]
	v_mfma_f32_16x16x32_bf16 v[54:57], v[166:169], v[190:193], v[54:57]
	v_mfma_f32_16x16x32_bf16 v[50:53], v[174:177], v[190:193], v[50:53]
	v_mfma_f32_16x16x32_bf16 v[46:49], v[166:169], v[206:209], v[46:49]
	v_mfma_f32_16x16x32_bf16 v[42:45], v[174:177], v[206:209], v[42:45]
	v_mfma_f32_16x16x32_bf16 v[38:41], v[166:169], v[214:217], v[38:41]
	v_mfma_f32_16x16x32_bf16 v[34:37], v[174:177], v[214:217], v[34:37]
	s_barrier
	s_add_i32 s28, s51, s34
	v_lshl_add_u64 v[194:195], v[194:195], 0, s[16:17]
	s_mov_b32 m0, s28
	ds_read_b128 v[178:181], v201 offset:49152
	ds_read_b128 v[182:185], v201 offset:50176
	ds_read_b128 v[186:189], v201 offset:51200
	ds_read_b128 v[190:193], v201 offset:52224
	ds_read_b128 v[202:205], v201 offset:53248
	ds_read_b128 v[206:209], v201 offset:54272
	ds_read_b128 v[210:213], v201 offset:55296
	ds_read_b128 v[214:217], v201 offset:56320
	global_load_lds_dwordx4 v[194:195], off
	s_add_i32 m0, s28, 0x2000
	s_add_u32 s26, s26, 0x2b0080
	v_lshl_add_u64 v[194:195], v[218:219], 0, s[16:17]
	s_addc_u32 s27, s27, 0
	s_add_i32 s28, s52, s34
	global_load_lds_dwordx4 v[194:195], off
	v_lshl_add_u64 v[194:195], s[26:27], 0, v[152:153]
	s_mov_b32 m0, s28
	s_nop 0
	global_load_lds_dwordx4 v[194:195], off
	v_lshl_add_u64 v[194:195], s[26:27], 0, v[156:157]
	s_add_i32 m0, s28, 0x2000
	s_nop 0
	global_load_lds_dwordx4 v[194:195], off
	v_lshl_add_u64 v[194:195], v[220:221], 0, s[16:17]
	s_mov_b32 m0, s40
	s_nop 0
	global_load_lds_dwordx4 v[194:195], off
	v_lshl_add_u64 v[194:195], v[222:223], 0, s[16:17]
	s_mov_b32 m0, s41
	s_nop 0
	global_load_lds_dwordx4 v[194:195], off
	s_waitcnt vmcnt(8)
	s_waitcnt lgkmcnt(0)
	s_barrier
	v_mfma_f32_16x16x32_bf16 v[94:97], v[130:133], v[178:181], v[94:97]
	v_mfma_f32_16x16x32_bf16 v[90:93], v[138:141], v[178:181], v[90:93]
	v_mfma_f32_16x16x32_bf16 v[86:89], v[130:133], v[186:189], v[86:89]
	v_mfma_f32_16x16x32_bf16 v[82:85], v[138:141], v[186:189], v[82:85]
	v_mfma_f32_16x16x32_bf16 v[78:81], v[130:133], v[202:205], v[78:81]
	v_mfma_f32_16x16x32_bf16 v[74:77], v[138:141], v[202:205], v[74:77]
	v_mfma_f32_16x16x32_bf16 v[70:73], v[130:133], v[210:213], v[70:73]
	v_mfma_f32_16x16x32_bf16 v[66:69], v[138:141], v[210:213], v[66:69]
	v_mfma_f32_16x16x32_bf16 v[94:97], v[134:137], v[182:185], v[94:97]
	v_mfma_f32_16x16x32_bf16 v[90:93], v[142:145], v[182:185], v[90:93]
	v_mfma_f32_16x16x32_bf16 v[86:89], v[134:137], v[190:193], v[86:89]
	v_mfma_f32_16x16x32_bf16 v[82:85], v[142:145], v[190:193], v[82:85]
	v_mfma_f32_16x16x32_bf16 v[78:81], v[134:137], v[206:209], v[78:81]
	v_mfma_f32_16x16x32_bf16 v[74:77], v[142:145], v[206:209], v[74:77]
	v_mfma_f32_16x16x32_bf16 v[70:73], v[134:137], v[214:217], v[70:73]
	v_mfma_f32_16x16x32_bf16 v[66:69], v[142:145], v[214:217], v[66:69]
	v_mfma_f32_16x16x32_bf16 v[30:33], v[146:149], v[178:181], v[30:33]
	v_mfma_f32_16x16x32_bf16 v[26:29], v[170:173], v[178:181], v[26:29]
	v_mfma_f32_16x16x32_bf16 v[22:25], v[146:149], v[186:189], v[22:25]
	v_mfma_f32_16x16x32_bf16 v[18:21], v[170:173], v[186:189], v[18:21]
	v_mfma_f32_16x16x32_bf16 v[14:17], v[146:149], v[202:205], v[14:17]
	v_mfma_f32_16x16x32_bf16 v[10:13], v[170:173], v[202:205], v[10:13]
	v_mfma_f32_16x16x32_bf16 v[6:9], v[146:149], v[210:213], v[6:9]
	v_mfma_f32_16x16x32_bf16 v[2:5], v[170:173], v[210:213], v[2:5]
	v_mfma_f32_16x16x32_bf16 v[30:33], v[166:169], v[182:185], v[30:33]
	v_mfma_f32_16x16x32_bf16 v[26:29], v[174:177], v[182:185], v[26:29]
	v_mfma_f32_16x16x32_bf16 v[22:25], v[166:169], v[190:193], v[22:25]
	v_mfma_f32_16x16x32_bf16 v[18:21], v[174:177], v[190:193], v[18:21]
	v_mfma_f32_16x16x32_bf16 v[14:17], v[166:169], v[206:209], v[14:17]
	v_mfma_f32_16x16x32_bf16 v[10:13], v[174:177], v[206:209], v[10:13]
	v_mfma_f32_16x16x32_bf16 v[6:9], v[166:169], v[214:217], v[6:9]
	v_mfma_f32_16x16x32_bf16 v[2:5], v[174:177], v[214:217], v[2:5]
	s_barrier
	s_add_i32 s50, s50, 2
	s_add_u32 s24, s24, 0x100
	s_addc_u32 s25, s25, 0
	s_add_u32 s48, s48, 0x100
	s_addc_u32 s49, s49, 0
	s_cmpk_gt_u32 s50, 0xa9
	s_cbranch_scc0 .LBB0_955
	s_and_b64 vcc, exec, s[18:19]
	s_cbranch_vccz .LBB0_958
	s_barrier

.LBB0_1087:
	ds_read_b128 v[148:151], v156
	ds_read_b128 v[160:163], v156 offset:1024
	ds_read_b128 v[164:167], v156 offset:2048
	ds_read_b128 v[168:171], v156 offset:3072
	ds_read_b128 v[172:175], v157
	ds_read_b128 v[176:179], v157 offset:1024
	ds_read_b128 v[180:183], v157 offset:2048
	ds_read_b128 v[184:187], v157 offset:3072
	s_add_u32 s28, s26, 0xfff00080
	s_addc_u32 s29, s27, -1
	s_cmp_eq_u32 s51, 60
	s_cselect_b32 s31, s19, s29
	s_cselect_b32 s30, s47, s28
	s_cselect_b32 s29, s17, s50
	s_cselect_b32 s28, s48, s49
	v_lshl_add_u64 v[220:221], s[26:27], 0, v[138:139]
	s_add_i32 m0, s25, 0xc000
	ds_read_b128 v[188:191], v158
	ds_read_b128 v[192:195], v158 offset:1024
	ds_read_b128 v[196:199], v158 offset:2048
	ds_read_b128 v[200:203], v158 offset:3072
	ds_read_b128 v[204:207], v158 offset:4096
	ds_read_b128 v[208:211], v158 offset:5120
	ds_read_b128 v[212:215], v158 offset:6144
	ds_read_b128 v[216:219], v158 offset:7168
	global_load_lds_dwordx4 v[220:221], off
	v_lshl_add_u64 v[220:221], s[26:27], 0, v[140:141]
	s_add_i32 m0, s25, 0xe000
	s_nop 0
	global_load_lds_dwordx4 v[220:221], off
	s_waitcnt vmcnt(8)
	s_waitcnt lgkmcnt(0)
	s_barrier
	v_mfma_f32_16x16x32_bf16 v[126:129], v[148:151], v[188:191], v[126:129]
	v_mfma_f32_16x16x32_bf16 v[122:125], v[164:167], v[188:191], v[122:125]
	v_mfma_f32_16x16x32_bf16 v[114:117], v[148:151], v[196:199], v[114:117]
	v_mfma_f32_16x16x32_bf16 v[106:109], v[164:167], v[196:199], v[106:109]
	v_mfma_f32_16x16x32_bf16 v[98:101], v[148:151], v[204:207], v[98:101]
	v_mfma_f32_16x16x32_bf16 v[90:93], v[164:167], v[204:207], v[90:93]
	v_mfma_f32_16x16x32_bf16 v[82:85], v[148:151], v[212:215], v[82:85]
	v_mfma_f32_16x16x32_bf16 v[74:77], v[164:167], v[212:215], v[74:77]
	v_mfma_f32_16x16x32_bf16 v[126:129], v[160:163], v[192:195], v[126:129]
	v_mfma_f32_16x16x32_bf16 v[122:125], v[168:171], v[192:195], v[122:125]
	v_mfma_f32_16x16x32_bf16 v[114:117], v[160:163], v[200:203], v[114:117]
	v_mfma_f32_16x16x32_bf16 v[106:109], v[168:171], v[200:203], v[106:109]
	v_mfma_f32_16x16x32_bf16 v[98:101], v[160:163], v[208:211], v[98:101]
	v_mfma_f32_16x16x32_bf16 v[90:93], v[168:171], v[208:211], v[90:93]
	v_mfma_f32_16x16x32_bf16 v[82:85], v[160:163], v[216:219], v[82:85]
	v_mfma_f32_16x16x32_bf16 v[74:77], v[168:171], v[216:219], v[74:77]
	v_mfma_f32_16x16x32_bf16 v[118:121], v[172:175], v[188:191], v[118:121]
	v_mfma_f32_16x16x32_bf16 v[110:113], v[180:183], v[188:191], v[110:113]
	v_mfma_f32_16x16x32_bf16 v[102:105], v[172:175], v[196:199], v[102:105]
	v_mfma_f32_16x16x32_bf16 v[94:97], v[180:183], v[196:199], v[94:97]
	v_mfma_f32_16x16x32_bf16 v[86:89], v[172:175], v[204:207], v[86:89]
	v_mfma_f32_16x16x32_bf16 v[78:81], v[180:183], v[204:207], v[78:81]
	v_mfma_f32_16x16x32_bf16 v[70:73], v[172:175], v[212:215], v[70:73]
	v_mfma_f32_16x16x32_bf16 v[66:69], v[180:183], v[212:215], v[66:69]
	v_mfma_f32_16x16x32_bf16 v[118:121], v[176:179], v[192:195], v[118:121]
	v_mfma_f32_16x16x32_bf16 v[110:113], v[184:187], v[192:195], v[110:113]
	v_mfma_f32_16x16x32_bf16 v[102:105], v[176:179], v[200:203], v[102:105]
	v_mfma_f32_16x16x32_bf16 v[94:97], v[184:187], v[200:203], v[94:97]
	v_mfma_f32_16x16x32_bf16 v[86:89], v[176:179], v[208:211], v[86:89]
	v_mfma_f32_16x16x32_bf16 v[78:81], v[184:187], v[208:211], v[78:81]
	v_mfma_f32_16x16x32_bf16 v[70:73], v[176:179], v[216:219], v[70:73]
	v_mfma_f32_16x16x32_bf16 v[66:69], v[184:187], v[216:219], v[66:69]
	s_barrier
	s_add_i32 s52, s44, s34
	v_lshl_add_u64 v[220:221], s[28:29], 0, v[134:135]
	s_mov_b32 m0, s52
	ds_read_b128 v[188:191], v158 offset:16384
	ds_read_b128 v[192:195], v158 offset:17408
	ds_read_b128 v[196:199], v158 offset:18432
	ds_read_b128 v[200:203], v158 offset:19456
	ds_read_b128 v[204:207], v158 offset:20480
	ds_read_b128 v[208:211], v158 offset:21504
	ds_read_b128 v[212:215], v158 offset:22528
	ds_read_b128 v[216:219], v158 offset:23552
	global_load_lds_dwordx4 v[220:221], off
	s_add_i32 m0, s52, 0x2000
	s_add_u32 s52, s28, 0x100000
	v_lshl_add_u64 v[222:223], s[28:29], 0, v[130:131]
	s_addc_u32 s53, s29, 0
	s_add_i32 s54, s45, s34
	global_load_lds_dwordx4 v[222:223], off
	v_lshl_add_u64 v[224:225], s[52:53], 0, v[134:135]
	s_mov_b32 m0, s54
	v_lshl_add_u64 v[226:227], s[30:31], 0, v[132:133]
	global_load_lds_dwordx4 v[224:225], off
	v_lshl_add_u64 v[224:225], s[52:53], 0, v[130:131]
	s_add_i32 m0, s54, 0x2000
	s_nop 0
	global_load_lds_dwordx4 v[224:225], off
	v_lshl_add_u64 v[224:225], s[30:31], 0, v[136:137]
	s_mov_b32 m0, s25
	s_nop 0
	global_load_lds_dwordx4 v[224:225], off
	s_mov_b32 m0, s37
	s_nop 0
	global_load_lds_dwordx4 v[226:227], off
	s_waitcnt vmcnt(8)
	s_waitcnt lgkmcnt(0)
	s_barrier
	v_mfma_f32_16x16x32_bf16 v[62:65], v[148:151], v[188:191], v[62:65]
	v_mfma_f32_16x16x32_bf16 v[58:61], v[164:167], v[188:191], v[58:61]
	v_mfma_f32_16x16x32_bf16 v[50:53], v[148:151], v[196:199], v[50:53]
	v_mfma_f32_16x16x32_bf16 v[42:45], v[164:167], v[196:199], v[42:45]
	v_mfma_f32_16x16x32_bf16 v[34:37], v[148:151], v[204:207], v[34:37]
	v_mfma_f32_16x16x32_bf16 v[26:29], v[164:167], v[204:207], v[26:29]
	v_mfma_f32_16x16x32_bf16 v[18:21], v[148:151], v[212:215], v[18:21]
	v_mfma_f32_16x16x32_bf16 v[10:13], v[164:167], v[212:215], v[10:13]
	v_mfma_f32_16x16x32_bf16 v[62:65], v[160:163], v[192:195], v[62:65]
	v_mfma_f32_16x16x32_bf16 v[58:61], v[168:171], v[192:195], v[58:61]
	v_mfma_f32_16x16x32_bf16 v[50:53], v[160:163], v[200:203], v[50:53]
	v_mfma_f32_16x16x32_bf16 v[42:45], v[168:171], v[200:203], v[42:45]
	v_mfma_f32_16x16x32_bf16 v[34:37], v[160:163], v[208:211], v[34:37]
	v_mfma_f32_16x16x32_bf16 v[26:29], v[168:171], v[208:211], v[26:29]
	v_mfma_f32_16x16x32_bf16 v[18:21], v[160:163], v[216:219], v[18:21]
	v_mfma_f32_16x16x32_bf16 v[10:13], v[168:171], v[216:219], v[10:13]
	v_mfma_f32_16x16x32_bf16 v[54:57], v[172:175], v[188:191], v[54:57]
	v_mfma_f32_16x16x32_bf16 v[46:49], v[180:183], v[188:191], v[46:49]
	v_mfma_f32_16x16x32_bf16 v[38:41], v[172:175], v[196:199], v[38:41]
	v_mfma_f32_16x16x32_bf16 v[30:33], v[180:183], v[196:199], v[30:33]
	v_mfma_f32_16x16x32_bf16 v[22:25], v[172:175], v[204:207], v[22:25]
	v_mfma_f32_16x16x32_bf16 v[14:17], v[180:183], v[204:207], v[14:17]
	v_mfma_f32_16x16x32_bf16 v[6:9], v[172:175], v[212:215], v[6:9]
	v_mfma_f32_16x16x32_bf16 v[2:5], v[180:183], v[212:215], v[2:5]
	v_mfma_f32_16x16x32_bf16 v[54:57], v[176:179], v[192:195], v[54:57]
	v_mfma_f32_16x16x32_bf16 v[46:49], v[184:187], v[192:195], v[46:49]
	v_mfma_f32_16x16x32_bf16 v[38:41], v[176:179], v[200:203], v[38:41]
	v_mfma_f32_16x16x32_bf16 v[30:33], v[184:187], v[200:203], v[30:33]
	v_mfma_f32_16x16x32_bf16 v[22:25], v[176:179], v[208:211], v[22:25]
	v_mfma_f32_16x16x32_bf16 v[14:17], v[184:187], v[208:211], v[14:17]
	v_mfma_f32_16x16x32_bf16 v[6:9], v[176:179], v[216:219], v[6:9]
	v_mfma_f32_16x16x32_bf16 v[2:5], v[184:187], v[216:219], v[2:5]
	s_barrier
	s_add_i32 s52, 0, 0x18000
	v_add_u32_e32 v146, s52, v154
	s_add_i32 s53, 0, 0x1c000
	ds_read_b128 v[148:151], v146
	ds_read_b128 v[160:163], v146 offset:1024
	ds_read_b128 v[164:167], v146 offset:2048
	ds_read_b128 v[168:171], v146 offset:3072
	v_add_u32_e32 v146, s53, v154
	ds_read_b128 v[172:175], v146
	ds_read_b128 v[176:179], v146 offset:1024
	ds_read_b128 v[180:183], v146 offset:2048
	ds_read_b128 v[184:187], v146 offset:3072
	s_add_u32 s30, s30, 0x100000
	s_addc_u32 s31, s31, 0
	s_mov_b32 m0, s38
	v_lshl_add_u64 v[228:229], s[30:31], 0, v[136:137]
	ds_read_b128 v[188:191], v158 offset:32768
	ds_read_b128 v[192:195], v158 offset:33792
	ds_read_b128 v[196:199], v158 offset:34816
	ds_read_b128 v[200:203], v158 offset:35840
	ds_read_b128 v[204:207], v158 offset:36864
	ds_read_b128 v[208:211], v158 offset:37888
	ds_read_b128 v[212:215], v158 offset:38912
	ds_read_b128 v[216:219], v158 offset:39936
	global_load_lds_dwordx4 v[228:229], off
	v_lshl_add_u64 v[228:229], s[30:31], 0, v[132:133]
	s_mov_b32 m0, s39
	s_nop 0
	global_load_lds_dwordx4 v[228:229], off
	s_waitcnt vmcnt(8)
	s_waitcnt lgkmcnt(0)
	s_barrier
	v_mfma_f32_16x16x32_bf16 v[126:129], v[148:151], v[188:191], v[126:129]
	v_mfma_f32_16x16x32_bf16 v[122:125], v[164:167], v[188:191], v[122:125]
	v_mfma_f32_16x16x32_bf16 v[114:117], v[148:151], v[196:199], v[114:117]
	v_mfma_f32_16x16x32_bf16 v[106:109], v[164:167], v[196:199], v[106:109]
	v_mfma_f32_16x16x32_bf16 v[98:101], v[148:151], v[204:207], v[98:101]
	v_mfma_f32_16x16x32_bf16 v[90:93], v[164:167], v[204:207], v[90:93]
	v_mfma_f32_16x16x32_bf16 v[82:85], v[148:151], v[212:215], v[82:85]
	v_mfma_f32_16x16x32_bf16 v[74:77], v[164:167], v[212:215], v[74:77]
	v_mfma_f32_16x16x32_bf16 v[126:129], v[160:163], v[192:195], v[126:129]
	v_mfma_f32_16x16x32_bf16 v[122:125], v[168:171], v[192:195], v[122:125]
	v_mfma_f32_16x16x32_bf16 v[114:117], v[160:163], v[200:203], v[114:117]
	v_mfma_f32_16x16x32_bf16 v[106:109], v[168:171], v[200:203], v[106:109]
	v_mfma_f32_16x16x32_bf16 v[98:101], v[160:163], v[208:211], v[98:101]
	v_mfma_f32_16x16x32_bf16 v[90:93], v[168:171], v[208:211], v[90:93]
	v_mfma_f32_16x16x32_bf16 v[82:85], v[160:163], v[216:219], v[82:85]
	v_mfma_f32_16x16x32_bf16 v[74:77], v[168:171], v[216:219], v[74:77]
	v_mfma_f32_16x16x32_bf16 v[118:121], v[172:175], v[188:191], v[118:121]
	v_mfma_f32_16x16x32_bf16 v[110:113], v[180:183], v[188:191], v[110:113]
	v_mfma_f32_16x16x32_bf16 v[102:105], v[172:175], v[196:199], v[102:105]
	v_mfma_f32_16x16x32_bf16 v[94:97], v[180:183], v[196:199], v[94:97]
	v_mfma_f32_16x16x32_bf16 v[86:89], v[172:175], v[204:207], v[86:89]
	v_mfma_f32_16x16x32_bf16 v[78:81], v[180:183], v[204:207], v[78:81]
	v_mfma_f32_16x16x32_bf16 v[70:73], v[172:175], v[212:215], v[70:73]
	v_mfma_f32_16x16x32_bf16 v[66:69], v[180:183], v[212:215], v[66:69]
	v_mfma_f32_16x16x32_bf16 v[118:121], v[176:179], v[192:195], v[118:121]
	v_mfma_f32_16x16x32_bf16 v[110:113], v[184:187], v[192:195], v[110:113]
	v_mfma_f32_16x16x32_bf16 v[102:105], v[176:179], v[200:203], v[102:105]
	v_mfma_f32_16x16x32_bf16 v[94:97], v[184:187], v[200:203], v[94:97]
	v_mfma_f32_16x16x32_bf16 v[86:89], v[176:179], v[208:211], v[86:89]
	v_mfma_f32_16x16x32_bf16 v[78:81], v[184:187], v[208:211], v[78:81]
	v_mfma_f32_16x16x32_bf16 v[70:73], v[176:179], v[216:219], v[70:73]
	v_mfma_f32_16x16x32_bf16 v[66:69], v[184:187], v[216:219], v[66:69]
	s_barrier
	s_add_i32 s30, s52, s34
	v_lshl_add_u64 v[220:221], v[220:221], 0, s[12:13]
	s_mov_b32 m0, s30
	ds_read_b128 v[188:191], v158 offset:49152
	ds_read_b128 v[192:195], v158 offset:50176
	ds_read_b128 v[196:199], v158 offset:51200
	ds_read_b128 v[200:203], v158 offset:52224
	ds_read_b128 v[204:207], v158 offset:53248
	ds_read_b128 v[208:211], v158 offset:54272
	ds_read_b128 v[212:215], v158 offset:55296
	ds_read_b128 v[216:219], v158 offset:56320
	global_load_lds_dwordx4 v[220:221], off
	s_add_i32 m0, s30, 0x2000
	s_add_u32 s28, s28, 0x100080
	v_lshl_add_u64 v[220:221], v[222:223], 0, s[12:13]
	s_addc_u32 s29, s29, 0
	s_add_i32 s30, s53, s34
	global_load_lds_dwordx4 v[220:221], off
	v_lshl_add_u64 v[220:221], s[28:29], 0, v[134:135]
	s_mov_b32 m0, s30
	s_nop 0
	global_load_lds_dwordx4 v[220:221], off
	v_lshl_add_u64 v[220:221], s[28:29], 0, v[130:131]
	s_add_i32 m0, s30, 0x2000
	s_nop 0
	global_load_lds_dwordx4 v[220:221], off
	v_lshl_add_u64 v[220:221], v[224:225], 0, s[12:13]
	s_mov_b32 m0, s41
	s_nop 0
	global_load_lds_dwordx4 v[220:221], off
	v_lshl_add_u64 v[220:221], v[226:227], 0, s[12:13]
	s_mov_b32 m0, s42
	s_nop 0
	global_load_lds_dwordx4 v[220:221], off
	s_waitcnt vmcnt(8)
	s_waitcnt lgkmcnt(0)
	s_barrier
	v_mfma_f32_16x16x32_bf16 v[62:65], v[148:151], v[188:191], v[62:65]
	v_mfma_f32_16x16x32_bf16 v[58:61], v[164:167], v[188:191], v[58:61]
	v_mfma_f32_16x16x32_bf16 v[50:53], v[148:151], v[196:199], v[50:53]
	v_mfma_f32_16x16x32_bf16 v[42:45], v[164:167], v[196:199], v[42:45]
	v_mfma_f32_16x16x32_bf16 v[34:37], v[148:151], v[204:207], v[34:37]
	v_mfma_f32_16x16x32_bf16 v[26:29], v[164:167], v[204:207], v[26:29]
	v_mfma_f32_16x16x32_bf16 v[18:21], v[148:151], v[212:215], v[18:21]
	v_mfma_f32_16x16x32_bf16 v[10:13], v[164:167], v[212:215], v[10:13]
	v_mfma_f32_16x16x32_bf16 v[62:65], v[160:163], v[192:195], v[62:65]
	v_mfma_f32_16x16x32_bf16 v[58:61], v[168:171], v[192:195], v[58:61]
	v_mfma_f32_16x16x32_bf16 v[50:53], v[160:163], v[200:203], v[50:53]
	v_mfma_f32_16x16x32_bf16 v[42:45], v[168:171], v[200:203], v[42:45]
	v_mfma_f32_16x16x32_bf16 v[34:37], v[160:163], v[208:211], v[34:37]
	v_mfma_f32_16x16x32_bf16 v[26:29], v[168:171], v[208:211], v[26:29]
	v_mfma_f32_16x16x32_bf16 v[18:21], v[160:163], v[216:219], v[18:21]
	v_mfma_f32_16x16x32_bf16 v[10:13], v[168:171], v[216:219], v[10:13]
	v_mfma_f32_16x16x32_bf16 v[54:57], v[172:175], v[188:191], v[54:57]
	v_mfma_f32_16x16x32_bf16 v[46:49], v[180:183], v[188:191], v[46:49]
	v_mfma_f32_16x16x32_bf16 v[38:41], v[172:175], v[196:199], v[38:41]
	v_mfma_f32_16x16x32_bf16 v[30:33], v[180:183], v[196:199], v[30:33]
	v_mfma_f32_16x16x32_bf16 v[22:25], v[172:175], v[204:207], v[22:25]
	v_mfma_f32_16x16x32_bf16 v[14:17], v[180:183], v[204:207], v[14:17]
	v_mfma_f32_16x16x32_bf16 v[6:9], v[172:175], v[212:215], v[6:9]
	v_mfma_f32_16x16x32_bf16 v[2:5], v[180:183], v[212:215], v[2:5]
	v_mfma_f32_16x16x32_bf16 v[54:57], v[176:179], v[192:195], v[54:57]
	v_mfma_f32_16x16x32_bf16 v[46:49], v[184:187], v[192:195], v[46:49]
	v_mfma_f32_16x16x32_bf16 v[38:41], v[176:179], v[200:203], v[38:41]
	v_mfma_f32_16x16x32_bf16 v[30:33], v[184:187], v[200:203], v[30:33]
	v_mfma_f32_16x16x32_bf16 v[22:25], v[176:179], v[208:211], v[22:25]
	v_mfma_f32_16x16x32_bf16 v[14:17], v[184:187], v[208:211], v[14:17]
	v_mfma_f32_16x16x32_bf16 v[6:9], v[176:179], v[216:219], v[6:9]
	v_mfma_f32_16x16x32_bf16 v[2:5], v[184:187], v[216:219], v[2:5]
	s_barrier
	s_add_i32 s51, s51, 2
	s_add_u32 s26, s26, 0x100
	s_addc_u32 s27, s27, 0
	s_add_u32 s49, s49, 0x100
	s_addc_u32 s50, s50, 0
	s_cmp_gt_u32 s51, 61
	s_cbranch_scc0 .LBB0_1087
	s_and_b64 vcc, exec, s[14:15]
	s_cbranch_vccz .LBB0_1090
	s_barrier

.LBB0_1241:
	ds_read_b128 v[144:147], v162
	ds_read_b128 v[166:169], v162 offset:1024
	ds_read_b128 v[170:173], v162 offset:2048
	ds_read_b128 v[174:177], v162 offset:3072
	ds_read_b128 v[178:181], v163
	ds_read_b128 v[182:185], v163 offset:1024
	ds_read_b128 v[186:189], v163 offset:2048
	ds_read_b128 v[190:193], v163 offset:3072
	s_add_u32 s40, s38, 0xfff00080
	s_addc_u32 s41, s39, -1
	s_cmp_eq_u32 s63, 60
	s_cselect_b32 s43, s2, s41
	s_cselect_b32 s42, s29, s40
	s_cselect_b32 s41, s27, s62
	s_cselect_b32 s40, s60, s61
	v_lshl_add_u64 v[148:149], s[38:39], 0, v[138:139]
	s_add_i32 m0, s37, 0xc000
	ds_read_b128 v[194:197], v164
	ds_read_b128 v[198:201], v164 offset:1024
	ds_read_b128 v[202:205], v164 offset:2048
	ds_read_b128 v[206:209], v164 offset:3072
	ds_read_b128 v[210:213], v164 offset:4096
	ds_read_b128 v[214:217], v164 offset:5120
	ds_read_b128 v[218:221], v164 offset:6144
	ds_read_b128 v[222:225], v164 offset:7168
	global_load_lds_dwordx4 v[148:149], off
	v_lshl_add_u64 v[148:149], s[38:39], 0, v[140:141]
	s_add_i32 m0, s37, 0xe000
	s_nop 0
	global_load_lds_dwordx4 v[148:149], off
	s_waitcnt vmcnt(8)
	s_waitcnt lgkmcnt(0)
	s_barrier
	v_mfma_f32_16x16x32_bf16 v[126:129], v[144:147], v[194:197], v[126:129]
	v_mfma_f32_16x16x32_bf16 v[122:125], v[170:173], v[194:197], v[122:125]
	v_mfma_f32_16x16x32_bf16 v[110:113], v[144:147], v[202:205], v[110:113]
	v_mfma_f32_16x16x32_bf16 v[106:109], v[170:173], v[202:205], v[106:109]
	v_mfma_f32_16x16x32_bf16 v[94:97], v[144:147], v[210:213], v[94:97]
	v_mfma_f32_16x16x32_bf16 v[90:93], v[170:173], v[210:213], v[90:93]
	v_mfma_f32_16x16x32_bf16 v[78:81], v[144:147], v[218:221], v[78:81]
	v_mfma_f32_16x16x32_bf16 v[74:77], v[170:173], v[218:221], v[74:77]
	v_mfma_f32_16x16x32_bf16 v[126:129], v[166:169], v[198:201], v[126:129]
	v_mfma_f32_16x16x32_bf16 v[122:125], v[174:177], v[198:201], v[122:125]
	v_mfma_f32_16x16x32_bf16 v[110:113], v[166:169], v[206:209], v[110:113]
	v_mfma_f32_16x16x32_bf16 v[106:109], v[174:177], v[206:209], v[106:109]
	v_mfma_f32_16x16x32_bf16 v[94:97], v[166:169], v[214:217], v[94:97]
	v_mfma_f32_16x16x32_bf16 v[90:93], v[174:177], v[214:217], v[90:93]
	v_mfma_f32_16x16x32_bf16 v[78:81], v[166:169], v[222:225], v[78:81]
	v_mfma_f32_16x16x32_bf16 v[74:77], v[174:177], v[222:225], v[74:77]
	v_mfma_f32_16x16x32_bf16 v[118:121], v[178:181], v[194:197], v[118:121]
	v_mfma_f32_16x16x32_bf16 v[114:117], v[186:189], v[194:197], v[114:117]
	v_mfma_f32_16x16x32_bf16 v[102:105], v[178:181], v[202:205], v[102:105]
	v_mfma_f32_16x16x32_bf16 v[98:101], v[186:189], v[202:205], v[98:101]
	v_mfma_f32_16x16x32_bf16 v[86:89], v[178:181], v[210:213], v[86:89]
	v_mfma_f32_16x16x32_bf16 v[82:85], v[186:189], v[210:213], v[82:85]
	v_mfma_f32_16x16x32_bf16 v[70:73], v[178:181], v[218:221], v[70:73]
	v_mfma_f32_16x16x32_bf16 v[66:69], v[186:189], v[218:221], v[66:69]
	v_mfma_f32_16x16x32_bf16 v[118:121], v[182:185], v[198:201], v[118:121]
	v_mfma_f32_16x16x32_bf16 v[114:117], v[190:193], v[198:201], v[114:117]
	v_mfma_f32_16x16x32_bf16 v[102:105], v[182:185], v[206:209], v[102:105]
	v_mfma_f32_16x16x32_bf16 v[98:101], v[190:193], v[206:209], v[98:101]
	v_mfma_f32_16x16x32_bf16 v[86:89], v[182:185], v[214:217], v[86:89]
	v_mfma_f32_16x16x32_bf16 v[82:85], v[190:193], v[214:217], v[82:85]
	v_mfma_f32_16x16x32_bf16 v[70:73], v[182:185], v[222:225], v[70:73]
	v_mfma_f32_16x16x32_bf16 v[66:69], v[190:193], v[222:225], v[66:69]
	s_barrier
	s_add_i32 s64, s56, s45
	v_lshl_add_u64 v[148:149], s[40:41], 0, v[132:133]
	s_mov_b32 m0, s64
	ds_read_b128 v[194:197], v164 offset:16384
	ds_read_b128 v[198:201], v164 offset:17408
	ds_read_b128 v[202:205], v164 offset:18432
	ds_read_b128 v[206:209], v164 offset:19456
	ds_read_b128 v[210:213], v164 offset:20480
	ds_read_b128 v[214:217], v164 offset:21504
	ds_read_b128 v[218:221], v164 offset:22528
	ds_read_b128 v[222:225], v164 offset:23552
	global_load_lds_dwordx4 v[148:149], off
	s_add_i32 m0, s64, 0x2000
	s_add_u32 s64, s40, 0x100000
	v_lshl_add_u64 v[226:227], s[40:41], 0, v[136:137]
	s_addc_u32 s65, s41, 0
	s_add_i32 s66, s57, s45
	global_load_lds_dwordx4 v[226:227], off
	v_lshl_add_u64 v[228:229], s[64:65], 0, v[132:133]
	s_mov_b32 m0, s66
	v_lshl_add_u64 v[230:231], s[42:43], 0, v[134:135]
	global_load_lds_dwordx4 v[228:229], off
	v_lshl_add_u64 v[228:229], s[64:65], 0, v[136:137]
	s_add_i32 m0, s66, 0x2000
	s_nop 0
	global_load_lds_dwordx4 v[228:229], off
	v_lshl_add_u64 v[228:229], s[42:43], 0, v[130:131]
	s_mov_b32 m0, s37
	s_nop 0
	global_load_lds_dwordx4 v[228:229], off
	s_mov_b32 m0, s46
	s_nop 0
	global_load_lds_dwordx4 v[230:231], off
	s_waitcnt vmcnt(8)
	s_waitcnt lgkmcnt(0)
	s_barrier
	v_mfma_f32_16x16x32_bf16 v[62:65], v[144:147], v[194:197], v[62:65]
	v_mfma_f32_16x16x32_bf16 v[58:61], v[170:173], v[194:197], v[58:61]
	v_mfma_f32_16x16x32_bf16 v[46:49], v[144:147], v[202:205], v[46:49]
	v_mfma_f32_16x16x32_bf16 v[42:45], v[170:173], v[202:205], v[42:45]
	v_mfma_f32_16x16x32_bf16 v[30:33], v[144:147], v[210:213], v[30:33]
	v_mfma_f32_16x16x32_bf16 v[26:29], v[170:173], v[210:213], v[26:29]
	v_mfma_f32_16x16x32_bf16 v[14:17], v[144:147], v[218:221], v[14:17]
	v_mfma_f32_16x16x32_bf16 v[10:13], v[170:173], v[218:221], v[10:13]
	v_mfma_f32_16x16x32_bf16 v[62:65], v[166:169], v[198:201], v[62:65]
	v_mfma_f32_16x16x32_bf16 v[58:61], v[174:177], v[198:201], v[58:61]
	v_mfma_f32_16x16x32_bf16 v[46:49], v[166:169], v[206:209], v[46:49]
	v_mfma_f32_16x16x32_bf16 v[42:45], v[174:177], v[206:209], v[42:45]
	v_mfma_f32_16x16x32_bf16 v[30:33], v[166:169], v[214:217], v[30:33]
	v_mfma_f32_16x16x32_bf16 v[26:29], v[174:177], v[214:217], v[26:29]
	v_mfma_f32_16x16x32_bf16 v[14:17], v[166:169], v[222:225], v[14:17]
	v_mfma_f32_16x16x32_bf16 v[10:13], v[174:177], v[222:225], v[10:13]
	v_mfma_f32_16x16x32_bf16 v[54:57], v[178:181], v[194:197], v[54:57]
	v_mfma_f32_16x16x32_bf16 v[50:53], v[186:189], v[194:197], v[50:53]
	v_mfma_f32_16x16x32_bf16 v[38:41], v[178:181], v[202:205], v[38:41]
	v_mfma_f32_16x16x32_bf16 v[34:37], v[186:189], v[202:205], v[34:37]
	v_mfma_f32_16x16x32_bf16 v[22:25], v[178:181], v[210:213], v[22:25]
	v_mfma_f32_16x16x32_bf16 v[18:21], v[186:189], v[210:213], v[18:21]
	v_mfma_f32_16x16x32_bf16 v[6:9], v[178:181], v[218:221], v[6:9]
	v_mfma_f32_16x16x32_bf16 v[2:5], v[186:189], v[218:221], v[2:5]
	v_mfma_f32_16x16x32_bf16 v[54:57], v[182:185], v[198:201], v[54:57]
	v_mfma_f32_16x16x32_bf16 v[50:53], v[190:193], v[198:201], v[50:53]
	v_mfma_f32_16x16x32_bf16 v[38:41], v[182:185], v[206:209], v[38:41]
	v_mfma_f32_16x16x32_bf16 v[34:37], v[190:193], v[206:209], v[34:37]
	v_mfma_f32_16x16x32_bf16 v[22:25], v[182:185], v[214:217], v[22:25]
	v_mfma_f32_16x16x32_bf16 v[18:21], v[190:193], v[214:217], v[18:21]
	v_mfma_f32_16x16x32_bf16 v[6:9], v[182:185], v[222:225], v[6:9]
	v_mfma_f32_16x16x32_bf16 v[2:5], v[190:193], v[222:225], v[2:5]
	s_barrier
	s_add_i32 s64, 0, 0x18000
	v_add_u32_e32 v142, s64, v160
	s_add_i32 s65, 0, 0x1c000
	ds_read_b128 v[144:147], v142
	ds_read_b128 v[166:169], v142 offset:1024
	ds_read_b128 v[170:173], v142 offset:2048
	ds_read_b128 v[174:177], v142 offset:3072
	v_add_u32_e32 v142, s65, v160
	ds_read_b128 v[178:181], v142
	ds_read_b128 v[182:185], v142 offset:1024
	ds_read_b128 v[186:189], v142 offset:2048
	ds_read_b128 v[190:193], v142 offset:3072
	s_add_u32 s42, s42, 0x100000
	s_addc_u32 s43, s43, 0
	s_mov_b32 m0, s47
	v_lshl_add_u64 v[232:233], s[42:43], 0, v[130:131]
	ds_read_b128 v[194:197], v164 offset:32768
	ds_read_b128 v[198:201], v164 offset:33792
	ds_read_b128 v[202:205], v164 offset:34816
	ds_read_b128 v[206:209], v164 offset:35840
	ds_read_b128 v[210:213], v164 offset:36864
	ds_read_b128 v[214:217], v164 offset:37888
	ds_read_b128 v[218:221], v164 offset:38912
	ds_read_b128 v[222:225], v164 offset:39936
	global_load_lds_dwordx4 v[232:233], off
	v_lshl_add_u64 v[232:233], s[42:43], 0, v[134:135]
	s_mov_b32 m0, s48
	s_nop 0
	global_load_lds_dwordx4 v[232:233], off
	s_waitcnt vmcnt(8)
	s_waitcnt lgkmcnt(0)
	s_barrier
	v_mfma_f32_16x16x32_bf16 v[126:129], v[144:147], v[194:197], v[126:129]
	v_mfma_f32_16x16x32_bf16 v[122:125], v[170:173], v[194:197], v[122:125]
	v_mfma_f32_16x16x32_bf16 v[110:113], v[144:147], v[202:205], v[110:113]
	v_mfma_f32_16x16x32_bf16 v[106:109], v[170:173], v[202:205], v[106:109]
	v_mfma_f32_16x16x32_bf16 v[94:97], v[144:147], v[210:213], v[94:97]
	v_mfma_f32_16x16x32_bf16 v[90:93], v[170:173], v[210:213], v[90:93]
	v_mfma_f32_16x16x32_bf16 v[78:81], v[144:147], v[218:221], v[78:81]
	v_mfma_f32_16x16x32_bf16 v[74:77], v[170:173], v[218:221], v[74:77]
	v_mfma_f32_16x16x32_bf16 v[126:129], v[166:169], v[198:201], v[126:129]
	v_mfma_f32_16x16x32_bf16 v[122:125], v[174:177], v[198:201], v[122:125]
	v_mfma_f32_16x16x32_bf16 v[110:113], v[166:169], v[206:209], v[110:113]
	v_mfma_f32_16x16x32_bf16 v[106:109], v[174:177], v[206:209], v[106:109]
	v_mfma_f32_16x16x32_bf16 v[94:97], v[166:169], v[214:217], v[94:97]
	v_mfma_f32_16x16x32_bf16 v[90:93], v[174:177], v[214:217], v[90:93]
	v_mfma_f32_16x16x32_bf16 v[78:81], v[166:169], v[222:225], v[78:81]
	v_mfma_f32_16x16x32_bf16 v[74:77], v[174:177], v[222:225], v[74:77]
	v_mfma_f32_16x16x32_bf16 v[118:121], v[178:181], v[194:197], v[118:121]
	v_mfma_f32_16x16x32_bf16 v[114:117], v[186:189], v[194:197], v[114:117]
	v_mfma_f32_16x16x32_bf16 v[102:105], v[178:181], v[202:205], v[102:105]
	v_mfma_f32_16x16x32_bf16 v[98:101], v[186:189], v[202:205], v[98:101]
	v_mfma_f32_16x16x32_bf16 v[86:89], v[178:181], v[210:213], v[86:89]
	v_mfma_f32_16x16x32_bf16 v[82:85], v[186:189], v[210:213], v[82:85]
	v_mfma_f32_16x16x32_bf16 v[70:73], v[178:181], v[218:221], v[70:73]
	v_mfma_f32_16x16x32_bf16 v[66:69], v[186:189], v[218:221], v[66:69]
	v_mfma_f32_16x16x32_bf16 v[118:121], v[182:185], v[198:201], v[118:121]
	v_mfma_f32_16x16x32_bf16 v[114:117], v[190:193], v[198:201], v[114:117]
	v_mfma_f32_16x16x32_bf16 v[102:105], v[182:185], v[206:209], v[102:105]
	v_mfma_f32_16x16x32_bf16 v[98:101], v[190:193], v[206:209], v[98:101]
	v_mfma_f32_16x16x32_bf16 v[86:89], v[182:185], v[214:217], v[86:89]
	v_mfma_f32_16x16x32_bf16 v[82:85], v[190:193], v[214:217], v[82:85]
	v_mfma_f32_16x16x32_bf16 v[70:73], v[182:185], v[222:225], v[70:73]
	v_mfma_f32_16x16x32_bf16 v[66:69], v[190:193], v[222:225], v[66:69]
	s_barrier
	s_add_i32 s42, s64, s45
	v_lshl_add_u64 v[148:149], v[148:149], 0, s[12:13]
	s_mov_b32 m0, s42
	ds_read_b128 v[194:197], v164 offset:49152
	ds_read_b128 v[198:201], v164 offset:50176
	ds_read_b128 v[202:205], v164 offset:51200
	ds_read_b128 v[206:209], v164 offset:52224
	ds_read_b128 v[210:213], v164 offset:53248
	ds_read_b128 v[214:217], v164 offset:54272
	ds_read_b128 v[218:221], v164 offset:55296
	ds_read_b128 v[222:225], v164 offset:56320
	global_load_lds_dwordx4 v[148:149], off
	s_add_i32 m0, s42, 0x2000
	s_add_u32 s40, s40, 0x100080
	v_lshl_add_u64 v[148:149], v[226:227], 0, s[12:13]
	s_addc_u32 s41, s41, 0
	s_add_i32 s42, s65, s45
	global_load_lds_dwordx4 v[148:149], off
	v_lshl_add_u64 v[148:149], s[40:41], 0, v[132:133]
	s_mov_b32 m0, s42
	s_nop 0
	global_load_lds_dwordx4 v[148:149], off
	v_lshl_add_u64 v[148:149], s[40:41], 0, v[136:137]
	s_add_i32 m0, s42, 0x2000
	s_nop 0
	global_load_lds_dwordx4 v[148:149], off
	v_lshl_add_u64 v[148:149], v[228:229], 0, s[12:13]
	s_mov_b32 m0, s53
	s_nop 0
	global_load_lds_dwordx4 v[148:149], off
	v_lshl_add_u64 v[148:149], v[230:231], 0, s[12:13]
	s_mov_b32 m0, s54
	s_nop 0
	global_load_lds_dwordx4 v[148:149], off
	s_waitcnt vmcnt(8)
	s_waitcnt lgkmcnt(0)
	s_barrier
	v_mfma_f32_16x16x32_bf16 v[62:65], v[144:147], v[194:197], v[62:65]
	v_mfma_f32_16x16x32_bf16 v[58:61], v[170:173], v[194:197], v[58:61]
	v_mfma_f32_16x16x32_bf16 v[46:49], v[144:147], v[202:205], v[46:49]
	v_mfma_f32_16x16x32_bf16 v[42:45], v[170:173], v[202:205], v[42:45]
	v_mfma_f32_16x16x32_bf16 v[30:33], v[144:147], v[210:213], v[30:33]
	v_mfma_f32_16x16x32_bf16 v[26:29], v[170:173], v[210:213], v[26:29]
	v_mfma_f32_16x16x32_bf16 v[14:17], v[144:147], v[218:221], v[14:17]
	v_mfma_f32_16x16x32_bf16 v[10:13], v[170:173], v[218:221], v[10:13]
	v_mfma_f32_16x16x32_bf16 v[62:65], v[166:169], v[198:201], v[62:65]
	v_mfma_f32_16x16x32_bf16 v[58:61], v[174:177], v[198:201], v[58:61]
	v_mfma_f32_16x16x32_bf16 v[46:49], v[166:169], v[206:209], v[46:49]
	v_mfma_f32_16x16x32_bf16 v[42:45], v[174:177], v[206:209], v[42:45]
	v_mfma_f32_16x16x32_bf16 v[30:33], v[166:169], v[214:217], v[30:33]
	v_mfma_f32_16x16x32_bf16 v[26:29], v[174:177], v[214:217], v[26:29]
	v_mfma_f32_16x16x32_bf16 v[14:17], v[166:169], v[222:225], v[14:17]
	v_mfma_f32_16x16x32_bf16 v[10:13], v[174:177], v[222:225], v[10:13]
	v_mfma_f32_16x16x32_bf16 v[54:57], v[178:181], v[194:197], v[54:57]
	v_mfma_f32_16x16x32_bf16 v[50:53], v[186:189], v[194:197], v[50:53]
	v_mfma_f32_16x16x32_bf16 v[38:41], v[178:181], v[202:205], v[38:41]
	v_mfma_f32_16x16x32_bf16 v[34:37], v[186:189], v[202:205], v[34:37]
	v_mfma_f32_16x16x32_bf16 v[22:25], v[178:181], v[210:213], v[22:25]
	v_mfma_f32_16x16x32_bf16 v[18:21], v[186:189], v[210:213], v[18:21]
	v_mfma_f32_16x16x32_bf16 v[6:9], v[178:181], v[218:221], v[6:9]
	v_mfma_f32_16x16x32_bf16 v[2:5], v[186:189], v[218:221], v[2:5]
	v_mfma_f32_16x16x32_bf16 v[54:57], v[182:185], v[198:201], v[54:57]
	v_mfma_f32_16x16x32_bf16 v[50:53], v[190:193], v[198:201], v[50:53]
	v_mfma_f32_16x16x32_bf16 v[38:41], v[182:185], v[206:209], v[38:41]
	v_mfma_f32_16x16x32_bf16 v[34:37], v[190:193], v[206:209], v[34:37]
	v_mfma_f32_16x16x32_bf16 v[22:25], v[182:185], v[214:217], v[22:25]
	v_mfma_f32_16x16x32_bf16 v[18:21], v[190:193], v[214:217], v[18:21]
	v_mfma_f32_16x16x32_bf16 v[6:9], v[182:185], v[222:225], v[6:9]
	v_mfma_f32_16x16x32_bf16 v[2:5], v[190:193], v[222:225], v[2:5]
	s_barrier
	s_add_i32 s63, s63, 2
	s_add_u32 s38, s38, 0x100
	s_addc_u32 s39, s39, 0
	s_add_u32 s61, s61, 0x100
	s_addc_u32 s62, s62, 0
	s_cmp_gt_u32 s63, 61
	s_cbranch_scc0 .LBB0_1241
	s_and_b64 vcc, exec, s[14:15]
	s_cbranch_vccz .LBB0_1244
	s_barrier

.LBB0_1294:
	ds_read_b128 v[144:147], v151
	ds_read_b128 v[160:163], v151 offset:1024
	ds_read_b128 v[164:167], v151 offset:2048
	ds_read_b128 v[168:171], v151 offset:3072
	ds_read_b128 v[172:175], v152
	ds_read_b128 v[176:179], v152 offset:1024
	ds_read_b128 v[180:183], v152 offset:2048
	ds_read_b128 v[184:187], v152 offset:3072
	s_add_u32 s40, s38, 0xfff00080
	s_addc_u32 s41, s39, -1
	s_cmp_eq_u32 s64, 60
	s_cselect_b32 s43, s2, s41
	s_cselect_b32 s42, s29, s40
	s_cselect_b32 s41, s27, s63
	s_cselect_b32 s40, s61, s62
	v_lshl_add_u64 v[148:149], s[38:39], 0, v[138:139]
	s_add_i32 m0, s37, 0xc000
	ds_read_b128 v[188:191], v153
	ds_read_b128 v[192:195], v153 offset:1024
	ds_read_b128 v[196:199], v153 offset:2048
	ds_read_b128 v[200:203], v153 offset:3072
	ds_read_b128 v[204:207], v153 offset:4096
	ds_read_b128 v[208:211], v153 offset:5120
	ds_read_b128 v[212:215], v153 offset:6144
	ds_read_b128 v[216:219], v153 offset:7168
	global_load_lds_dwordx4 v[148:149], off
	v_lshl_add_u64 v[148:149], s[38:39], 0, v[140:141]
	s_add_i32 m0, s37, 0xe000
	s_nop 0
	global_load_lds_dwordx4 v[148:149], off
	s_waitcnt vmcnt(8)
	s_waitcnt lgkmcnt(0)
	s_barrier
	v_mfma_f32_16x16x32_bf16 v[126:129], v[144:147], v[188:191], v[126:129]
	v_mfma_f32_16x16x32_bf16 v[122:125], v[164:167], v[188:191], v[122:125]
	v_mfma_f32_16x16x32_bf16 v[110:113], v[144:147], v[196:199], v[110:113]
	v_mfma_f32_16x16x32_bf16 v[106:109], v[164:167], v[196:199], v[106:109]
	v_mfma_f32_16x16x32_bf16 v[94:97], v[144:147], v[204:207], v[94:97]
	v_mfma_f32_16x16x32_bf16 v[90:93], v[164:167], v[204:207], v[90:93]
	v_mfma_f32_16x16x32_bf16 v[78:81], v[144:147], v[212:215], v[78:81]
	v_mfma_f32_16x16x32_bf16 v[74:77], v[164:167], v[212:215], v[74:77]
	v_mfma_f32_16x16x32_bf16 v[126:129], v[160:163], v[192:195], v[126:129]
	v_mfma_f32_16x16x32_bf16 v[122:125], v[168:171], v[192:195], v[122:125]
	v_mfma_f32_16x16x32_bf16 v[110:113], v[160:163], v[200:203], v[110:113]
	v_mfma_f32_16x16x32_bf16 v[106:109], v[168:171], v[200:203], v[106:109]
	v_mfma_f32_16x16x32_bf16 v[94:97], v[160:163], v[208:211], v[94:97]
	v_mfma_f32_16x16x32_bf16 v[90:93], v[168:171], v[208:211], v[90:93]
	v_mfma_f32_16x16x32_bf16 v[78:81], v[160:163], v[216:219], v[78:81]
	v_mfma_f32_16x16x32_bf16 v[74:77], v[168:171], v[216:219], v[74:77]
	v_mfma_f32_16x16x32_bf16 v[118:121], v[172:175], v[188:191], v[118:121]
	v_mfma_f32_16x16x32_bf16 v[114:117], v[180:183], v[188:191], v[114:117]
	v_mfma_f32_16x16x32_bf16 v[102:105], v[172:175], v[196:199], v[102:105]
	v_mfma_f32_16x16x32_bf16 v[98:101], v[180:183], v[196:199], v[98:101]
	v_mfma_f32_16x16x32_bf16 v[86:89], v[172:175], v[204:207], v[86:89]
	v_mfma_f32_16x16x32_bf16 v[82:85], v[180:183], v[204:207], v[82:85]
	v_mfma_f32_16x16x32_bf16 v[70:73], v[172:175], v[212:215], v[70:73]
	v_mfma_f32_16x16x32_bf16 v[66:69], v[180:183], v[212:215], v[66:69]
	v_mfma_f32_16x16x32_bf16 v[118:121], v[176:179], v[192:195], v[118:121]
	v_mfma_f32_16x16x32_bf16 v[114:117], v[184:187], v[192:195], v[114:117]
	v_mfma_f32_16x16x32_bf16 v[102:105], v[176:179], v[200:203], v[102:105]
	v_mfma_f32_16x16x32_bf16 v[98:101], v[184:187], v[200:203], v[98:101]
	v_mfma_f32_16x16x32_bf16 v[86:89], v[176:179], v[208:211], v[86:89]
	v_mfma_f32_16x16x32_bf16 v[82:85], v[184:187], v[208:211], v[82:85]
	v_mfma_f32_16x16x32_bf16 v[70:73], v[176:179], v[216:219], v[70:73]
	v_mfma_f32_16x16x32_bf16 v[66:69], v[184:187], v[216:219], v[66:69]
	s_barrier
	s_add_i32 s65, s57, s46
	v_lshl_add_u64 v[148:149], s[40:41], 0, v[132:133]
	s_mov_b32 m0, s65
	ds_read_b128 v[188:191], v153 offset:16384
	ds_read_b128 v[192:195], v153 offset:17408
	ds_read_b128 v[196:199], v153 offset:18432
	ds_read_b128 v[200:203], v153 offset:19456
	ds_read_b128 v[204:207], v153 offset:20480
	ds_read_b128 v[208:211], v153 offset:21504
	ds_read_b128 v[212:215], v153 offset:22528
	ds_read_b128 v[216:219], v153 offset:23552
	global_load_lds_dwordx4 v[148:149], off
	s_add_i32 m0, s65, 0x2000
	s_add_u32 s66, s40, 0x100000
	v_lshl_add_u64 v[220:221], s[40:41], 0, v[136:137]
	s_addc_u32 s67, s41, 0
	s_add_i32 s65, s58, s46
	global_load_lds_dwordx4 v[220:221], off
	v_lshl_add_u64 v[222:223], s[66:67], 0, v[132:133]
	s_mov_b32 m0, s65
	v_lshl_add_u64 v[224:225], s[42:43], 0, v[134:135]
	global_load_lds_dwordx4 v[222:223], off
	v_lshl_add_u64 v[222:223], s[66:67], 0, v[136:137]
	s_add_i32 m0, s65, 0x2000
	s_nop 0
	global_load_lds_dwordx4 v[222:223], off
	v_lshl_add_u64 v[222:223], s[42:43], 0, v[130:131]
	s_mov_b32 m0, s37
	s_nop 0
	global_load_lds_dwordx4 v[222:223], off
	s_mov_b32 m0, s47
	s_nop 0
	global_load_lds_dwordx4 v[224:225], off
	s_waitcnt vmcnt(8)
	s_waitcnt lgkmcnt(0)
	s_barrier
	v_mfma_f32_16x16x32_bf16 v[62:65], v[144:147], v[188:191], v[62:65]
	v_mfma_f32_16x16x32_bf16 v[58:61], v[164:167], v[188:191], v[58:61]
	v_mfma_f32_16x16x32_bf16 v[46:49], v[144:147], v[196:199], v[46:49]
	v_mfma_f32_16x16x32_bf16 v[42:45], v[164:167], v[196:199], v[42:45]
	v_mfma_f32_16x16x32_bf16 v[30:33], v[144:147], v[204:207], v[30:33]
	v_mfma_f32_16x16x32_bf16 v[26:29], v[164:167], v[204:207], v[26:29]
	v_mfma_f32_16x16x32_bf16 v[14:17], v[144:147], v[212:215], v[14:17]
	v_mfma_f32_16x16x32_bf16 v[10:13], v[164:167], v[212:215], v[10:13]
	v_mfma_f32_16x16x32_bf16 v[62:65], v[160:163], v[192:195], v[62:65]
	v_mfma_f32_16x16x32_bf16 v[58:61], v[168:171], v[192:195], v[58:61]
	v_mfma_f32_16x16x32_bf16 v[46:49], v[160:163], v[200:203], v[46:49]
	v_mfma_f32_16x16x32_bf16 v[42:45], v[168:171], v[200:203], v[42:45]
	v_mfma_f32_16x16x32_bf16 v[30:33], v[160:163], v[208:211], v[30:33]
	v_mfma_f32_16x16x32_bf16 v[26:29], v[168:171], v[208:211], v[26:29]
	v_mfma_f32_16x16x32_bf16 v[14:17], v[160:163], v[216:219], v[14:17]
	v_mfma_f32_16x16x32_bf16 v[10:13], v[168:171], v[216:219], v[10:13]
	v_mfma_f32_16x16x32_bf16 v[54:57], v[172:175], v[188:191], v[54:57]
	v_mfma_f32_16x16x32_bf16 v[50:53], v[180:183], v[188:191], v[50:53]
	v_mfma_f32_16x16x32_bf16 v[38:41], v[172:175], v[196:199], v[38:41]
	v_mfma_f32_16x16x32_bf16 v[34:37], v[180:183], v[196:199], v[34:37]
	v_mfma_f32_16x16x32_bf16 v[22:25], v[172:175], v[204:207], v[22:25]
	v_mfma_f32_16x16x32_bf16 v[18:21], v[180:183], v[204:207], v[18:21]
	v_mfma_f32_16x16x32_bf16 v[6:9], v[172:175], v[212:215], v[6:9]
	v_mfma_f32_16x16x32_bf16 v[2:5], v[180:183], v[212:215], v[2:5]
	v_mfma_f32_16x16x32_bf16 v[54:57], v[176:179], v[192:195], v[54:57]
	v_mfma_f32_16x16x32_bf16 v[50:53], v[184:187], v[192:195], v[50:53]
	v_mfma_f32_16x16x32_bf16 v[38:41], v[176:179], v[200:203], v[38:41]
	v_mfma_f32_16x16x32_bf16 v[34:37], v[184:187], v[200:203], v[34:37]
	v_mfma_f32_16x16x32_bf16 v[22:25], v[176:179], v[208:211], v[22:25]
	v_mfma_f32_16x16x32_bf16 v[18:21], v[184:187], v[208:211], v[18:21]
	v_mfma_f32_16x16x32_bf16 v[6:9], v[176:179], v[216:219], v[6:9]
	v_mfma_f32_16x16x32_bf16 v[2:5], v[184:187], v[216:219], v[2:5]
	s_barrier
	s_add_i32 s65, 0, 0x18000
	v_add_u32_e32 v142, s65, v156
	s_add_i32 s66, 0, 0x1c000
	ds_read_b128 v[144:147], v142
	ds_read_b128 v[160:163], v142 offset:1024
	ds_read_b128 v[164:167], v142 offset:2048
	ds_read_b128 v[168:171], v142 offset:3072
	v_add_u32_e32 v142, s66, v156
	ds_read_b128 v[172:175], v142
	ds_read_b128 v[176:179], v142 offset:1024
	ds_read_b128 v[180:183], v142 offset:2048
	ds_read_b128 v[184:187], v142 offset:3072
	s_add_u32 s42, s42, 0x100000
	s_addc_u32 s43, s43, 0
	s_mov_b32 m0, s48
	v_lshl_add_u64 v[226:227], s[42:43], 0, v[130:131]
	ds_read_b128 v[188:191], v153 offset:32768
	ds_read_b128 v[192:195], v153 offset:33792
	ds_read_b128 v[196:199], v153 offset:34816
	ds_read_b128 v[200:203], v153 offset:35840
	ds_read_b128 v[204:207], v153 offset:36864
	ds_read_b128 v[208:211], v153 offset:37888
	ds_read_b128 v[212:215], v153 offset:38912
	ds_read_b128 v[216:219], v153 offset:39936
	global_load_lds_dwordx4 v[226:227], off
	v_lshl_add_u64 v[226:227], s[42:43], 0, v[134:135]
	s_mov_b32 m0, s49
	s_nop 0
	global_load_lds_dwordx4 v[226:227], off
	s_waitcnt vmcnt(8)
	s_waitcnt lgkmcnt(0)
	s_barrier
	v_mfma_f32_16x16x32_bf16 v[126:129], v[144:147], v[188:191], v[126:129]
	v_mfma_f32_16x16x32_bf16 v[122:125], v[164:167], v[188:191], v[122:125]
	v_mfma_f32_16x16x32_bf16 v[110:113], v[144:147], v[196:199], v[110:113]
	v_mfma_f32_16x16x32_bf16 v[106:109], v[164:167], v[196:199], v[106:109]
	v_mfma_f32_16x16x32_bf16 v[94:97], v[144:147], v[204:207], v[94:97]
	v_mfma_f32_16x16x32_bf16 v[90:93], v[164:167], v[204:207], v[90:93]
	v_mfma_f32_16x16x32_bf16 v[78:81], v[144:147], v[212:215], v[78:81]
	v_mfma_f32_16x16x32_bf16 v[74:77], v[164:167], v[212:215], v[74:77]
	v_mfma_f32_16x16x32_bf16 v[126:129], v[160:163], v[192:195], v[126:129]
	v_mfma_f32_16x16x32_bf16 v[122:125], v[168:171], v[192:195], v[122:125]
	v_mfma_f32_16x16x32_bf16 v[110:113], v[160:163], v[200:203], v[110:113]
	v_mfma_f32_16x16x32_bf16 v[106:109], v[168:171], v[200:203], v[106:109]
	v_mfma_f32_16x16x32_bf16 v[94:97], v[160:163], v[208:211], v[94:97]
	v_mfma_f32_16x16x32_bf16 v[90:93], v[168:171], v[208:211], v[90:93]
	v_mfma_f32_16x16x32_bf16 v[78:81], v[160:163], v[216:219], v[78:81]
	v_mfma_f32_16x16x32_bf16 v[74:77], v[168:171], v[216:219], v[74:77]
	v_mfma_f32_16x16x32_bf16 v[118:121], v[172:175], v[188:191], v[118:121]
	v_mfma_f32_16x16x32_bf16 v[114:117], v[180:183], v[188:191], v[114:117]
	v_mfma_f32_16x16x32_bf16 v[102:105], v[172:175], v[196:199], v[102:105]
	v_mfma_f32_16x16x32_bf16 v[98:101], v[180:183], v[196:199], v[98:101]
	v_mfma_f32_16x16x32_bf16 v[86:89], v[172:175], v[204:207], v[86:89]
	v_mfma_f32_16x16x32_bf16 v[82:85], v[180:183], v[204:207], v[82:85]
	v_mfma_f32_16x16x32_bf16 v[70:73], v[172:175], v[212:215], v[70:73]
	v_mfma_f32_16x16x32_bf16 v[66:69], v[180:183], v[212:215], v[66:69]
	v_mfma_f32_16x16x32_bf16 v[118:121], v[176:179], v[192:195], v[118:121]
	v_mfma_f32_16x16x32_bf16 v[114:117], v[184:187], v[192:195], v[114:117]
	v_mfma_f32_16x16x32_bf16 v[102:105], v[176:179], v[200:203], v[102:105]
	v_mfma_f32_16x16x32_bf16 v[98:101], v[184:187], v[200:203], v[98:101]
	v_mfma_f32_16x16x32_bf16 v[86:89], v[176:179], v[208:211], v[86:89]
	v_mfma_f32_16x16x32_bf16 v[82:85], v[184:187], v[208:211], v[82:85]
	v_mfma_f32_16x16x32_bf16 v[70:73], v[176:179], v[216:219], v[70:73]
	v_mfma_f32_16x16x32_bf16 v[66:69], v[184:187], v[216:219], v[66:69]
	s_barrier
	s_add_i32 s42, s65, s46
	v_lshl_add_u64 v[148:149], v[148:149], 0, s[12:13]
	s_mov_b32 m0, s42
	ds_read_b128 v[188:191], v153 offset:49152
	ds_read_b128 v[192:195], v153 offset:50176
	ds_read_b128 v[196:199], v153 offset:51200
	ds_read_b128 v[200:203], v153 offset:52224
	ds_read_b128 v[204:207], v153 offset:53248
	ds_read_b128 v[208:211], v153 offset:54272
	ds_read_b128 v[212:215], v153 offset:55296
	ds_read_b128 v[216:219], v153 offset:56320
	global_load_lds_dwordx4 v[148:149], off
	s_add_i32 m0, s42, 0x2000
	s_add_u32 s40, s40, 0x100080
	v_lshl_add_u64 v[148:149], v[220:221], 0, s[12:13]
	s_addc_u32 s41, s41, 0
	s_add_i32 s42, s66, s46
	global_load_lds_dwordx4 v[148:149], off
	v_lshl_add_u64 v[148:149], s[40:41], 0, v[132:133]
	s_mov_b32 m0, s42
	s_nop 0
	global_load_lds_dwordx4 v[148:149], off
	v_lshl_add_u64 v[148:149], s[40:41], 0, v[136:137]
	s_add_i32 m0, s42, 0x2000
	s_nop 0
	global_load_lds_dwordx4 v[148:149], off
	v_lshl_add_u64 v[148:149], v[222:223], 0, s[12:13]
	s_mov_b32 m0, s54
	s_nop 0
	global_load_lds_dwordx4 v[148:149], off
	v_lshl_add_u64 v[148:149], v[224:225], 0, s[12:13]
	s_mov_b32 m0, s55
	s_nop 0
	global_load_lds_dwordx4 v[148:149], off
	s_waitcnt vmcnt(8)
	s_waitcnt lgkmcnt(0)
	s_barrier
	v_mfma_f32_16x16x32_bf16 v[62:65], v[144:147], v[188:191], v[62:65]
	v_mfma_f32_16x16x32_bf16 v[58:61], v[164:167], v[188:191], v[58:61]
	v_mfma_f32_16x16x32_bf16 v[46:49], v[144:147], v[196:199], v[46:49]
	v_mfma_f32_16x16x32_bf16 v[42:45], v[164:167], v[196:199], v[42:45]
	v_mfma_f32_16x16x32_bf16 v[30:33], v[144:147], v[204:207], v[30:33]
	v_mfma_f32_16x16x32_bf16 v[26:29], v[164:167], v[204:207], v[26:29]
	v_mfma_f32_16x16x32_bf16 v[14:17], v[144:147], v[212:215], v[14:17]
	v_mfma_f32_16x16x32_bf16 v[10:13], v[164:167], v[212:215], v[10:13]
	v_mfma_f32_16x16x32_bf16 v[62:65], v[160:163], v[192:195], v[62:65]
	v_mfma_f32_16x16x32_bf16 v[58:61], v[168:171], v[192:195], v[58:61]
	v_mfma_f32_16x16x32_bf16 v[46:49], v[160:163], v[200:203], v[46:49]
	v_mfma_f32_16x16x32_bf16 v[42:45], v[168:171], v[200:203], v[42:45]
	v_mfma_f32_16x16x32_bf16 v[30:33], v[160:163], v[208:211], v[30:33]
	v_mfma_f32_16x16x32_bf16 v[26:29], v[168:171], v[208:211], v[26:29]
	v_mfma_f32_16x16x32_bf16 v[14:17], v[160:163], v[216:219], v[14:17]
	v_mfma_f32_16x16x32_bf16 v[10:13], v[168:171], v[216:219], v[10:13]
	v_mfma_f32_16x16x32_bf16 v[54:57], v[172:175], v[188:191], v[54:57]
	v_mfma_f32_16x16x32_bf16 v[50:53], v[180:183], v[188:191], v[50:53]
	v_mfma_f32_16x16x32_bf16 v[38:41], v[172:175], v[196:199], v[38:41]
	v_mfma_f32_16x16x32_bf16 v[34:37], v[180:183], v[196:199], v[34:37]
	v_mfma_f32_16x16x32_bf16 v[22:25], v[172:175], v[204:207], v[22:25]
	v_mfma_f32_16x16x32_bf16 v[18:21], v[180:183], v[204:207], v[18:21]
	v_mfma_f32_16x16x32_bf16 v[6:9], v[172:175], v[212:215], v[6:9]
	v_mfma_f32_16x16x32_bf16 v[2:5], v[180:183], v[212:215], v[2:5]
	v_mfma_f32_16x16x32_bf16 v[54:57], v[176:179], v[192:195], v[54:57]
	v_mfma_f32_16x16x32_bf16 v[50:53], v[184:187], v[192:195], v[50:53]
	v_mfma_f32_16x16x32_bf16 v[38:41], v[176:179], v[200:203], v[38:41]
	v_mfma_f32_16x16x32_bf16 v[34:37], v[184:187], v[200:203], v[34:37]
	v_mfma_f32_16x16x32_bf16 v[22:25], v[176:179], v[208:211], v[22:25]
	v_mfma_f32_16x16x32_bf16 v[18:21], v[184:187], v[208:211], v[18:21]
	v_mfma_f32_16x16x32_bf16 v[6:9], v[176:179], v[216:219], v[6:9]
	v_mfma_f32_16x16x32_bf16 v[2:5], v[184:187], v[216:219], v[2:5]
	s_barrier
	s_add_i32 s64, s64, 2
	s_add_u32 s38, s38, 0x100
	s_addc_u32 s39, s39, 0
	s_add_u32 s62, s62, 0x100
	s_addc_u32 s63, s63, 0
	s_cmp_gt_u32 s64, 61
	s_cbranch_scc0 .LBB0_1294
	s_and_b64 vcc, exec, s[14:15]
	s_cbranch_vccz .LBB0_1297
	s_barrier

.LBB0_1386:
	s_add_u32 s47, s38, s46
	s_addc_u32 s52, s39, 0
	s_add_u32 s50, s47, 0x100
	s_addc_u32 s51, s52, 0
	s_and_b64 s[48:49], s[44:45], exec
	s_cselect_b32 s49, s2, s51
	s_cselect_b32 s48, s29, s50
	s_add_u32 s46, s40, s46
	s_addc_u32 s50, s41, 0
	s_add_u32 s46, s46, 0x100
	s_addc_u32 s50, s50, 0
	s_and_b64 s[44:45], s[44:45], exec
	s_cselect_b32 s51, s27, s50
	s_cselect_b32 s50, s70, s46
	s_add_u32 s54, s47, 0x10080
	ds_read_b128 v[152:155], v148
	ds_read_b128 v[156:159], v148 offset:1024
	ds_read_b128 v[160:163], v148 offset:2048
	ds_read_b128 v[164:167], v148 offset:3072
	ds_read_b128 v[168:171], v149
	ds_read_b128 v[172:175], v149 offset:1024
	ds_read_b128 v[176:179], v149 offset:2048
	ds_read_b128 v[180:183], v149 offset:3072
	s_addc_u32 s55, s52, 0
	s_add_i32 s83, s66, s57
	s_add_i32 m0, s37, 0xc000
	s_add_i32 s84, s37, 0xe000
	s_add_i32 s79, s83, 0x2000
	s_add_u32 s52, s50, 0x10000
	s_addc_u32 s53, s51, 0
	s_add_i32 s82, s67, s57
	s_add_i32 s81, s82, 0x2000
	s_add_i32 s78, 0, 0x18000
	s_add_i32 s77, 0, 0x1c000
	s_add_u32 s46, s48, 0x10000
	s_addc_u32 s47, s49, 0
	s_add_i32 s76, s78, s57
	s_add_i32 s72, s76, 0x2000
	s_add_u32 s44, s50, 0x10080
	s_addc_u32 s45, s51, 0
	s_add_i32 s73, s77, s57
	s_add_i32 s71, s73, 0x2000
	v_lshl_add_u64 v[140:141], s[54:55], 0, v[130:131]
	ds_read_b128 v[184:187], v150
	ds_read_b128 v[188:191], v150 offset:1024
	ds_read_b128 v[192:195], v150 offset:2048
	ds_read_b128 v[196:199], v150 offset:3072
	ds_read_b128 v[200:203], v150 offset:4096
	ds_read_b128 v[204:207], v150 offset:5120
	ds_read_b128 v[208:211], v150 offset:6144
	ds_read_b128 v[212:215], v150 offset:7168
	global_load_lds_dwordx4 v[140:141], off
	v_lshl_add_u64 v[140:141], s[54:55], 0, v[134:135]
	s_mov_b32 m0, s84
	s_nop 0
	global_load_lds_dwordx4 v[140:141], off
	s_waitcnt vmcnt(8)
	s_waitcnt lgkmcnt(0)
	s_barrier
	v_mfma_f32_16x16x32_bf16 v[126:129], v[152:155], v[184:187], v[126:129]
	v_mfma_f32_16x16x32_bf16 v[122:125], v[160:163], v[184:187], v[122:125]
	v_mfma_f32_16x16x32_bf16 v[114:117], v[152:155], v[192:195], v[114:117]
	v_mfma_f32_16x16x32_bf16 v[106:109], v[160:163], v[192:195], v[106:109]
	v_mfma_f32_16x16x32_bf16 v[98:101], v[152:155], v[200:203], v[98:101]
	v_mfma_f32_16x16x32_bf16 v[90:93], v[160:163], v[200:203], v[90:93]
	v_mfma_f32_16x16x32_bf16 v[82:85], v[152:155], v[208:211], v[82:85]
	v_mfma_f32_16x16x32_bf16 v[74:77], v[160:163], v[208:211], v[74:77]
	v_mfma_f32_16x16x32_bf16 v[126:129], v[156:159], v[188:191], v[126:129]
	v_mfma_f32_16x16x32_bf16 v[122:125], v[164:167], v[188:191], v[122:125]
	v_mfma_f32_16x16x32_bf16 v[114:117], v[156:159], v[196:199], v[114:117]
	v_mfma_f32_16x16x32_bf16 v[106:109], v[164:167], v[196:199], v[106:109]
	v_mfma_f32_16x16x32_bf16 v[98:101], v[156:159], v[204:207], v[98:101]
	v_mfma_f32_16x16x32_bf16 v[90:93], v[164:167], v[204:207], v[90:93]
	v_mfma_f32_16x16x32_bf16 v[82:85], v[156:159], v[212:215], v[82:85]
	v_mfma_f32_16x16x32_bf16 v[74:77], v[164:167], v[212:215], v[74:77]
	v_mfma_f32_16x16x32_bf16 v[118:121], v[168:171], v[184:187], v[118:121]
	v_mfma_f32_16x16x32_bf16 v[110:113], v[176:179], v[184:187], v[110:113]
	v_mfma_f32_16x16x32_bf16 v[102:105], v[168:171], v[192:195], v[102:105]
	v_mfma_f32_16x16x32_bf16 v[94:97], v[176:179], v[192:195], v[94:97]
	v_mfma_f32_16x16x32_bf16 v[86:89], v[168:171], v[200:203], v[86:89]
	v_mfma_f32_16x16x32_bf16 v[78:81], v[176:179], v[200:203], v[78:81]
	v_mfma_f32_16x16x32_bf16 v[70:73], v[168:171], v[208:211], v[70:73]
	v_mfma_f32_16x16x32_bf16 v[66:69], v[176:179], v[208:211], v[66:69]
	v_mfma_f32_16x16x32_bf16 v[118:121], v[172:175], v[188:191], v[118:121]
	v_mfma_f32_16x16x32_bf16 v[110:113], v[180:183], v[188:191], v[110:113]
	v_mfma_f32_16x16x32_bf16 v[102:105], v[172:175], v[196:199], v[102:105]
	v_mfma_f32_16x16x32_bf16 v[94:97], v[180:183], v[196:199], v[94:97]
	v_mfma_f32_16x16x32_bf16 v[86:89], v[172:175], v[204:207], v[86:89]
	v_mfma_f32_16x16x32_bf16 v[78:81], v[180:183], v[204:207], v[78:81]
	v_mfma_f32_16x16x32_bf16 v[70:73], v[172:175], v[212:215], v[70:73]
	v_mfma_f32_16x16x32_bf16 v[66:69], v[180:183], v[212:215], v[66:69]
	s_barrier
	s_mov_b32 m0, s83
	v_lshl_add_u64 v[140:141], s[50:51], 0, v[132:133]
	ds_read_b128 v[184:187], v150 offset:16384
	ds_read_b128 v[188:191], v150 offset:17408
	ds_read_b128 v[192:195], v150 offset:18432
	ds_read_b128 v[196:199], v150 offset:19456
	ds_read_b128 v[200:203], v150 offset:20480
	ds_read_b128 v[204:207], v150 offset:21504
	ds_read_b128 v[208:211], v150 offset:22528
	ds_read_b128 v[212:215], v150 offset:23552
	global_load_lds_dwordx4 v[140:141], off
	v_lshl_add_u64 v[216:217], s[50:51], 0, v[136:137]
	s_mov_b32 m0, s79
	v_lshl_add_u64 v[218:219], s[52:53], 0, v[132:133]
	global_load_lds_dwordx4 v[216:217], off
	s_mov_b32 m0, s82
	v_lshl_add_u64 v[220:221], s[48:49], 0, v[134:135]
	global_load_lds_dwordx4 v[218:219], off
	v_lshl_add_u64 v[218:219], s[52:53], 0, v[136:137]
	s_mov_b32 m0, s81
	s_nop 0
	global_load_lds_dwordx4 v[218:219], off
	v_lshl_add_u64 v[218:219], s[48:49], 0, v[130:131]
	s_mov_b32 m0, s37
	s_nop 0
	global_load_lds_dwordx4 v[218:219], off
	s_mov_b32 m0, s58
	s_nop 0
	global_load_lds_dwordx4 v[220:221], off
	s_waitcnt vmcnt(8)
	s_waitcnt lgkmcnt(0)
	s_barrier
	v_mfma_f32_16x16x32_bf16 v[62:65], v[152:155], v[184:187], v[62:65]
	v_mfma_f32_16x16x32_bf16 v[58:61], v[160:163], v[184:187], v[58:61]
	v_mfma_f32_16x16x32_bf16 v[50:53], v[152:155], v[192:195], v[50:53]
	v_mfma_f32_16x16x32_bf16 v[42:45], v[160:163], v[192:195], v[42:45]
	v_mfma_f32_16x16x32_bf16 v[34:37], v[152:155], v[200:203], v[34:37]
	v_mfma_f32_16x16x32_bf16 v[26:29], v[160:163], v[200:203], v[26:29]
	v_mfma_f32_16x16x32_bf16 v[18:21], v[152:155], v[208:211], v[18:21]
	v_mfma_f32_16x16x32_bf16 v[10:13], v[160:163], v[208:211], v[10:13]
	v_mfma_f32_16x16x32_bf16 v[62:65], v[156:159], v[188:191], v[62:65]
	v_mfma_f32_16x16x32_bf16 v[58:61], v[164:167], v[188:191], v[58:61]
	v_mfma_f32_16x16x32_bf16 v[50:53], v[156:159], v[196:199], v[50:53]
	v_mfma_f32_16x16x32_bf16 v[42:45], v[164:167], v[196:199], v[42:45]
	v_mfma_f32_16x16x32_bf16 v[34:37], v[156:159], v[204:207], v[34:37]
	v_mfma_f32_16x16x32_bf16 v[26:29], v[164:167], v[204:207], v[26:29]
	v_mfma_f32_16x16x32_bf16 v[18:21], v[156:159], v[212:215], v[18:21]
	v_mfma_f32_16x16x32_bf16 v[10:13], v[164:167], v[212:215], v[10:13]
	v_mfma_f32_16x16x32_bf16 v[54:57], v[168:171], v[184:187], v[54:57]
	v_mfma_f32_16x16x32_bf16 v[46:49], v[176:179], v[184:187], v[46:49]
	v_mfma_f32_16x16x32_bf16 v[38:41], v[168:171], v[192:195], v[38:41]
	v_mfma_f32_16x16x32_bf16 v[30:33], v[176:179], v[192:195], v[30:33]
	v_mfma_f32_16x16x32_bf16 v[22:25], v[168:171], v[200:203], v[22:25]
	v_mfma_f32_16x16x32_bf16 v[14:17], v[176:179], v[200:203], v[14:17]
	v_mfma_f32_16x16x32_bf16 v[6:9], v[168:171], v[208:211], v[6:9]
	v_mfma_f32_16x16x32_bf16 v[2:5], v[176:179], v[208:211], v[2:5]
	v_mfma_f32_16x16x32_bf16 v[54:57], v[172:175], v[188:191], v[54:57]
	v_mfma_f32_16x16x32_bf16 v[46:49], v[180:183], v[188:191], v[46:49]
	v_mfma_f32_16x16x32_bf16 v[38:41], v[172:175], v[196:199], v[38:41]
	v_mfma_f32_16x16x32_bf16 v[30:33], v[180:183], v[196:199], v[30:33]
	v_mfma_f32_16x16x32_bf16 v[22:25], v[172:175], v[204:207], v[22:25]
	v_mfma_f32_16x16x32_bf16 v[14:17], v[180:183], v[204:207], v[14:17]
	v_mfma_f32_16x16x32_bf16 v[6:9], v[172:175], v[212:215], v[6:9]
	v_mfma_f32_16x16x32_bf16 v[2:5], v[180:183], v[212:215], v[2:5]
	s_barrier
	v_add_u32_e32 v138, s78, v146
	ds_read_b128 v[152:155], v138
	ds_read_b128 v[156:159], v138 offset:1024
	ds_read_b128 v[160:163], v138 offset:2048
	ds_read_b128 v[164:167], v138 offset:3072
	v_add_u32_e32 v138, s77, v146
	ds_read_b128 v[168:171], v138
	ds_read_b128 v[172:175], v138 offset:1024
	ds_read_b128 v[176:179], v138 offset:2048
	ds_read_b128 v[180:183], v138 offset:3072
	s_mov_b32 m0, s59
	v_lshl_add_u64 v[222:223], s[46:47], 0, v[130:131]
	ds_read_b128 v[184:187], v150 offset:32768
	ds_read_b128 v[188:191], v150 offset:33792
	ds_read_b128 v[192:195], v150 offset:34816
	ds_read_b128 v[196:199], v150 offset:35840
	ds_read_b128 v[200:203], v150 offset:36864
	ds_read_b128 v[204:207], v150 offset:37888
	ds_read_b128 v[208:211], v150 offset:38912
	ds_read_b128 v[212:215], v150 offset:39936
	global_load_lds_dwordx4 v[222:223], off
	v_lshl_add_u64 v[222:223], s[46:47], 0, v[134:135]
	s_mov_b32 m0, s60
	s_nop 0
	global_load_lds_dwordx4 v[222:223], off
	s_waitcnt vmcnt(8)
	s_waitcnt lgkmcnt(0)
	s_barrier
	v_mfma_f32_16x16x32_bf16 v[126:129], v[152:155], v[184:187], v[126:129]
	v_mfma_f32_16x16x32_bf16 v[122:125], v[160:163], v[184:187], v[122:125]
	v_mfma_f32_16x16x32_bf16 v[114:117], v[152:155], v[192:195], v[114:117]
	v_mfma_f32_16x16x32_bf16 v[106:109], v[160:163], v[192:195], v[106:109]
	v_mfma_f32_16x16x32_bf16 v[98:101], v[152:155], v[200:203], v[98:101]
	v_mfma_f32_16x16x32_bf16 v[90:93], v[160:163], v[200:203], v[90:93]
	v_mfma_f32_16x16x32_bf16 v[82:85], v[152:155], v[208:211], v[82:85]
	v_mfma_f32_16x16x32_bf16 v[74:77], v[160:163], v[208:211], v[74:77]
	v_mfma_f32_16x16x32_bf16 v[126:129], v[156:159], v[188:191], v[126:129]
	v_mfma_f32_16x16x32_bf16 v[122:125], v[164:167], v[188:191], v[122:125]
	v_mfma_f32_16x16x32_bf16 v[114:117], v[156:159], v[196:199], v[114:117]
	v_mfma_f32_16x16x32_bf16 v[106:109], v[164:167], v[196:199], v[106:109]
	v_mfma_f32_16x16x32_bf16 v[98:101], v[156:159], v[204:207], v[98:101]
	v_mfma_f32_16x16x32_bf16 v[90:93], v[164:167], v[204:207], v[90:93]
	v_mfma_f32_16x16x32_bf16 v[82:85], v[156:159], v[212:215], v[82:85]
	v_mfma_f32_16x16x32_bf16 v[74:77], v[164:167], v[212:215], v[74:77]
	v_mfma_f32_16x16x32_bf16 v[118:121], v[168:171], v[184:187], v[118:121]
	v_mfma_f32_16x16x32_bf16 v[110:113], v[176:179], v[184:187], v[110:113]
	v_mfma_f32_16x16x32_bf16 v[102:105], v[168:171], v[192:195], v[102:105]
	v_mfma_f32_16x16x32_bf16 v[94:97], v[176:179], v[192:195], v[94:97]
	v_mfma_f32_16x16x32_bf16 v[86:89], v[168:171], v[200:203], v[86:89]
	v_mfma_f32_16x16x32_bf16 v[78:81], v[176:179], v[200:203], v[78:81]
	v_mfma_f32_16x16x32_bf16 v[70:73], v[168:171], v[208:211], v[70:73]
	v_mfma_f32_16x16x32_bf16 v[66:69], v[176:179], v[208:211], v[66:69]
	v_mfma_f32_16x16x32_bf16 v[118:121], v[172:175], v[188:191], v[118:121]
	v_mfma_f32_16x16x32_bf16 v[110:113], v[180:183], v[188:191], v[110:113]
	v_mfma_f32_16x16x32_bf16 v[102:105], v[172:175], v[196:199], v[102:105]
	v_mfma_f32_16x16x32_bf16 v[94:97], v[180:183], v[196:199], v[94:97]
	v_mfma_f32_16x16x32_bf16 v[86:89], v[172:175], v[204:207], v[86:89]
	v_mfma_f32_16x16x32_bf16 v[78:81], v[180:183], v[204:207], v[78:81]
	v_mfma_f32_16x16x32_bf16 v[70:73], v[172:175], v[212:215], v[70:73]
	v_mfma_f32_16x16x32_bf16 v[66:69], v[180:183], v[212:215], v[66:69]
	s_barrier
	s_mov_b32 m0, s76
	v_lshl_add_u64 v[140:141], v[140:141], 0, s[14:15]
	ds_read_b128 v[184:187], v150 offset:49152
	ds_read_b128 v[188:191], v150 offset:50176
	ds_read_b128 v[192:195], v150 offset:51200
	ds_read_b128 v[196:199], v150 offset:52224
	ds_read_b128 v[200:203], v150 offset:53248
	ds_read_b128 v[204:207], v150 offset:54272
	ds_read_b128 v[208:211], v150 offset:55296
	ds_read_b128 v[212:215], v150 offset:56320
	global_load_lds_dwordx4 v[140:141], off
	v_lshl_add_u64 v[140:141], v[216:217], 0, s[14:15]
	s_mov_b32 m0, s72
	s_nop 0
	global_load_lds_dwordx4 v[140:141], off
	v_lshl_add_u64 v[140:141], s[44:45], 0, v[132:133]
	s_mov_b32 m0, s73
	s_nop 0
	global_load_lds_dwordx4 v[140:141], off
	v_lshl_add_u64 v[140:141], s[44:45], 0, v[136:137]
	s_mov_b32 m0, s71
	s_nop 0
	global_load_lds_dwordx4 v[140:141], off
	v_lshl_add_u64 v[140:141], v[218:219], 0, s[14:15]
	s_mov_b32 m0, s63
	s_nop 0
	global_load_lds_dwordx4 v[140:141], off
	v_lshl_add_u64 v[140:141], v[220:221], 0, s[14:15]
	s_mov_b32 m0, s64
	s_nop 0
	global_load_lds_dwordx4 v[140:141], off
	s_waitcnt vmcnt(8)
	s_waitcnt lgkmcnt(0)
	s_barrier
	v_mfma_f32_16x16x32_bf16 v[62:65], v[152:155], v[184:187], v[62:65]
	v_mfma_f32_16x16x32_bf16 v[58:61], v[160:163], v[184:187], v[58:61]
	v_mfma_f32_16x16x32_bf16 v[50:53], v[152:155], v[192:195], v[50:53]
	v_mfma_f32_16x16x32_bf16 v[42:45], v[160:163], v[192:195], v[42:45]
	v_mfma_f32_16x16x32_bf16 v[34:37], v[152:155], v[200:203], v[34:37]
	v_mfma_f32_16x16x32_bf16 v[26:29], v[160:163], v[200:203], v[26:29]
	v_mfma_f32_16x16x32_bf16 v[18:21], v[152:155], v[208:211], v[18:21]
	v_mfma_f32_16x16x32_bf16 v[10:13], v[160:163], v[208:211], v[10:13]
	v_mfma_f32_16x16x32_bf16 v[62:65], v[156:159], v[188:191], v[62:65]
	v_mfma_f32_16x16x32_bf16 v[58:61], v[164:167], v[188:191], v[58:61]
	v_mfma_f32_16x16x32_bf16 v[50:53], v[156:159], v[196:199], v[50:53]
	v_mfma_f32_16x16x32_bf16 v[42:45], v[164:167], v[196:199], v[42:45]
	v_mfma_f32_16x16x32_bf16 v[34:37], v[156:159], v[204:207], v[34:37]
	v_mfma_f32_16x16x32_bf16 v[26:29], v[164:167], v[204:207], v[26:29]
	v_mfma_f32_16x16x32_bf16 v[18:21], v[156:159], v[212:215], v[18:21]
	v_mfma_f32_16x16x32_bf16 v[10:13], v[164:167], v[212:215], v[10:13]
	v_mfma_f32_16x16x32_bf16 v[54:57], v[168:171], v[184:187], v[54:57]
	v_mfma_f32_16x16x32_bf16 v[46:49], v[176:179], v[184:187], v[46:49]
	v_mfma_f32_16x16x32_bf16 v[38:41], v[168:171], v[192:195], v[38:41]
	v_mfma_f32_16x16x32_bf16 v[30:33], v[176:179], v[192:195], v[30:33]
	v_mfma_f32_16x16x32_bf16 v[22:25], v[168:171], v[200:203], v[22:25]
	v_mfma_f32_16x16x32_bf16 v[14:17], v[176:179], v[200:203], v[14:17]
	v_mfma_f32_16x16x32_bf16 v[6:9], v[168:171], v[208:211], v[6:9]
	v_mfma_f32_16x16x32_bf16 v[2:5], v[176:179], v[208:211], v[2:5]
	v_mfma_f32_16x16x32_bf16 v[54:57], v[172:175], v[188:191], v[54:57]
	v_mfma_f32_16x16x32_bf16 v[46:49], v[180:183], v[188:191], v[46:49]
	v_mfma_f32_16x16x32_bf16 v[38:41], v[172:175], v[196:199], v[38:41]
	v_mfma_f32_16x16x32_bf16 v[30:33], v[180:183], v[196:199], v[30:33]
	v_mfma_f32_16x16x32_bf16 v[22:25], v[172:175], v[204:207], v[22:25]
	v_mfma_f32_16x16x32_bf16 v[14:17], v[180:183], v[204:207], v[14:17]
	v_mfma_f32_16x16x32_bf16 v[6:9], v[172:175], v[212:215], v[6:9]
	v_mfma_f32_16x16x32_bf16 v[2:5], v[180:183], v[212:215], v[2:5]
	s_barrier
	s_movk_i32 s46, 0x100
	s_andn2_b64 vcc, exec, s[42:43]
	s_mov_b64 s[44:45], -1
	s_mov_b64 s[42:43], 0
	s_cbranch_vccz .LBB0_1386
	s_and_b64 vcc, exec, s[16:17]
	s_cbranch_vccz .LBB0_1389
	s_barrier

.LBB0_1410:
	s_add_u32 s47, s38, s46
	s_addc_u32 s52, s39, 0
	s_add_u32 s50, s47, 0x100
	s_addc_u32 s51, s52, 0
	s_and_b64 s[48:49], s[44:45], exec
	s_cselect_b32 s49, s2, s51
	s_cselect_b32 s48, s29, s50
	s_add_u32 s46, s40, s46
	s_addc_u32 s50, s41, 0
	s_add_u32 s46, s46, 0x100
	s_addc_u32 s50, s50, 0
	s_and_b64 s[44:45], s[44:45], exec
	s_cselect_b32 s51, s27, s50
	s_cselect_b32 s50, s70, s46
	s_add_u32 s54, s47, 0x10080
	ds_read_b128 v[148:151], v143
	ds_read_b128 v[152:155], v143 offset:1024
	ds_read_b128 v[156:159], v143 offset:2048
	ds_read_b128 v[160:163], v143 offset:3072
	ds_read_b128 v[164:167], v144
	ds_read_b128 v[168:171], v144 offset:1024
	ds_read_b128 v[172:175], v144 offset:2048
	ds_read_b128 v[176:179], v144 offset:3072
	s_addc_u32 s55, s52, 0
	s_add_i32 s83, s66, s58
	s_add_i32 m0, s37, 0xc000
	s_add_i32 s84, s37, 0xe000
	s_add_i32 s79, s83, 0x2000
	s_add_u32 s52, s50, 0x10000
	s_addc_u32 s53, s51, 0
	s_add_i32 s82, s67, s58
	s_add_i32 s81, s82, 0x2000
	s_add_i32 s78, 0, 0x18000
	s_add_i32 s77, 0, 0x1c000
	s_add_u32 s46, s48, 0x10000
	s_addc_u32 s47, s49, 0
	s_add_i32 s76, s78, s58
	s_add_i32 s72, s76, 0x2000
	s_add_u32 s44, s50, 0x10080
	s_addc_u32 s45, s51, 0
	s_add_i32 s73, s77, s58
	s_add_i32 s71, s73, 0x2000
	v_lshl_add_u64 v[140:141], s[54:55], 0, v[130:131]
	ds_read_b128 v[180:183], v146
	ds_read_b128 v[184:187], v146 offset:1024
	ds_read_b128 v[188:191], v146 offset:2048
	ds_read_b128 v[192:195], v146 offset:3072
	ds_read_b128 v[196:199], v146 offset:4096
	ds_read_b128 v[200:203], v146 offset:5120
	ds_read_b128 v[204:207], v146 offset:6144
	ds_read_b128 v[208:211], v146 offset:7168
	global_load_lds_dwordx4 v[140:141], off
	v_lshl_add_u64 v[140:141], s[54:55], 0, v[134:135]
	s_mov_b32 m0, s84
	s_nop 0
	global_load_lds_dwordx4 v[140:141], off
	s_waitcnt vmcnt(8)
	s_waitcnt lgkmcnt(0)
	s_barrier
	v_mfma_f32_16x16x32_bf16 v[126:129], v[148:151], v[180:183], v[126:129]
	v_mfma_f32_16x16x32_bf16 v[122:125], v[156:159], v[180:183], v[122:125]
	v_mfma_f32_16x16x32_bf16 v[114:117], v[148:151], v[188:191], v[114:117]
	v_mfma_f32_16x16x32_bf16 v[106:109], v[156:159], v[188:191], v[106:109]
	v_mfma_f32_16x16x32_bf16 v[98:101], v[148:151], v[196:199], v[98:101]
	v_mfma_f32_16x16x32_bf16 v[90:93], v[156:159], v[196:199], v[90:93]
	v_mfma_f32_16x16x32_bf16 v[82:85], v[148:151], v[204:207], v[82:85]
	v_mfma_f32_16x16x32_bf16 v[74:77], v[156:159], v[204:207], v[74:77]
	v_mfma_f32_16x16x32_bf16 v[126:129], v[152:155], v[184:187], v[126:129]
	v_mfma_f32_16x16x32_bf16 v[122:125], v[160:163], v[184:187], v[122:125]
	v_mfma_f32_16x16x32_bf16 v[114:117], v[152:155], v[192:195], v[114:117]
	v_mfma_f32_16x16x32_bf16 v[106:109], v[160:163], v[192:195], v[106:109]
	v_mfma_f32_16x16x32_bf16 v[98:101], v[152:155], v[200:203], v[98:101]
	v_mfma_f32_16x16x32_bf16 v[90:93], v[160:163], v[200:203], v[90:93]
	v_mfma_f32_16x16x32_bf16 v[82:85], v[152:155], v[208:211], v[82:85]
	v_mfma_f32_16x16x32_bf16 v[74:77], v[160:163], v[208:211], v[74:77]
	v_mfma_f32_16x16x32_bf16 v[118:121], v[164:167], v[180:183], v[118:121]
	v_mfma_f32_16x16x32_bf16 v[110:113], v[172:175], v[180:183], v[110:113]
	v_mfma_f32_16x16x32_bf16 v[102:105], v[164:167], v[188:191], v[102:105]
	v_mfma_f32_16x16x32_bf16 v[94:97], v[172:175], v[188:191], v[94:97]
	v_mfma_f32_16x16x32_bf16 v[86:89], v[164:167], v[196:199], v[86:89]
	v_mfma_f32_16x16x32_bf16 v[78:81], v[172:175], v[196:199], v[78:81]
	v_mfma_f32_16x16x32_bf16 v[70:73], v[164:167], v[204:207], v[70:73]
	v_mfma_f32_16x16x32_bf16 v[66:69], v[172:175], v[204:207], v[66:69]
	v_mfma_f32_16x16x32_bf16 v[118:121], v[168:171], v[184:187], v[118:121]
	v_mfma_f32_16x16x32_bf16 v[110:113], v[176:179], v[184:187], v[110:113]
	v_mfma_f32_16x16x32_bf16 v[102:105], v[168:171], v[192:195], v[102:105]
	v_mfma_f32_16x16x32_bf16 v[94:97], v[176:179], v[192:195], v[94:97]
	v_mfma_f32_16x16x32_bf16 v[86:89], v[168:171], v[200:203], v[86:89]
	v_mfma_f32_16x16x32_bf16 v[78:81], v[176:179], v[200:203], v[78:81]
	v_mfma_f32_16x16x32_bf16 v[70:73], v[168:171], v[208:211], v[70:73]
	v_mfma_f32_16x16x32_bf16 v[66:69], v[176:179], v[208:211], v[66:69]
	s_barrier
	s_mov_b32 m0, s83
	v_lshl_add_u64 v[140:141], s[50:51], 0, v[132:133]
	ds_read_b128 v[180:183], v146 offset:16384
	ds_read_b128 v[184:187], v146 offset:17408
	ds_read_b128 v[188:191], v146 offset:18432
	ds_read_b128 v[192:195], v146 offset:19456
	ds_read_b128 v[196:199], v146 offset:20480
	ds_read_b128 v[200:203], v146 offset:21504
	ds_read_b128 v[204:207], v146 offset:22528
	ds_read_b128 v[208:211], v146 offset:23552
	global_load_lds_dwordx4 v[140:141], off
	v_lshl_add_u64 v[212:213], s[50:51], 0, v[136:137]
	s_mov_b32 m0, s79
	v_lshl_add_u64 v[214:215], s[52:53], 0, v[132:133]
	global_load_lds_dwordx4 v[212:213], off
	s_mov_b32 m0, s82
	v_lshl_add_u64 v[216:217], s[48:49], 0, v[134:135]
	global_load_lds_dwordx4 v[214:215], off
	v_lshl_add_u64 v[214:215], s[52:53], 0, v[136:137]
	s_mov_b32 m0, s81
	s_nop 0
	global_load_lds_dwordx4 v[214:215], off
	v_lshl_add_u64 v[214:215], s[48:49], 0, v[130:131]
	s_mov_b32 m0, s37
	s_nop 0
	global_load_lds_dwordx4 v[214:215], off
	s_mov_b32 m0, s59
	s_nop 0
	global_load_lds_dwordx4 v[216:217], off
	s_waitcnt vmcnt(8)
	s_waitcnt lgkmcnt(0)
	s_barrier
	v_mfma_f32_16x16x32_bf16 v[62:65], v[148:151], v[180:183], v[62:65]
	v_mfma_f32_16x16x32_bf16 v[58:61], v[156:159], v[180:183], v[58:61]
	v_mfma_f32_16x16x32_bf16 v[50:53], v[148:151], v[188:191], v[50:53]
	v_mfma_f32_16x16x32_bf16 v[42:45], v[156:159], v[188:191], v[42:45]
	v_mfma_f32_16x16x32_bf16 v[34:37], v[148:151], v[196:199], v[34:37]
	v_mfma_f32_16x16x32_bf16 v[26:29], v[156:159], v[196:199], v[26:29]
	v_mfma_f32_16x16x32_bf16 v[18:21], v[148:151], v[204:207], v[18:21]
	v_mfma_f32_16x16x32_bf16 v[10:13], v[156:159], v[204:207], v[10:13]
	v_mfma_f32_16x16x32_bf16 v[62:65], v[152:155], v[184:187], v[62:65]
	v_mfma_f32_16x16x32_bf16 v[58:61], v[160:163], v[184:187], v[58:61]
	v_mfma_f32_16x16x32_bf16 v[50:53], v[152:155], v[192:195], v[50:53]
	v_mfma_f32_16x16x32_bf16 v[42:45], v[160:163], v[192:195], v[42:45]
	v_mfma_f32_16x16x32_bf16 v[34:37], v[152:155], v[200:203], v[34:37]
	v_mfma_f32_16x16x32_bf16 v[26:29], v[160:163], v[200:203], v[26:29]
	v_mfma_f32_16x16x32_bf16 v[18:21], v[152:155], v[208:211], v[18:21]
	v_mfma_f32_16x16x32_bf16 v[10:13], v[160:163], v[208:211], v[10:13]
	v_mfma_f32_16x16x32_bf16 v[54:57], v[164:167], v[180:183], v[54:57]
	v_mfma_f32_16x16x32_bf16 v[46:49], v[172:175], v[180:183], v[46:49]
	v_mfma_f32_16x16x32_bf16 v[38:41], v[164:167], v[188:191], v[38:41]
	v_mfma_f32_16x16x32_bf16 v[30:33], v[172:175], v[188:191], v[30:33]
	v_mfma_f32_16x16x32_bf16 v[22:25], v[164:167], v[196:199], v[22:25]
	v_mfma_f32_16x16x32_bf16 v[14:17], v[172:175], v[196:199], v[14:17]
	v_mfma_f32_16x16x32_bf16 v[6:9], v[164:167], v[204:207], v[6:9]
	v_mfma_f32_16x16x32_bf16 v[2:5], v[172:175], v[204:207], v[2:5]
	v_mfma_f32_16x16x32_bf16 v[54:57], v[168:171], v[184:187], v[54:57]
	v_mfma_f32_16x16x32_bf16 v[46:49], v[176:179], v[184:187], v[46:49]
	v_mfma_f32_16x16x32_bf16 v[38:41], v[168:171], v[192:195], v[38:41]
	v_mfma_f32_16x16x32_bf16 v[30:33], v[176:179], v[192:195], v[30:33]
	v_mfma_f32_16x16x32_bf16 v[22:25], v[168:171], v[200:203], v[22:25]
	v_mfma_f32_16x16x32_bf16 v[14:17], v[176:179], v[200:203], v[14:17]
	v_mfma_f32_16x16x32_bf16 v[6:9], v[168:171], v[208:211], v[6:9]
	v_mfma_f32_16x16x32_bf16 v[2:5], v[176:179], v[208:211], v[2:5]
	s_barrier
	v_add_u32_e32 v138, s78, v142
	ds_read_b128 v[148:151], v138
	ds_read_b128 v[152:155], v138 offset:1024
	ds_read_b128 v[156:159], v138 offset:2048
	ds_read_b128 v[160:163], v138 offset:3072
	v_add_u32_e32 v138, s77, v142
	ds_read_b128 v[164:167], v138
	ds_read_b128 v[168:171], v138 offset:1024
	ds_read_b128 v[172:175], v138 offset:2048
	ds_read_b128 v[176:179], v138 offset:3072
	s_mov_b32 m0, s60
	v_lshl_add_u64 v[218:219], s[46:47], 0, v[130:131]
	ds_read_b128 v[180:183], v146 offset:32768
	ds_read_b128 v[184:187], v146 offset:33792
	ds_read_b128 v[188:191], v146 offset:34816
	ds_read_b128 v[192:195], v146 offset:35840
	ds_read_b128 v[196:199], v146 offset:36864
	ds_read_b128 v[200:203], v146 offset:37888
	ds_read_b128 v[204:207], v146 offset:38912
	ds_read_b128 v[208:211], v146 offset:39936
	global_load_lds_dwordx4 v[218:219], off
	v_lshl_add_u64 v[218:219], s[46:47], 0, v[134:135]
	s_mov_b32 m0, s61
	s_nop 0
	global_load_lds_dwordx4 v[218:219], off
	s_waitcnt vmcnt(8)
	s_waitcnt lgkmcnt(0)
	s_barrier
	v_mfma_f32_16x16x32_bf16 v[126:129], v[148:151], v[180:183], v[126:129]
	v_mfma_f32_16x16x32_bf16 v[122:125], v[156:159], v[180:183], v[122:125]
	v_mfma_f32_16x16x32_bf16 v[114:117], v[148:151], v[188:191], v[114:117]
	v_mfma_f32_16x16x32_bf16 v[106:109], v[156:159], v[188:191], v[106:109]
	v_mfma_f32_16x16x32_bf16 v[98:101], v[148:151], v[196:199], v[98:101]
	v_mfma_f32_16x16x32_bf16 v[90:93], v[156:159], v[196:199], v[90:93]
	v_mfma_f32_16x16x32_bf16 v[82:85], v[148:151], v[204:207], v[82:85]
	v_mfma_f32_16x16x32_bf16 v[74:77], v[156:159], v[204:207], v[74:77]
	v_mfma_f32_16x16x32_bf16 v[126:129], v[152:155], v[184:187], v[126:129]
	v_mfma_f32_16x16x32_bf16 v[122:125], v[160:163], v[184:187], v[122:125]
	v_mfma_f32_16x16x32_bf16 v[114:117], v[152:155], v[192:195], v[114:117]
	v_mfma_f32_16x16x32_bf16 v[106:109], v[160:163], v[192:195], v[106:109]
	v_mfma_f32_16x16x32_bf16 v[98:101], v[152:155], v[200:203], v[98:101]
	v_mfma_f32_16x16x32_bf16 v[90:93], v[160:163], v[200:203], v[90:93]
	v_mfma_f32_16x16x32_bf16 v[82:85], v[152:155], v[208:211], v[82:85]
	v_mfma_f32_16x16x32_bf16 v[74:77], v[160:163], v[208:211], v[74:77]
	v_mfma_f32_16x16x32_bf16 v[118:121], v[164:167], v[180:183], v[118:121]
	v_mfma_f32_16x16x32_bf16 v[110:113], v[172:175], v[180:183], v[110:113]
	v_mfma_f32_16x16x32_bf16 v[102:105], v[164:167], v[188:191], v[102:105]
	v_mfma_f32_16x16x32_bf16 v[94:97], v[172:175], v[188:191], v[94:97]
	v_mfma_f32_16x16x32_bf16 v[86:89], v[164:167], v[196:199], v[86:89]
	v_mfma_f32_16x16x32_bf16 v[78:81], v[172:175], v[196:199], v[78:81]
	v_mfma_f32_16x16x32_bf16 v[70:73], v[164:167], v[204:207], v[70:73]
	v_mfma_f32_16x16x32_bf16 v[66:69], v[172:175], v[204:207], v[66:69]
	v_mfma_f32_16x16x32_bf16 v[118:121], v[168:171], v[184:187], v[118:121]
	v_mfma_f32_16x16x32_bf16 v[110:113], v[176:179], v[184:187], v[110:113]
	v_mfma_f32_16x16x32_bf16 v[102:105], v[168:171], v[192:195], v[102:105]
	v_mfma_f32_16x16x32_bf16 v[94:97], v[176:179], v[192:195], v[94:97]
	v_mfma_f32_16x16x32_bf16 v[86:89], v[168:171], v[200:203], v[86:89]
	v_mfma_f32_16x16x32_bf16 v[78:81], v[176:179], v[200:203], v[78:81]
	v_mfma_f32_16x16x32_bf16 v[70:73], v[168:171], v[208:211], v[70:73]
	v_mfma_f32_16x16x32_bf16 v[66:69], v[176:179], v[208:211], v[66:69]
	s_barrier
	s_mov_b32 m0, s76
	v_lshl_add_u64 v[140:141], v[140:141], 0, s[14:15]
	ds_read_b128 v[180:183], v146 offset:49152
	ds_read_b128 v[184:187], v146 offset:50176
	ds_read_b128 v[188:191], v146 offset:51200
	ds_read_b128 v[192:195], v146 offset:52224
	ds_read_b128 v[196:199], v146 offset:53248
	ds_read_b128 v[200:203], v146 offset:54272
	ds_read_b128 v[204:207], v146 offset:55296
	ds_read_b128 v[208:211], v146 offset:56320
	global_load_lds_dwordx4 v[140:141], off
	v_lshl_add_u64 v[140:141], v[212:213], 0, s[14:15]
	s_mov_b32 m0, s72
	s_nop 0
	global_load_lds_dwordx4 v[140:141], off
	v_lshl_add_u64 v[140:141], s[44:45], 0, v[132:133]
	s_mov_b32 m0, s73
	s_nop 0
	global_load_lds_dwordx4 v[140:141], off
	v_lshl_add_u64 v[140:141], s[44:45], 0, v[136:137]
	s_mov_b32 m0, s71
	s_nop 0
	global_load_lds_dwordx4 v[140:141], off
	v_lshl_add_u64 v[140:141], v[214:215], 0, s[14:15]
	s_mov_b32 m0, s63
	s_nop 0
	global_load_lds_dwordx4 v[140:141], off
	v_lshl_add_u64 v[140:141], v[216:217], 0, s[14:15]
	s_mov_b32 m0, s64
	s_nop 0
	global_load_lds_dwordx4 v[140:141], off
	s_waitcnt vmcnt(8)
	s_waitcnt lgkmcnt(0)
	s_barrier
	v_mfma_f32_16x16x32_bf16 v[62:65], v[148:151], v[180:183], v[62:65]
	v_mfma_f32_16x16x32_bf16 v[58:61], v[156:159], v[180:183], v[58:61]
	v_mfma_f32_16x16x32_bf16 v[50:53], v[148:151], v[188:191], v[50:53]
	v_mfma_f32_16x16x32_bf16 v[42:45], v[156:159], v[188:191], v[42:45]
	v_mfma_f32_16x16x32_bf16 v[34:37], v[148:151], v[196:199], v[34:37]
	v_mfma_f32_16x16x32_bf16 v[26:29], v[156:159], v[196:199], v[26:29]
	v_mfma_f32_16x16x32_bf16 v[18:21], v[148:151], v[204:207], v[18:21]
	v_mfma_f32_16x16x32_bf16 v[10:13], v[156:159], v[204:207], v[10:13]
	v_mfma_f32_16x16x32_bf16 v[62:65], v[152:155], v[184:187], v[62:65]
	v_mfma_f32_16x16x32_bf16 v[58:61], v[160:163], v[184:187], v[58:61]
	v_mfma_f32_16x16x32_bf16 v[50:53], v[152:155], v[192:195], v[50:53]
	v_mfma_f32_16x16x32_bf16 v[42:45], v[160:163], v[192:195], v[42:45]
	v_mfma_f32_16x16x32_bf16 v[34:37], v[152:155], v[200:203], v[34:37]
	v_mfma_f32_16x16x32_bf16 v[26:29], v[160:163], v[200:203], v[26:29]
	v_mfma_f32_16x16x32_bf16 v[18:21], v[152:155], v[208:211], v[18:21]
	v_mfma_f32_16x16x32_bf16 v[10:13], v[160:163], v[208:211], v[10:13]
	v_mfma_f32_16x16x32_bf16 v[54:57], v[164:167], v[180:183], v[54:57]
	v_mfma_f32_16x16x32_bf16 v[46:49], v[172:175], v[180:183], v[46:49]
	v_mfma_f32_16x16x32_bf16 v[38:41], v[164:167], v[188:191], v[38:41]
	v_mfma_f32_16x16x32_bf16 v[30:33], v[172:175], v[188:191], v[30:33]
	v_mfma_f32_16x16x32_bf16 v[22:25], v[164:167], v[196:199], v[22:25]
	v_mfma_f32_16x16x32_bf16 v[14:17], v[172:175], v[196:199], v[14:17]
	v_mfma_f32_16x16x32_bf16 v[6:9], v[164:167], v[204:207], v[6:9]
	v_mfma_f32_16x16x32_bf16 v[2:5], v[172:175], v[204:207], v[2:5]
	v_mfma_f32_16x16x32_bf16 v[54:57], v[168:171], v[184:187], v[54:57]
	v_mfma_f32_16x16x32_bf16 v[46:49], v[176:179], v[184:187], v[46:49]
	v_mfma_f32_16x16x32_bf16 v[38:41], v[168:171], v[192:195], v[38:41]
	v_mfma_f32_16x16x32_bf16 v[30:33], v[176:179], v[192:195], v[30:33]
	v_mfma_f32_16x16x32_bf16 v[22:25], v[168:171], v[200:203], v[22:25]
	v_mfma_f32_16x16x32_bf16 v[14:17], v[176:179], v[200:203], v[14:17]
	v_mfma_f32_16x16x32_bf16 v[6:9], v[168:171], v[208:211], v[6:9]
	v_mfma_f32_16x16x32_bf16 v[2:5], v[176:179], v[208:211], v[2:5]
	s_barrier
	s_movk_i32 s46, 0x100
	s_andn2_b64 vcc, exec, s[42:43]
	s_mov_b64 s[44:45], -1
	s_mov_b64 s[42:43], 0
	s_cbranch_vccz .LBB0_1410
	s_and_b64 vcc, exec, s[16:17]
	s_cbranch_vccz .LBB0_1413
	s_barrier

.LBB0_2142:
	ds_read_b128 v[130:133], v199
	ds_read_b128 v[134:137], v199 offset:1024
	ds_read_b128 v[138:141], v199 offset:2048
	ds_read_b128 v[142:145], v199 offset:3072
	ds_read_b128 v[146:149], v200
	ds_read_b128 v[166:169], v200 offset:1024
	ds_read_b128 v[170:173], v200 offset:2048
	ds_read_b128 v[174:177], v200 offset:3072
	s_add_u32 s34, s30, 0xfff00080
	s_addc_u32 s35, s31, -1
	s_cmp_eq_u32 s52, 60
	s_cselect_b32 s37, s23, s35
	s_cselect_b32 s36, s48, s34
	s_cselect_b32 s35, s21, s51
	s_cselect_b32 s34, s49, s50
	v_lshl_add_u64 v[194:195], s[30:31], 0, v[158:159]
	s_add_i32 m0, s29, 0xc000
	ds_read_b128 v[178:181], v201
	ds_read_b128 v[182:185], v201 offset:1024
	ds_read_b128 v[186:189], v201 offset:2048
	ds_read_b128 v[190:193], v201 offset:3072
	ds_read_b128 v[202:205], v201 offset:4096
	ds_read_b128 v[206:209], v201 offset:5120
	ds_read_b128 v[210:213], v201 offset:6144
	ds_read_b128 v[214:217], v201 offset:7168
	global_load_lds_dwordx4 v[194:195], off
	v_lshl_add_u64 v[194:195], s[30:31], 0, v[160:161]
	s_add_i32 m0, s29, 0xe000
	s_nop 0
	global_load_lds_dwordx4 v[194:195], off
	s_waitcnt vmcnt(8)
	s_waitcnt lgkmcnt(0)
	s_barrier
	v_mfma_f32_16x16x32_bf16 v[126:129], v[130:133], v[178:181], v[126:129]
	v_mfma_f32_16x16x32_bf16 v[122:125], v[138:141], v[178:181], v[122:125]
	v_mfma_f32_16x16x32_bf16 v[118:121], v[130:133], v[186:189], v[118:121]
	v_mfma_f32_16x16x32_bf16 v[114:117], v[138:141], v[186:189], v[114:117]
	v_mfma_f32_16x16x32_bf16 v[110:113], v[130:133], v[202:205], v[110:113]
	v_mfma_f32_16x16x32_bf16 v[106:109], v[138:141], v[202:205], v[106:109]
	v_mfma_f32_16x16x32_bf16 v[102:105], v[130:133], v[210:213], v[102:105]
	v_mfma_f32_16x16x32_bf16 v[98:101], v[138:141], v[210:213], v[98:101]
	v_mfma_f32_16x16x32_bf16 v[126:129], v[134:137], v[182:185], v[126:129]
	v_mfma_f32_16x16x32_bf16 v[122:125], v[142:145], v[182:185], v[122:125]
	v_mfma_f32_16x16x32_bf16 v[118:121], v[134:137], v[190:193], v[118:121]
	v_mfma_f32_16x16x32_bf16 v[114:117], v[142:145], v[190:193], v[114:117]
	v_mfma_f32_16x16x32_bf16 v[110:113], v[134:137], v[206:209], v[110:113]
	v_mfma_f32_16x16x32_bf16 v[106:109], v[142:145], v[206:209], v[106:109]
	v_mfma_f32_16x16x32_bf16 v[102:105], v[134:137], v[214:217], v[102:105]
	v_mfma_f32_16x16x32_bf16 v[98:101], v[142:145], v[214:217], v[98:101]
	v_mfma_f32_16x16x32_bf16 v[62:65], v[146:149], v[178:181], v[62:65]
	v_mfma_f32_16x16x32_bf16 v[58:61], v[170:173], v[178:181], v[58:61]
	v_mfma_f32_16x16x32_bf16 v[54:57], v[146:149], v[186:189], v[54:57]
	v_mfma_f32_16x16x32_bf16 v[50:53], v[170:173], v[186:189], v[50:53]
	v_mfma_f32_16x16x32_bf16 v[46:49], v[146:149], v[202:205], v[46:49]
	v_mfma_f32_16x16x32_bf16 v[42:45], v[170:173], v[202:205], v[42:45]
	v_mfma_f32_16x16x32_bf16 v[38:41], v[146:149], v[210:213], v[38:41]
	v_mfma_f32_16x16x32_bf16 v[34:37], v[170:173], v[210:213], v[34:37]
	v_mfma_f32_16x16x32_bf16 v[62:65], v[166:169], v[182:185], v[62:65]
	v_mfma_f32_16x16x32_bf16 v[58:61], v[174:177], v[182:185], v[58:61]
	v_mfma_f32_16x16x32_bf16 v[54:57], v[166:169], v[190:193], v[54:57]
	v_mfma_f32_16x16x32_bf16 v[50:53], v[174:177], v[190:193], v[50:53]
	v_mfma_f32_16x16x32_bf16 v[46:49], v[166:169], v[206:209], v[46:49]
	v_mfma_f32_16x16x32_bf16 v[42:45], v[174:177], v[206:209], v[42:45]
	v_mfma_f32_16x16x32_bf16 v[38:41], v[166:169], v[214:217], v[38:41]
	v_mfma_f32_16x16x32_bf16 v[34:37], v[174:177], v[214:217], v[34:37]
	s_barrier
	s_add_i32 s53, s46, s38
	v_lshl_add_u64 v[194:195], s[34:35], 0, v[152:153]
	s_mov_b32 m0, s53
	ds_read_b128 v[178:181], v201 offset:16384
	ds_read_b128 v[182:185], v201 offset:17408
	ds_read_b128 v[186:189], v201 offset:18432
	ds_read_b128 v[190:193], v201 offset:19456
	ds_read_b128 v[202:205], v201 offset:20480
	ds_read_b128 v[206:209], v201 offset:21504
	ds_read_b128 v[210:213], v201 offset:22528
	ds_read_b128 v[214:217], v201 offset:23552
	global_load_lds_dwordx4 v[194:195], off
	s_add_i32 m0, s53, 0x2000
	s_add_u32 s54, s34, 0x100000
	v_lshl_add_u64 v[218:219], s[34:35], 0, v[156:157]
	s_addc_u32 s55, s35, 0
	s_add_i32 s53, s47, s38
	global_load_lds_dwordx4 v[218:219], off
	v_lshl_add_u64 v[220:221], s[54:55], 0, v[152:153]
	s_mov_b32 m0, s53
	v_lshl_add_u64 v[222:223], s[36:37], 0, v[154:155]
	global_load_lds_dwordx4 v[220:221], off
	v_lshl_add_u64 v[220:221], s[54:55], 0, v[156:157]
	s_add_i32 m0, s53, 0x2000
	s_nop 0
	global_load_lds_dwordx4 v[220:221], off
	v_lshl_add_u64 v[220:221], s[36:37], 0, v[150:151]
	s_mov_b32 m0, s29
	s_nop 0
	global_load_lds_dwordx4 v[220:221], off
	s_mov_b32 m0, s39
	s_nop 0
	global_load_lds_dwordx4 v[222:223], off
	s_waitcnt vmcnt(8)
	s_waitcnt lgkmcnt(0)
	s_barrier
	v_mfma_f32_16x16x32_bf16 v[94:97], v[130:133], v[178:181], v[94:97]
	v_mfma_f32_16x16x32_bf16 v[90:93], v[138:141], v[178:181], v[90:93]
	v_mfma_f32_16x16x32_bf16 v[86:89], v[130:133], v[186:189], v[86:89]
	v_mfma_f32_16x16x32_bf16 v[82:85], v[138:141], v[186:189], v[82:85]
	v_mfma_f32_16x16x32_bf16 v[78:81], v[130:133], v[202:205], v[78:81]
	v_mfma_f32_16x16x32_bf16 v[74:77], v[138:141], v[202:205], v[74:77]
	v_mfma_f32_16x16x32_bf16 v[70:73], v[130:133], v[210:213], v[70:73]
	v_mfma_f32_16x16x32_bf16 v[66:69], v[138:141], v[210:213], v[66:69]
	v_mfma_f32_16x16x32_bf16 v[94:97], v[134:137], v[182:185], v[94:97]
	v_mfma_f32_16x16x32_bf16 v[90:93], v[142:145], v[182:185], v[90:93]
	v_mfma_f32_16x16x32_bf16 v[86:89], v[134:137], v[190:193], v[86:89]
	v_mfma_f32_16x16x32_bf16 v[82:85], v[142:145], v[190:193], v[82:85]
	v_mfma_f32_16x16x32_bf16 v[78:81], v[134:137], v[206:209], v[78:81]
	v_mfma_f32_16x16x32_bf16 v[74:77], v[142:145], v[206:209], v[74:77]
	v_mfma_f32_16x16x32_bf16 v[70:73], v[134:137], v[214:217], v[70:73]
	v_mfma_f32_16x16x32_bf16 v[66:69], v[142:145], v[214:217], v[66:69]
	v_mfma_f32_16x16x32_bf16 v[30:33], v[146:149], v[178:181], v[30:33]
	v_mfma_f32_16x16x32_bf16 v[26:29], v[170:173], v[178:181], v[26:29]
	v_mfma_f32_16x16x32_bf16 v[22:25], v[146:149], v[186:189], v[22:25]
	v_mfma_f32_16x16x32_bf16 v[18:21], v[170:173], v[186:189], v[18:21]
	v_mfma_f32_16x16x32_bf16 v[14:17], v[146:149], v[202:205], v[14:17]
	v_mfma_f32_16x16x32_bf16 v[10:13], v[170:173], v[202:205], v[10:13]
	v_mfma_f32_16x16x32_bf16 v[6:9], v[146:149], v[210:213], v[6:9]
	v_mfma_f32_16x16x32_bf16 v[2:5], v[170:173], v[210:213], v[2:5]
	v_mfma_f32_16x16x32_bf16 v[30:33], v[166:169], v[182:185], v[30:33]
	v_mfma_f32_16x16x32_bf16 v[26:29], v[174:177], v[182:185], v[26:29]
	v_mfma_f32_16x16x32_bf16 v[22:25], v[166:169], v[190:193], v[22:25]
	v_mfma_f32_16x16x32_bf16 v[18:21], v[174:177], v[190:193], v[18:21]
	v_mfma_f32_16x16x32_bf16 v[14:17], v[166:169], v[206:209], v[14:17]
	v_mfma_f32_16x16x32_bf16 v[10:13], v[174:177], v[206:209], v[10:13]
	v_mfma_f32_16x16x32_bf16 v[6:9], v[166:169], v[214:217], v[6:9]
	v_mfma_f32_16x16x32_bf16 v[2:5], v[174:177], v[214:217], v[2:5]
	s_barrier
	s_add_i32 s53, 0, 0x18000
	s_add_i32 s54, 0, 0x1c000
	v_add_u32_e32 v142, s53, v197
	v_add_u32_e32 v174, s54, v197
	ds_read_b128 v[130:133], v142
	ds_read_b128 v[134:137], v142 offset:1024
	ds_read_b128 v[138:141], v142 offset:2048
	ds_read_b128 v[142:145], v142 offset:3072
	ds_read_b128 v[146:149], v174
	ds_read_b128 v[166:169], v174 offset:1024
	ds_read_b128 v[170:173], v174 offset:2048
	ds_read_b128 v[174:177], v174 offset:3072
	s_add_u32 s36, s36, 0x100000
	s_addc_u32 s37, s37, 0
	s_mov_b32 m0, s40
	v_lshl_add_u64 v[224:225], s[36:37], 0, v[150:151]
	ds_read_b128 v[178:181], v201 offset:32768
	ds_read_b128 v[182:185], v201 offset:33792
	ds_read_b128 v[186:189], v201 offset:34816
	ds_read_b128 v[190:193], v201 offset:35840
	ds_read_b128 v[202:205], v201 offset:36864
	ds_read_b128 v[206:209], v201 offset:37888
	ds_read_b128 v[210:213], v201 offset:38912
	ds_read_b128 v[214:217], v201 offset:39936
	global_load_lds_dwordx4 v[224:225], off
	v_lshl_add_u64 v[224:225], s[36:37], 0, v[154:155]
	s_mov_b32 m0, s41
	s_nop 0
	global_load_lds_dwordx4 v[224:225], off
	s_waitcnt vmcnt(8)
	s_waitcnt lgkmcnt(0)
	s_barrier
	v_mfma_f32_16x16x32_bf16 v[126:129], v[130:133], v[178:181], v[126:129]
	v_mfma_f32_16x16x32_bf16 v[122:125], v[138:141], v[178:181], v[122:125]
	v_mfma_f32_16x16x32_bf16 v[118:121], v[130:133], v[186:189], v[118:121]
	v_mfma_f32_16x16x32_bf16 v[114:117], v[138:141], v[186:189], v[114:117]
	v_mfma_f32_16x16x32_bf16 v[110:113], v[130:133], v[202:205], v[110:113]
	v_mfma_f32_16x16x32_bf16 v[106:109], v[138:141], v[202:205], v[106:109]
	v_mfma_f32_16x16x32_bf16 v[102:105], v[130:133], v[210:213], v[102:105]
	v_mfma_f32_16x16x32_bf16 v[98:101], v[138:141], v[210:213], v[98:101]
	v_mfma_f32_16x16x32_bf16 v[126:129], v[134:137], v[182:185], v[126:129]
	v_mfma_f32_16x16x32_bf16 v[122:125], v[142:145], v[182:185], v[122:125]
	v_mfma_f32_16x16x32_bf16 v[118:121], v[134:137], v[190:193], v[118:121]
	v_mfma_f32_16x16x32_bf16 v[114:117], v[142:145], v[190:193], v[114:117]
	v_mfma_f32_16x16x32_bf16 v[110:113], v[134:137], v[206:209], v[110:113]
	v_mfma_f32_16x16x32_bf16 v[106:109], v[142:145], v[206:209], v[106:109]
	v_mfma_f32_16x16x32_bf16 v[102:105], v[134:137], v[214:217], v[102:105]
	v_mfma_f32_16x16x32_bf16 v[98:101], v[142:145], v[214:217], v[98:101]
	v_mfma_f32_16x16x32_bf16 v[62:65], v[146:149], v[178:181], v[62:65]
	v_mfma_f32_16x16x32_bf16 v[58:61], v[170:173], v[178:181], v[58:61]
	v_mfma_f32_16x16x32_bf16 v[54:57], v[146:149], v[186:189], v[54:57]
	v_mfma_f32_16x16x32_bf16 v[50:53], v[170:173], v[186:189], v[50:53]
	v_mfma_f32_16x16x32_bf16 v[46:49], v[146:149], v[202:205], v[46:49]
	v_mfma_f32_16x16x32_bf16 v[42:45], v[170:173], v[202:205], v[42:45]
	v_mfma_f32_16x16x32_bf16 v[38:41], v[146:149], v[210:213], v[38:41]
	v_mfma_f32_16x16x32_bf16 v[34:37], v[170:173], v[210:213], v[34:37]
	v_mfma_f32_16x16x32_bf16 v[62:65], v[166:169], v[182:185], v[62:65]
	v_mfma_f32_16x16x32_bf16 v[58:61], v[174:177], v[182:185], v[58:61]
	v_mfma_f32_16x16x32_bf16 v[54:57], v[166:169], v[190:193], v[54:57]
	v_mfma_f32_16x16x32_bf16 v[50:53], v[174:177], v[190:193], v[50:53]
	v_mfma_f32_16x16x32_bf16 v[46:49], v[166:169], v[206:209], v[46:49]
	v_mfma_f32_16x16x32_bf16 v[42:45], v[174:177], v[206:209], v[42:45]
	v_mfma_f32_16x16x32_bf16 v[38:41], v[166:169], v[214:217], v[38:41]
	v_mfma_f32_16x16x32_bf16 v[34:37], v[174:177], v[214:217], v[34:37]
	s_barrier
	s_add_i32 s36, s53, s38
	v_lshl_add_u64 v[194:195], v[194:195], 0, s[14:15]
	s_mov_b32 m0, s36
	ds_read_b128 v[178:181], v201 offset:49152
	ds_read_b128 v[182:185], v201 offset:50176
	ds_read_b128 v[186:189], v201 offset:51200
	ds_read_b128 v[190:193], v201 offset:52224
	ds_read_b128 v[202:205], v201 offset:53248
	ds_read_b128 v[206:209], v201 offset:54272
	ds_read_b128 v[210:213], v201 offset:55296
	ds_read_b128 v[214:217], v201 offset:56320
	global_load_lds_dwordx4 v[194:195], off
	s_add_i32 m0, s36, 0x2000
	s_add_u32 s34, s34, 0x100080
	v_lshl_add_u64 v[194:195], v[218:219], 0, s[14:15]
	s_addc_u32 s35, s35, 0
	s_add_i32 s36, s54, s38
	global_load_lds_dwordx4 v[194:195], off
	v_lshl_add_u64 v[194:195], s[34:35], 0, v[152:153]
	s_mov_b32 m0, s36
	s_nop 0
	global_load_lds_dwordx4 v[194:195], off
	v_lshl_add_u64 v[194:195], s[34:35], 0, v[156:157]
	s_add_i32 m0, s36, 0x2000
	s_nop 0
	global_load_lds_dwordx4 v[194:195], off
	v_lshl_add_u64 v[194:195], v[220:221], 0, s[14:15]
	s_mov_b32 m0, s43
	s_nop 0
	global_load_lds_dwordx4 v[194:195], off
	v_lshl_add_u64 v[194:195], v[222:223], 0, s[14:15]
	s_mov_b32 m0, s44
	s_nop 0
	global_load_lds_dwordx4 v[194:195], off
	s_waitcnt vmcnt(8)
	s_waitcnt lgkmcnt(0)
	s_barrier
	v_mfma_f32_16x16x32_bf16 v[94:97], v[130:133], v[178:181], v[94:97]
	v_mfma_f32_16x16x32_bf16 v[90:93], v[138:141], v[178:181], v[90:93]
	v_mfma_f32_16x16x32_bf16 v[86:89], v[130:133], v[186:189], v[86:89]
	v_mfma_f32_16x16x32_bf16 v[82:85], v[138:141], v[186:189], v[82:85]
	v_mfma_f32_16x16x32_bf16 v[78:81], v[130:133], v[202:205], v[78:81]
	v_mfma_f32_16x16x32_bf16 v[74:77], v[138:141], v[202:205], v[74:77]
	v_mfma_f32_16x16x32_bf16 v[70:73], v[130:133], v[210:213], v[70:73]
	v_mfma_f32_16x16x32_bf16 v[66:69], v[138:141], v[210:213], v[66:69]
	v_mfma_f32_16x16x32_bf16 v[94:97], v[134:137], v[182:185], v[94:97]
	v_mfma_f32_16x16x32_bf16 v[90:93], v[142:145], v[182:185], v[90:93]
	v_mfma_f32_16x16x32_bf16 v[86:89], v[134:137], v[190:193], v[86:89]
	v_mfma_f32_16x16x32_bf16 v[82:85], v[142:145], v[190:193], v[82:85]
	v_mfma_f32_16x16x32_bf16 v[78:81], v[134:137], v[206:209], v[78:81]
	v_mfma_f32_16x16x32_bf16 v[74:77], v[142:145], v[206:209], v[74:77]
	v_mfma_f32_16x16x32_bf16 v[70:73], v[134:137], v[214:217], v[70:73]
	v_mfma_f32_16x16x32_bf16 v[66:69], v[142:145], v[214:217], v[66:69]
	v_mfma_f32_16x16x32_bf16 v[30:33], v[146:149], v[178:181], v[30:33]
	v_mfma_f32_16x16x32_bf16 v[26:29], v[170:173], v[178:181], v[26:29]
	v_mfma_f32_16x16x32_bf16 v[22:25], v[146:149], v[186:189], v[22:25]
	v_mfma_f32_16x16x32_bf16 v[18:21], v[170:173], v[186:189], v[18:21]
	v_mfma_f32_16x16x32_bf16 v[14:17], v[146:149], v[202:205], v[14:17]
	v_mfma_f32_16x16x32_bf16 v[10:13], v[170:173], v[202:205], v[10:13]
	v_mfma_f32_16x16x32_bf16 v[6:9], v[146:149], v[210:213], v[6:9]
	v_mfma_f32_16x16x32_bf16 v[2:5], v[170:173], v[210:213], v[2:5]
	v_mfma_f32_16x16x32_bf16 v[30:33], v[166:169], v[182:185], v[30:33]
	v_mfma_f32_16x16x32_bf16 v[26:29], v[174:177], v[182:185], v[26:29]
	v_mfma_f32_16x16x32_bf16 v[22:25], v[166:169], v[190:193], v[22:25]
	v_mfma_f32_16x16x32_bf16 v[18:21], v[174:177], v[190:193], v[18:21]
	v_mfma_f32_16x16x32_bf16 v[14:17], v[166:169], v[206:209], v[14:17]
	v_mfma_f32_16x16x32_bf16 v[10:13], v[174:177], v[206:209], v[10:13]
	v_mfma_f32_16x16x32_bf16 v[6:9], v[166:169], v[214:217], v[6:9]
	v_mfma_f32_16x16x32_bf16 v[2:5], v[174:177], v[214:217], v[2:5]
	s_barrier
	s_add_i32 s52, s52, 2
	s_add_u32 s30, s30, 0x100
	s_addc_u32 s31, s31, 0
	s_add_u32 s50, s50, 0x100
	s_addc_u32 s51, s51, 0
	s_cmp_gt_u32 s52, 61
	s_cbranch_scc0 .LBB0_2142
	s_and_b64 vcc, exec, s[16:17]
	s_cbranch_vccz .LBB0_2145
	s_barrier

.LBB0_2369:
	ds_read_b128 v[130:133], v197
	ds_read_b128 v[134:137], v197 offset:1024
	ds_read_b128 v[138:141], v197 offset:2048
	ds_read_b128 v[142:145], v197 offset:3072
	ds_read_b128 v[146:149], v198
	ds_read_b128 v[166:169], v198 offset:1024
	ds_read_b128 v[170:173], v198 offset:2048
	ds_read_b128 v[174:177], v198 offset:3072
	s_add_u32 s28, s26, 0xffd50080
	s_addc_u32 s29, s27, -1
	s_cmpk_eq_i32 s52, 0xa8
	s_cselect_b32 s31, s9, s29
	s_cselect_b32 s30, s8, s28
	s_cselect_b32 s29, s25, s51
	s_cselect_b32 s28, s24, s50
	v_lshl_add_u64 v[216:217], s[26:27], 0, v[158:159]
	s_add_i32 m0, s37, 0xc000
	ds_read_b128 v[178:181], v199
	ds_read_b128 v[182:185], v199 offset:1024
	ds_read_b128 v[186:189], v199 offset:2048
	ds_read_b128 v[190:193], v199 offset:3072
	ds_read_b128 v[200:203], v199 offset:4096
	ds_read_b128 v[204:207], v199 offset:5120
	ds_read_b128 v[208:211], v199 offset:6144
	ds_read_b128 v[212:215], v199 offset:7168
	global_load_lds_dwordx4 v[216:217], off
	v_lshl_add_u64 v[216:217], s[26:27], 0, v[160:161]
	s_add_i32 m0, s37, 0xe000
	s_nop 0
	global_load_lds_dwordx4 v[216:217], off
	s_waitcnt vmcnt(8)
	s_waitcnt lgkmcnt(0)
	s_barrier
	v_mfma_f32_16x16x32_bf16 v[126:129], v[130:133], v[178:181], v[126:129]
	v_mfma_f32_16x16x32_bf16 v[122:125], v[138:141], v[178:181], v[122:125]
	v_mfma_f32_16x16x32_bf16 v[118:121], v[130:133], v[186:189], v[118:121]
	v_mfma_f32_16x16x32_bf16 v[114:117], v[138:141], v[186:189], v[114:117]
	v_mfma_f32_16x16x32_bf16 v[110:113], v[130:133], v[200:203], v[110:113]
	v_mfma_f32_16x16x32_bf16 v[106:109], v[138:141], v[200:203], v[106:109]
	v_mfma_f32_16x16x32_bf16 v[102:105], v[130:133], v[208:211], v[102:105]
	v_mfma_f32_16x16x32_bf16 v[98:101], v[138:141], v[208:211], v[98:101]
	v_mfma_f32_16x16x32_bf16 v[126:129], v[134:137], v[182:185], v[126:129]
	v_mfma_f32_16x16x32_bf16 v[122:125], v[142:145], v[182:185], v[122:125]
	v_mfma_f32_16x16x32_bf16 v[118:121], v[134:137], v[190:193], v[118:121]
	v_mfma_f32_16x16x32_bf16 v[114:117], v[142:145], v[190:193], v[114:117]
	v_mfma_f32_16x16x32_bf16 v[110:113], v[134:137], v[204:207], v[110:113]
	v_mfma_f32_16x16x32_bf16 v[106:109], v[142:145], v[204:207], v[106:109]
	v_mfma_f32_16x16x32_bf16 v[102:105], v[134:137], v[212:215], v[102:105]
	v_mfma_f32_16x16x32_bf16 v[98:101], v[142:145], v[212:215], v[98:101]
	v_mfma_f32_16x16x32_bf16 v[62:65], v[146:149], v[178:181], v[62:65]
	v_mfma_f32_16x16x32_bf16 v[58:61], v[170:173], v[178:181], v[58:61]
	v_mfma_f32_16x16x32_bf16 v[54:57], v[146:149], v[186:189], v[54:57]
	v_mfma_f32_16x16x32_bf16 v[50:53], v[170:173], v[186:189], v[50:53]
	v_mfma_f32_16x16x32_bf16 v[46:49], v[146:149], v[200:203], v[46:49]
	v_mfma_f32_16x16x32_bf16 v[42:45], v[170:173], v[200:203], v[42:45]
	v_mfma_f32_16x16x32_bf16 v[38:41], v[146:149], v[208:211], v[38:41]
	v_mfma_f32_16x16x32_bf16 v[34:37], v[170:173], v[208:211], v[34:37]
	v_mfma_f32_16x16x32_bf16 v[62:65], v[166:169], v[182:185], v[62:65]
	v_mfma_f32_16x16x32_bf16 v[58:61], v[174:177], v[182:185], v[58:61]
	v_mfma_f32_16x16x32_bf16 v[54:57], v[166:169], v[190:193], v[54:57]
	v_mfma_f32_16x16x32_bf16 v[50:53], v[174:177], v[190:193], v[50:53]
	v_mfma_f32_16x16x32_bf16 v[46:49], v[166:169], v[204:207], v[46:49]
	v_mfma_f32_16x16x32_bf16 v[42:45], v[174:177], v[204:207], v[42:45]
	v_mfma_f32_16x16x32_bf16 v[38:41], v[166:169], v[212:215], v[38:41]
	v_mfma_f32_16x16x32_bf16 v[34:37], v[174:177], v[212:215], v[34:37]
	s_barrier
	s_add_i32 s53, s45, s36
	v_lshl_add_u64 v[216:217], s[28:29], 0, v[152:153]
	s_mov_b32 m0, s53
	ds_read_b128 v[178:181], v199 offset:16384
	ds_read_b128 v[182:185], v199 offset:17408
	ds_read_b128 v[186:189], v199 offset:18432
	ds_read_b128 v[190:193], v199 offset:19456
	ds_read_b128 v[200:203], v199 offset:20480
	ds_read_b128 v[204:207], v199 offset:21504
	ds_read_b128 v[208:211], v199 offset:22528
	ds_read_b128 v[212:215], v199 offset:23552
	global_load_lds_dwordx4 v[216:217], off
	s_add_i32 m0, s53, 0x2000
	s_add_u32 s54, s28, 0x2b0000
	v_lshl_add_u64 v[218:219], s[28:29], 0, v[156:157]
	s_addc_u32 s55, s29, 0
	s_add_i32 s53, s46, s36
	global_load_lds_dwordx4 v[218:219], off
	v_lshl_add_u64 v[220:221], s[54:55], 0, v[152:153]
	s_mov_b32 m0, s53
	v_lshl_add_u64 v[222:223], s[30:31], 0, v[154:155]
	global_load_lds_dwordx4 v[220:221], off
	v_lshl_add_u64 v[220:221], s[54:55], 0, v[156:157]
	s_add_i32 m0, s53, 0x2000
	s_nop 0
	global_load_lds_dwordx4 v[220:221], off
	v_lshl_add_u64 v[220:221], s[30:31], 0, v[150:151]
	s_mov_b32 m0, s37
	s_nop 0
	global_load_lds_dwordx4 v[220:221], off
	s_mov_b32 m0, s38
	s_nop 0
	global_load_lds_dwordx4 v[222:223], off
	s_waitcnt vmcnt(8)
	s_waitcnt lgkmcnt(0)
	s_barrier
	v_mfma_f32_16x16x32_bf16 v[94:97], v[130:133], v[178:181], v[94:97]
	v_mfma_f32_16x16x32_bf16 v[90:93], v[138:141], v[178:181], v[90:93]
	v_mfma_f32_16x16x32_bf16 v[86:89], v[130:133], v[186:189], v[86:89]
	v_mfma_f32_16x16x32_bf16 v[82:85], v[138:141], v[186:189], v[82:85]
	v_mfma_f32_16x16x32_bf16 v[78:81], v[130:133], v[200:203], v[78:81]
	v_mfma_f32_16x16x32_bf16 v[74:77], v[138:141], v[200:203], v[74:77]
	v_mfma_f32_16x16x32_bf16 v[70:73], v[130:133], v[208:211], v[70:73]
	v_mfma_f32_16x16x32_bf16 v[66:69], v[138:141], v[208:211], v[66:69]
	v_mfma_f32_16x16x32_bf16 v[94:97], v[134:137], v[182:185], v[94:97]
	v_mfma_f32_16x16x32_bf16 v[90:93], v[142:145], v[182:185], v[90:93]
	v_mfma_f32_16x16x32_bf16 v[86:89], v[134:137], v[190:193], v[86:89]
	v_mfma_f32_16x16x32_bf16 v[82:85], v[142:145], v[190:193], v[82:85]
	v_mfma_f32_16x16x32_bf16 v[78:81], v[134:137], v[204:207], v[78:81]
	v_mfma_f32_16x16x32_bf16 v[74:77], v[142:145], v[204:207], v[74:77]
	v_mfma_f32_16x16x32_bf16 v[70:73], v[134:137], v[212:215], v[70:73]
	v_mfma_f32_16x16x32_bf16 v[66:69], v[142:145], v[212:215], v[66:69]
	v_mfma_f32_16x16x32_bf16 v[30:33], v[146:149], v[178:181], v[30:33]
	v_mfma_f32_16x16x32_bf16 v[26:29], v[170:173], v[178:181], v[26:29]
	v_mfma_f32_16x16x32_bf16 v[22:25], v[146:149], v[186:189], v[22:25]
	v_mfma_f32_16x16x32_bf16 v[18:21], v[170:173], v[186:189], v[18:21]
	v_mfma_f32_16x16x32_bf16 v[14:17], v[146:149], v[200:203], v[14:17]
	v_mfma_f32_16x16x32_bf16 v[10:13], v[170:173], v[200:203], v[10:13]
	v_mfma_f32_16x16x32_bf16 v[6:9], v[146:149], v[208:211], v[6:9]
	v_mfma_f32_16x16x32_bf16 v[2:5], v[170:173], v[208:211], v[2:5]
	v_mfma_f32_16x16x32_bf16 v[30:33], v[166:169], v[182:185], v[30:33]
	v_mfma_f32_16x16x32_bf16 v[26:29], v[174:177], v[182:185], v[26:29]
	v_mfma_f32_16x16x32_bf16 v[22:25], v[166:169], v[190:193], v[22:25]
	v_mfma_f32_16x16x32_bf16 v[18:21], v[174:177], v[190:193], v[18:21]
	v_mfma_f32_16x16x32_bf16 v[14:17], v[166:169], v[204:207], v[14:17]
	v_mfma_f32_16x16x32_bf16 v[10:13], v[174:177], v[204:207], v[10:13]
	v_mfma_f32_16x16x32_bf16 v[6:9], v[166:169], v[212:215], v[6:9]
	v_mfma_f32_16x16x32_bf16 v[2:5], v[174:177], v[212:215], v[2:5]
	s_barrier
	s_add_i32 s53, 0, 0x18000
	s_add_i32 s54, 0, 0x1c000
	v_add_u32_e32 v142, s53, v195
	v_add_u32_e32 v174, s54, v195
	ds_read_b128 v[130:133], v142
	ds_read_b128 v[134:137], v142 offset:1024
	ds_read_b128 v[138:141], v142 offset:2048
	ds_read_b128 v[142:145], v142 offset:3072
	ds_read_b128 v[146:149], v174
	ds_read_b128 v[166:169], v174 offset:1024
	ds_read_b128 v[170:173], v174 offset:2048
	ds_read_b128 v[174:177], v174 offset:3072
	s_add_u32 s30, s30, 0x2b0000
	s_addc_u32 s31, s31, 0
	s_mov_b32 m0, s39
	v_lshl_add_u64 v[224:225], s[30:31], 0, v[150:151]
	ds_read_b128 v[178:181], v199 offset:32768
	ds_read_b128 v[182:185], v199 offset:33792
	ds_read_b128 v[186:189], v199 offset:34816
	ds_read_b128 v[190:193], v199 offset:35840
	ds_read_b128 v[200:203], v199 offset:36864
	ds_read_b128 v[204:207], v199 offset:37888
	ds_read_b128 v[208:211], v199 offset:38912
	ds_read_b128 v[212:215], v199 offset:39936
	global_load_lds_dwordx4 v[224:225], off
	v_lshl_add_u64 v[224:225], s[30:31], 0, v[154:155]
	s_mov_b32 m0, s40
	s_nop 0
	global_load_lds_dwordx4 v[224:225], off
	s_waitcnt vmcnt(8)
	s_waitcnt lgkmcnt(0)
	s_barrier
	v_mfma_f32_16x16x32_bf16 v[126:129], v[130:133], v[178:181], v[126:129]
	v_mfma_f32_16x16x32_bf16 v[122:125], v[138:141], v[178:181], v[122:125]
	v_mfma_f32_16x16x32_bf16 v[118:121], v[130:133], v[186:189], v[118:121]
	v_mfma_f32_16x16x32_bf16 v[114:117], v[138:141], v[186:189], v[114:117]
	v_mfma_f32_16x16x32_bf16 v[110:113], v[130:133], v[200:203], v[110:113]
	v_mfma_f32_16x16x32_bf16 v[106:109], v[138:141], v[200:203], v[106:109]
	v_mfma_f32_16x16x32_bf16 v[102:105], v[130:133], v[208:211], v[102:105]
	v_mfma_f32_16x16x32_bf16 v[98:101], v[138:141], v[208:211], v[98:101]
	v_mfma_f32_16x16x32_bf16 v[126:129], v[134:137], v[182:185], v[126:129]
	v_mfma_f32_16x16x32_bf16 v[122:125], v[142:145], v[182:185], v[122:125]
	v_mfma_f32_16x16x32_bf16 v[118:121], v[134:137], v[190:193], v[118:121]
	v_mfma_f32_16x16x32_bf16 v[114:117], v[142:145], v[190:193], v[114:117]
	v_mfma_f32_16x16x32_bf16 v[110:113], v[134:137], v[204:207], v[110:113]
	v_mfma_f32_16x16x32_bf16 v[106:109], v[142:145], v[204:207], v[106:109]
	v_mfma_f32_16x16x32_bf16 v[102:105], v[134:137], v[212:215], v[102:105]
	v_mfma_f32_16x16x32_bf16 v[98:101], v[142:145], v[212:215], v[98:101]
	v_mfma_f32_16x16x32_bf16 v[62:65], v[146:149], v[178:181], v[62:65]
	v_mfma_f32_16x16x32_bf16 v[58:61], v[170:173], v[178:181], v[58:61]
	v_mfma_f32_16x16x32_bf16 v[54:57], v[146:149], v[186:189], v[54:57]
	v_mfma_f32_16x16x32_bf16 v[50:53], v[170:173], v[186:189], v[50:53]
	v_mfma_f32_16x16x32_bf16 v[46:49], v[146:149], v[200:203], v[46:49]
	v_mfma_f32_16x16x32_bf16 v[42:45], v[170:173], v[200:203], v[42:45]
	v_mfma_f32_16x16x32_bf16 v[38:41], v[146:149], v[208:211], v[38:41]
	v_mfma_f32_16x16x32_bf16 v[34:37], v[170:173], v[208:211], v[34:37]
	v_mfma_f32_16x16x32_bf16 v[62:65], v[166:169], v[182:185], v[62:65]
	v_mfma_f32_16x16x32_bf16 v[58:61], v[174:177], v[182:185], v[58:61]
	v_mfma_f32_16x16x32_bf16 v[54:57], v[166:169], v[190:193], v[54:57]
	v_mfma_f32_16x16x32_bf16 v[50:53], v[174:177], v[190:193], v[50:53]
	v_mfma_f32_16x16x32_bf16 v[46:49], v[166:169], v[204:207], v[46:49]
	v_mfma_f32_16x16x32_bf16 v[42:45], v[174:177], v[204:207], v[42:45]
	v_mfma_f32_16x16x32_bf16 v[38:41], v[166:169], v[212:215], v[38:41]
	v_mfma_f32_16x16x32_bf16 v[34:37], v[174:177], v[212:215], v[34:37]
	s_barrier
	s_add_i32 s30, s53, s36
	v_lshl_add_u64 v[216:217], v[216:217], 0, s[18:19]
	s_mov_b32 m0, s30
	ds_read_b128 v[178:181], v199 offset:49152
	ds_read_b128 v[182:185], v199 offset:50176
	ds_read_b128 v[186:189], v199 offset:51200
	ds_read_b128 v[190:193], v199 offset:52224
	ds_read_b128 v[200:203], v199 offset:53248
	ds_read_b128 v[204:207], v199 offset:54272
	ds_read_b128 v[208:211], v199 offset:55296
	ds_read_b128 v[212:215], v199 offset:56320
	global_load_lds_dwordx4 v[216:217], off
	s_add_i32 m0, s30, 0x2000
	s_add_u32 s28, s28, 0x2b0080
	v_lshl_add_u64 v[216:217], v[218:219], 0, s[18:19]
	s_addc_u32 s29, s29, 0
	s_add_i32 s30, s54, s36
	global_load_lds_dwordx4 v[216:217], off
	v_lshl_add_u64 v[216:217], s[28:29], 0, v[152:153]
	s_mov_b32 m0, s30
	s_nop 0
	global_load_lds_dwordx4 v[216:217], off
	v_lshl_add_u64 v[216:217], s[28:29], 0, v[156:157]
	s_add_i32 m0, s30, 0x2000
	s_nop 0
	global_load_lds_dwordx4 v[216:217], off
	v_lshl_add_u64 v[216:217], v[220:221], 0, s[18:19]
	s_mov_b32 m0, s42
	s_nop 0
	global_load_lds_dwordx4 v[216:217], off
	v_lshl_add_u64 v[216:217], v[222:223], 0, s[18:19]
	s_mov_b32 m0, s43
	s_nop 0
	global_load_lds_dwordx4 v[216:217], off
	s_waitcnt vmcnt(8)
	s_waitcnt lgkmcnt(0)
	s_barrier
	v_mfma_f32_16x16x32_bf16 v[94:97], v[130:133], v[178:181], v[94:97]
	v_mfma_f32_16x16x32_bf16 v[90:93], v[138:141], v[178:181], v[90:93]
	v_mfma_f32_16x16x32_bf16 v[86:89], v[130:133], v[186:189], v[86:89]
	v_mfma_f32_16x16x32_bf16 v[82:85], v[138:141], v[186:189], v[82:85]
	v_mfma_f32_16x16x32_bf16 v[78:81], v[130:133], v[200:203], v[78:81]
	v_mfma_f32_16x16x32_bf16 v[74:77], v[138:141], v[200:203], v[74:77]
	v_mfma_f32_16x16x32_bf16 v[70:73], v[130:133], v[208:211], v[70:73]
	v_mfma_f32_16x16x32_bf16 v[66:69], v[138:141], v[208:211], v[66:69]
	v_mfma_f32_16x16x32_bf16 v[94:97], v[134:137], v[182:185], v[94:97]
	v_mfma_f32_16x16x32_bf16 v[90:93], v[142:145], v[182:185], v[90:93]
	v_mfma_f32_16x16x32_bf16 v[86:89], v[134:137], v[190:193], v[86:89]
	v_mfma_f32_16x16x32_bf16 v[82:85], v[142:145], v[190:193], v[82:85]
	v_mfma_f32_16x16x32_bf16 v[78:81], v[134:137], v[204:207], v[78:81]
	v_mfma_f32_16x16x32_bf16 v[74:77], v[142:145], v[204:207], v[74:77]
	v_mfma_f32_16x16x32_bf16 v[70:73], v[134:137], v[212:215], v[70:73]
	v_mfma_f32_16x16x32_bf16 v[66:69], v[142:145], v[212:215], v[66:69]
	v_mfma_f32_16x16x32_bf16 v[30:33], v[146:149], v[178:181], v[30:33]
	v_mfma_f32_16x16x32_bf16 v[26:29], v[170:173], v[178:181], v[26:29]
	v_mfma_f32_16x16x32_bf16 v[22:25], v[146:149], v[186:189], v[22:25]
	v_mfma_f32_16x16x32_bf16 v[18:21], v[170:173], v[186:189], v[18:21]
	v_mfma_f32_16x16x32_bf16 v[14:17], v[146:149], v[200:203], v[14:17]
	v_mfma_f32_16x16x32_bf16 v[10:13], v[170:173], v[200:203], v[10:13]
	v_mfma_f32_16x16x32_bf16 v[6:9], v[146:149], v[208:211], v[6:9]
	v_mfma_f32_16x16x32_bf16 v[2:5], v[170:173], v[208:211], v[2:5]
	v_mfma_f32_16x16x32_bf16 v[30:33], v[166:169], v[182:185], v[30:33]
	v_mfma_f32_16x16x32_bf16 v[26:29], v[174:177], v[182:185], v[26:29]
	v_mfma_f32_16x16x32_bf16 v[22:25], v[166:169], v[190:193], v[22:25]
	v_mfma_f32_16x16x32_bf16 v[18:21], v[174:177], v[190:193], v[18:21]
	v_mfma_f32_16x16x32_bf16 v[14:17], v[166:169], v[204:207], v[14:17]
	v_mfma_f32_16x16x32_bf16 v[10:13], v[174:177], v[204:207], v[10:13]
	v_mfma_f32_16x16x32_bf16 v[6:9], v[166:169], v[212:215], v[6:9]
	v_mfma_f32_16x16x32_bf16 v[2:5], v[174:177], v[212:215], v[2:5]
	s_barrier
	s_add_i32 s52, s52, 2
	s_add_u32 s26, s26, 0x100
	s_addc_u32 s27, s27, 0
	s_add_u32 s50, s50, 0x100
	s_addc_u32 s51, s51, 0
	s_cmpk_gt_u32 s52, 0xa9
	s_cbranch_scc0 .LBB0_2369
	s_and_b64 vcc, exec, s[20:21]
	s_cbranch_vccz .LBB0_2372
	s_barrier
